# baseline (speedup 1.0000x reference)
.LBB0_201:
	s_waitcnt lgkmcnt(0)
	ds_read_b128 v[128:131], v152
	ds_read_b128 v[146:149], v152 offset:1024
	ds_read_b128 v[158:161], v152 offset:2048
	ds_read_b128 v[162:165], v152 offset:3072
	ds_read_b128 v[166:169], v153
	ds_read_b128 v[170:173], v153 offset:1024
	ds_read_b128 v[174:177], v153 offset:2048
	ds_read_b128 v[178:181], v153 offset:3072
	s_add_u32 s54, s0, 0xfff80080
	s_addc_u32 s55, s1, -1
	s_cmp_eq_u32 s64, 28
	s_cselect_b32 s67, s2, s55
	s_cselect_b32 s66, s27, s54
	s_cselect_b32 s55, s40, s49
	s_cselect_b32 s54, s41, s48
	v_lshl_add_u64 v[214:215], s[0:1], 0, v[142:143]
	s_add_i32 m0, s33, 0xc000
	ds_read_b128 v[182:185], v154
	ds_read_b128 v[186:189], v154 offset:1024
	ds_read_b128 v[190:193], v154 offset:2048
	ds_read_b128 v[194:197], v154 offset:3072
	ds_read_b128 v[198:201], v154 offset:4096
	ds_read_b128 v[202:205], v154 offset:5120
	ds_read_b128 v[206:209], v154 offset:6144
	ds_read_b128 v[210:213], v154 offset:7168
	global_load_lds_dwordx4 v[214:215], off
	v_lshl_add_u64 v[214:215], s[0:1], 0, v[144:145]
	s_add_i32 m0, s33, 0xe000
	s_nop 0
	global_load_lds_dwordx4 v[214:215], off
	s_waitcnt vmcnt(8)
	s_waitcnt lgkmcnt(0)
	s_barrier
	v_mfma_f32_16x16x32_bf16 v[124:127], v[128:131], v[182:185], v[124:127]
	v_mfma_f32_16x16x32_bf16 v[120:123], v[158:161], v[182:185], v[120:123]
	v_mfma_f32_16x16x32_bf16 v[116:119], v[128:131], v[190:193], v[116:119]
	v_mfma_f32_16x16x32_bf16 v[108:111], v[158:161], v[190:193], v[108:111]
	v_mfma_f32_16x16x32_bf16 v[100:103], v[128:131], v[198:201], v[100:103]
	v_mfma_f32_16x16x32_bf16 v[92:95], v[158:161], v[198:201], v[92:95]
	v_mfma_f32_16x16x32_bf16 v[84:87], v[128:131], v[206:209], v[84:87]
	v_mfma_f32_16x16x32_bf16 v[76:79], v[158:161], v[206:209], v[76:79]
	v_mfma_f32_16x16x32_bf16 v[124:127], v[146:149], v[186:189], v[124:127]
	v_mfma_f32_16x16x32_bf16 v[120:123], v[162:165], v[186:189], v[120:123]
	v_mfma_f32_16x16x32_bf16 v[116:119], v[146:149], v[194:197], v[116:119]
	v_mfma_f32_16x16x32_bf16 v[108:111], v[162:165], v[194:197], v[108:111]
	v_mfma_f32_16x16x32_bf16 v[100:103], v[146:149], v[202:205], v[100:103]
	v_mfma_f32_16x16x32_bf16 v[92:95], v[162:165], v[202:205], v[92:95]
	v_mfma_f32_16x16x32_bf16 v[84:87], v[146:149], v[210:213], v[84:87]
	v_mfma_f32_16x16x32_bf16 v[76:79], v[162:165], v[210:213], v[76:79]
	v_mfma_f32_16x16x32_bf16 v[112:115], v[166:169], v[182:185], v[112:115]
	v_mfma_f32_16x16x32_bf16 v[104:107], v[174:177], v[182:185], v[104:107]
	v_mfma_f32_16x16x32_bf16 v[96:99], v[166:169], v[190:193], v[96:99]
	v_mfma_f32_16x16x32_bf16 v[88:91], v[174:177], v[190:193], v[88:91]
	v_mfma_f32_16x16x32_bf16 v[80:83], v[166:169], v[198:201], v[80:83]
	v_mfma_f32_16x16x32_bf16 v[72:75], v[174:177], v[198:201], v[72:75]
	v_mfma_f32_16x16x32_bf16 v[68:71], v[166:169], v[206:209], v[68:71]
	v_mfma_f32_16x16x32_bf16 v[64:67], v[174:177], v[206:209], v[64:67]
	v_mfma_f32_16x16x32_bf16 v[112:115], v[170:173], v[186:189], v[112:115]
	v_mfma_f32_16x16x32_bf16 v[104:107], v[178:181], v[186:189], v[104:107]
	v_mfma_f32_16x16x32_bf16 v[96:99], v[170:173], v[194:197], v[96:99]
	v_mfma_f32_16x16x32_bf16 v[88:91], v[178:181], v[194:197], v[88:91]
	v_mfma_f32_16x16x32_bf16 v[80:83], v[170:173], v[202:205], v[80:83]
	v_mfma_f32_16x16x32_bf16 v[72:75], v[178:181], v[202:205], v[72:75]
	v_mfma_f32_16x16x32_bf16 v[68:71], v[170:173], v[210:213], v[68:71]
	v_mfma_f32_16x16x32_bf16 v[64:67], v[178:181], v[210:213], v[64:67]
	s_barrier
	s_add_i32 s88, s74, s25
	v_lshl_add_u64 v[214:215], s[54:55], 0, v[134:135]
	s_mov_b32 m0, s88
	ds_read_b128 v[182:185], v154 offset:16384
	ds_read_b128 v[186:189], v154 offset:17408
	ds_read_b128 v[190:193], v154 offset:18432
	ds_read_b128 v[194:197], v154 offset:19456
	ds_read_b128 v[198:201], v154 offset:20480
	ds_read_b128 v[202:205], v154 offset:21504
	ds_read_b128 v[206:209], v154 offset:22528
	ds_read_b128 v[210:213], v154 offset:23552
	global_load_lds_dwordx4 v[214:215], off
	s_add_i32 m0, s88, 0x2000
	s_add_u32 s88, s54, 0x80000
	v_lshl_add_u64 v[216:217], s[54:55], 0, v[138:139]
	s_addc_u32 s89, s55, 0
	s_add_i32 s90, s75, s25
	global_load_lds_dwordx4 v[216:217], off
	v_lshl_add_u64 v[220:221], s[88:89], 0, v[134:135]
	s_mov_b32 m0, s90
	v_lshl_add_u64 v[222:223], s[66:67], 0, v[136:137]
	global_load_lds_dwordx4 v[220:221], off
	v_lshl_add_u64 v[220:221], s[88:89], 0, v[138:139]
	s_add_i32 m0, s90, 0x2000
	s_nop 0
	global_load_lds_dwordx4 v[220:221], off
	v_lshl_add_u64 v[220:221], s[66:67], 0, v[132:133]
	s_mov_b32 m0, s33
	s_nop 0
	global_load_lds_dwordx4 v[220:221], off
	s_mov_b32 m0, s46
	s_nop 0
	global_load_lds_dwordx4 v[222:223], off
	s_waitcnt vmcnt(8)
	s_waitcnt lgkmcnt(0)
	s_barrier
	v_mfma_f32_16x16x32_bf16 v[60:63], v[128:131], v[182:185], v[60:63]
	v_mfma_f32_16x16x32_bf16 v[56:59], v[158:161], v[182:185], v[56:59]
	v_mfma_f32_16x16x32_bf16 v[52:55], v[128:131], v[190:193], v[52:55]
	v_mfma_f32_16x16x32_bf16 v[44:47], v[158:161], v[190:193], v[44:47]
	v_mfma_f32_16x16x32_bf16 v[36:39], v[128:131], v[198:201], v[36:39]
	v_mfma_f32_16x16x32_bf16 v[28:31], v[158:161], v[198:201], v[28:31]
	v_mfma_f32_16x16x32_bf16 v[20:23], v[128:131], v[206:209], v[20:23]
	v_mfma_f32_16x16x32_bf16 v[12:15], v[158:161], v[206:209], v[12:15]
	v_mfma_f32_16x16x32_bf16 v[60:63], v[146:149], v[186:189], v[60:63]
	v_mfma_f32_16x16x32_bf16 v[56:59], v[162:165], v[186:189], v[56:59]
	v_mfma_f32_16x16x32_bf16 v[52:55], v[146:149], v[194:197], v[52:55]
	v_mfma_f32_16x16x32_bf16 v[44:47], v[162:165], v[194:197], v[44:47]
	v_mfma_f32_16x16x32_bf16 v[36:39], v[146:149], v[202:205], v[36:39]
	v_mfma_f32_16x16x32_bf16 v[28:31], v[162:165], v[202:205], v[28:31]
	v_mfma_f32_16x16x32_bf16 v[20:23], v[146:149], v[210:213], v[20:23]
	v_mfma_f32_16x16x32_bf16 v[12:15], v[162:165], v[210:213], v[12:15]
	v_mfma_f32_16x16x32_bf16 v[48:51], v[166:169], v[182:185], v[48:51]
	v_mfma_f32_16x16x32_bf16 v[40:43], v[174:177], v[182:185], v[40:43]
	v_mfma_f32_16x16x32_bf16 v[32:35], v[166:169], v[190:193], v[32:35]
	v_mfma_f32_16x16x32_bf16 v[24:27], v[174:177], v[190:193], v[24:27]
	v_mfma_f32_16x16x32_bf16 v[16:19], v[166:169], v[198:201], v[16:19]
	v_mfma_f32_16x16x32_bf16 v[8:11], v[174:177], v[198:201], v[8:11]
	v_mfma_f32_16x16x32_bf16 v[4:7], v[166:169], v[206:209], v[4:7]
	v_mfma_f32_16x16x32_bf16 v[0:3], v[174:177], v[206:209], v[0:3]
	v_mfma_f32_16x16x32_bf16 v[48:51], v[170:173], v[186:189], v[48:51]
	v_mfma_f32_16x16x32_bf16 v[40:43], v[178:181], v[186:189], v[40:43]
	v_mfma_f32_16x16x32_bf16 v[32:35], v[170:173], v[194:197], v[32:35]
	v_mfma_f32_16x16x32_bf16 v[24:27], v[178:181], v[194:197], v[24:27]
	v_mfma_f32_16x16x32_bf16 v[16:19], v[170:173], v[202:205], v[16:19]
	v_mfma_f32_16x16x32_bf16 v[8:11], v[178:181], v[202:205], v[8:11]
	v_mfma_f32_16x16x32_bf16 v[4:7], v[170:173], v[210:213], v[4:7]
	v_mfma_f32_16x16x32_bf16 v[0:3], v[178:181], v[210:213], v[0:3]
	s_barrier
	s_add_i32 s88, 0, 0x18000
	v_add_u32_e32 v140, s88, v151
	s_add_i32 s89, 0, 0x1c000
	ds_read_b128 v[128:131], v140
	ds_read_b128 v[146:149], v140 offset:1024
	ds_read_b128 v[158:161], v140 offset:2048
	ds_read_b128 v[162:165], v140 offset:3072
	v_add_u32_e32 v140, s89, v151
	ds_read_b128 v[166:169], v140
	ds_read_b128 v[170:173], v140 offset:1024
	ds_read_b128 v[174:177], v140 offset:2048
	ds_read_b128 v[178:181], v140 offset:3072
	s_add_u32 s66, s66, 0x80000
	s_addc_u32 s67, s67, 0
	s_mov_b32 m0, s47
	v_lshl_add_u64 v[224:225], s[66:67], 0, v[132:133]
	ds_read_b128 v[182:185], v154 offset:32768
	ds_read_b128 v[186:189], v154 offset:33792
	ds_read_b128 v[190:193], v154 offset:34816
	ds_read_b128 v[194:197], v154 offset:35840
	ds_read_b128 v[198:201], v154 offset:36864
	ds_read_b128 v[202:205], v154 offset:37888
	ds_read_b128 v[206:209], v154 offset:38912
	ds_read_b128 v[210:213], v154 offset:39936
	global_load_lds_dwordx4 v[224:225], off
	v_lshl_add_u64 v[224:225], s[66:67], 0, v[136:137]
	s_mov_b32 m0, s50
	s_nop 0
	global_load_lds_dwordx4 v[224:225], off
	s_waitcnt vmcnt(8)
	s_waitcnt lgkmcnt(0)
	s_barrier
	v_mfma_f32_16x16x32_bf16 v[124:127], v[128:131], v[182:185], v[124:127]
	v_mfma_f32_16x16x32_bf16 v[120:123], v[158:161], v[182:185], v[120:123]
	v_mfma_f32_16x16x32_bf16 v[116:119], v[128:131], v[190:193], v[116:119]
	v_mfma_f32_16x16x32_bf16 v[108:111], v[158:161], v[190:193], v[108:111]
	v_mfma_f32_16x16x32_bf16 v[100:103], v[128:131], v[198:201], v[100:103]
	v_mfma_f32_16x16x32_bf16 v[92:95], v[158:161], v[198:201], v[92:95]
	v_mfma_f32_16x16x32_bf16 v[84:87], v[128:131], v[206:209], v[84:87]
	v_mfma_f32_16x16x32_bf16 v[76:79], v[158:161], v[206:209], v[76:79]
	v_mfma_f32_16x16x32_bf16 v[124:127], v[146:149], v[186:189], v[124:127]
	v_mfma_f32_16x16x32_bf16 v[120:123], v[162:165], v[186:189], v[120:123]
	v_mfma_f32_16x16x32_bf16 v[116:119], v[146:149], v[194:197], v[116:119]
	v_mfma_f32_16x16x32_bf16 v[108:111], v[162:165], v[194:197], v[108:111]
	v_mfma_f32_16x16x32_bf16 v[100:103], v[146:149], v[202:205], v[100:103]
	v_mfma_f32_16x16x32_bf16 v[92:95], v[162:165], v[202:205], v[92:95]
	v_mfma_f32_16x16x32_bf16 v[84:87], v[146:149], v[210:213], v[84:87]
	v_mfma_f32_16x16x32_bf16 v[76:79], v[162:165], v[210:213], v[76:79]
	v_mfma_f32_16x16x32_bf16 v[112:115], v[166:169], v[182:185], v[112:115]
	v_mfma_f32_16x16x32_bf16 v[104:107], v[174:177], v[182:185], v[104:107]
	v_mfma_f32_16x16x32_bf16 v[96:99], v[166:169], v[190:193], v[96:99]
	v_mfma_f32_16x16x32_bf16 v[88:91], v[174:177], v[190:193], v[88:91]
	v_mfma_f32_16x16x32_bf16 v[80:83], v[166:169], v[198:201], v[80:83]
	v_mfma_f32_16x16x32_bf16 v[72:75], v[174:177], v[198:201], v[72:75]
	v_mfma_f32_16x16x32_bf16 v[68:71], v[166:169], v[206:209], v[68:71]
	v_mfma_f32_16x16x32_bf16 v[64:67], v[174:177], v[206:209], v[64:67]
	v_mfma_f32_16x16x32_bf16 v[112:115], v[170:173], v[186:189], v[112:115]
	v_mfma_f32_16x16x32_bf16 v[104:107], v[178:181], v[186:189], v[104:107]
	v_mfma_f32_16x16x32_bf16 v[96:99], v[170:173], v[194:197], v[96:99]
	v_mfma_f32_16x16x32_bf16 v[88:91], v[178:181], v[194:197], v[88:91]
	v_mfma_f32_16x16x32_bf16 v[80:83], v[170:173], v[202:205], v[80:83]
	v_mfma_f32_16x16x32_bf16 v[72:75], v[178:181], v[202:205], v[72:75]
	v_mfma_f32_16x16x32_bf16 v[68:71], v[170:173], v[210:213], v[68:71]
	v_mfma_f32_16x16x32_bf16 v[64:67], v[178:181], v[210:213], v[64:67]
	s_barrier
	s_add_i32 s66, s88, s25
	v_lshl_add_u64 v[214:215], v[214:215], 0, s[6:7]
	s_mov_b32 m0, s66
	ds_read_b128 v[182:185], v154 offset:49152
	ds_read_b128 v[186:189], v154 offset:50176
	ds_read_b128 v[190:193], v154 offset:51200
	ds_read_b128 v[194:197], v154 offset:52224
	ds_read_b128 v[198:201], v154 offset:53248
	ds_read_b128 v[202:205], v154 offset:54272
	ds_read_b128 v[206:209], v154 offset:55296
	ds_read_b128 v[210:213], v154 offset:56320
	global_load_lds_dwordx4 v[214:215], off
	s_add_i32 m0, s66, 0x2000
	s_add_u32 s54, s54, 0x80080
	v_lshl_add_u64 v[214:215], v[216:217], 0, s[6:7]
	s_addc_u32 s55, s55, 0
	s_add_i32 s66, s89, s25
	global_load_lds_dwordx4 v[214:215], off
	v_lshl_add_u64 v[214:215], s[54:55], 0, v[134:135]
	s_mov_b32 m0, s66
	s_nop 0
	global_load_lds_dwordx4 v[214:215], off
	v_lshl_add_u64 v[214:215], s[54:55], 0, v[138:139]
	s_add_i32 m0, s66, 0x2000
	s_nop 0
	global_load_lds_dwordx4 v[214:215], off
	v_lshl_add_u64 v[214:215], v[220:221], 0, s[6:7]
	s_mov_b32 m0, s65
	s_nop 0
	global_load_lds_dwordx4 v[214:215], off
	v_lshl_add_u64 v[214:215], v[222:223], 0, s[6:7]
	s_mov_b32 m0, s72
	s_nop 0
	global_load_lds_dwordx4 v[214:215], off
	s_waitcnt vmcnt(8)
	s_waitcnt lgkmcnt(0)
	s_barrier
	v_mfma_f32_16x16x32_bf16 v[60:63], v[128:131], v[182:185], v[60:63]
	v_mfma_f32_16x16x32_bf16 v[56:59], v[158:161], v[182:185], v[56:59]
	v_mfma_f32_16x16x32_bf16 v[52:55], v[128:131], v[190:193], v[52:55]
	v_mfma_f32_16x16x32_bf16 v[44:47], v[158:161], v[190:193], v[44:47]
	v_mfma_f32_16x16x32_bf16 v[36:39], v[128:131], v[198:201], v[36:39]
	v_mfma_f32_16x16x32_bf16 v[28:31], v[158:161], v[198:201], v[28:31]
	v_mfma_f32_16x16x32_bf16 v[20:23], v[128:131], v[206:209], v[20:23]
	v_mfma_f32_16x16x32_bf16 v[12:15], v[158:161], v[206:209], v[12:15]
	v_mfma_f32_16x16x32_bf16 v[60:63], v[146:149], v[186:189], v[60:63]
	v_mfma_f32_16x16x32_bf16 v[56:59], v[162:165], v[186:189], v[56:59]
	v_mfma_f32_16x16x32_bf16 v[52:55], v[146:149], v[194:197], v[52:55]
	v_mfma_f32_16x16x32_bf16 v[44:47], v[162:165], v[194:197], v[44:47]
	v_mfma_f32_16x16x32_bf16 v[36:39], v[146:149], v[202:205], v[36:39]
	v_mfma_f32_16x16x32_bf16 v[28:31], v[162:165], v[202:205], v[28:31]
	v_mfma_f32_16x16x32_bf16 v[20:23], v[146:149], v[210:213], v[20:23]
	v_mfma_f32_16x16x32_bf16 v[12:15], v[162:165], v[210:213], v[12:15]
	v_mfma_f32_16x16x32_bf16 v[48:51], v[166:169], v[182:185], v[48:51]
	v_mfma_f32_16x16x32_bf16 v[40:43], v[174:177], v[182:185], v[40:43]
	v_mfma_f32_16x16x32_bf16 v[32:35], v[166:169], v[190:193], v[32:35]
	v_mfma_f32_16x16x32_bf16 v[24:27], v[174:177], v[190:193], v[24:27]
	v_mfma_f32_16x16x32_bf16 v[16:19], v[166:169], v[198:201], v[16:19]
	v_mfma_f32_16x16x32_bf16 v[8:11], v[174:177], v[198:201], v[8:11]
	v_mfma_f32_16x16x32_bf16 v[4:7], v[166:169], v[206:209], v[4:7]
	v_mfma_f32_16x16x32_bf16 v[0:3], v[174:177], v[206:209], v[0:3]
	v_mfma_f32_16x16x32_bf16 v[48:51], v[170:173], v[186:189], v[48:51]
	v_mfma_f32_16x16x32_bf16 v[40:43], v[178:181], v[186:189], v[40:43]
	v_mfma_f32_16x16x32_bf16 v[32:35], v[170:173], v[194:197], v[32:35]
	v_mfma_f32_16x16x32_bf16 v[24:27], v[178:181], v[194:197], v[24:27]
	v_mfma_f32_16x16x32_bf16 v[16:19], v[170:173], v[202:205], v[16:19]
	v_mfma_f32_16x16x32_bf16 v[8:11], v[178:181], v[202:205], v[8:11]
	v_mfma_f32_16x16x32_bf16 v[4:7], v[170:173], v[210:213], v[4:7]
	v_mfma_f32_16x16x32_bf16 v[0:3], v[178:181], v[210:213], v[0:3]
	s_barrier
	s_add_i32 s64, s64, 2
	s_add_u32 s0, s0, 0x100
	s_addc_u32 s1, s1, 0
	s_add_u32 s48, s48, 0x100
	s_addc_u32 s49, s49, 0
	s_cmp_gt_u32 s64, 29
	s_cbranch_scc0 .LBB0_201
	s_and_b64 vcc, exec, s[18:19]
	s_cbranch_vccz .LBB0_204
	s_barrier

.LBB0_314:
	ds_read_b128 v[150:153], v146
	ds_read_b128 v[154:157], v146 offset:1024
	ds_read_b128 v[158:161], v146 offset:2048
	ds_read_b128 v[162:165], v146 offset:3072
	ds_read_b128 v[166:169], v147
	ds_read_b128 v[170:173], v147 offset:1024
	ds_read_b128 v[174:177], v147 offset:2048
	ds_read_b128 v[178:181], v147 offset:3072
	s_add_u32 s38, s36, 0xfff80080
	s_addc_u32 s39, s37, -1
	s_cmp_eq_u32 s54, 28
	s_cselect_b32 s45, s25, s39
	s_cselect_b32 s44, s24, s38
	s_cselect_b32 s39, s27, s53
	s_cselect_b32 s38, s26, s23
	v_lshl_add_u64 v[142:143], s[36:37], 0, v[138:139]
	s_add_i32 m0, s2, 0xc000
	ds_read_b128 v[182:185], v148
	ds_read_b128 v[186:189], v148 offset:1024
	ds_read_b128 v[190:193], v148 offset:2048
	ds_read_b128 v[194:197], v148 offset:3072
	ds_read_b128 v[198:201], v148 offset:4096
	ds_read_b128 v[202:205], v148 offset:5120
	ds_read_b128 v[206:209], v148 offset:6144
	ds_read_b128 v[210:213], v148 offset:7168
	global_load_lds_dwordx4 v[142:143], off
	v_lshl_add_u64 v[142:143], s[36:37], 0, v[140:141]
	s_add_i32 m0, s2, 0xe000
	s_nop 0
	global_load_lds_dwordx4 v[142:143], off
	s_waitcnt vmcnt(8)
	s_waitcnt lgkmcnt(0)
	s_barrier
	v_mfma_f32_16x16x32_bf16 v[124:127], v[150:153], v[182:185], v[124:127]
	v_mfma_f32_16x16x32_bf16 v[120:123], v[158:161], v[182:185], v[120:123]
	v_mfma_f32_16x16x32_bf16 v[116:119], v[150:153], v[190:193], v[116:119]
	v_mfma_f32_16x16x32_bf16 v[108:111], v[158:161], v[190:193], v[108:111]
	v_mfma_f32_16x16x32_bf16 v[100:103], v[150:153], v[198:201], v[100:103]
	v_mfma_f32_16x16x32_bf16 v[92:95], v[158:161], v[198:201], v[92:95]
	v_mfma_f32_16x16x32_bf16 v[84:87], v[150:153], v[206:209], v[84:87]
	v_mfma_f32_16x16x32_bf16 v[76:79], v[158:161], v[206:209], v[76:79]
	v_mfma_f32_16x16x32_bf16 v[124:127], v[154:157], v[186:189], v[124:127]
	v_mfma_f32_16x16x32_bf16 v[120:123], v[162:165], v[186:189], v[120:123]
	v_mfma_f32_16x16x32_bf16 v[116:119], v[154:157], v[194:197], v[116:119]
	v_mfma_f32_16x16x32_bf16 v[108:111], v[162:165], v[194:197], v[108:111]
	v_mfma_f32_16x16x32_bf16 v[100:103], v[154:157], v[202:205], v[100:103]
	v_mfma_f32_16x16x32_bf16 v[92:95], v[162:165], v[202:205], v[92:95]
	v_mfma_f32_16x16x32_bf16 v[84:87], v[154:157], v[210:213], v[84:87]
	v_mfma_f32_16x16x32_bf16 v[76:79], v[162:165], v[210:213], v[76:79]
	v_mfma_f32_16x16x32_bf16 v[112:115], v[166:169], v[182:185], v[112:115]
	v_mfma_f32_16x16x32_bf16 v[104:107], v[174:177], v[182:185], v[104:107]
	v_mfma_f32_16x16x32_bf16 v[96:99], v[166:169], v[190:193], v[96:99]
	v_mfma_f32_16x16x32_bf16 v[88:91], v[174:177], v[190:193], v[88:91]
	v_mfma_f32_16x16x32_bf16 v[80:83], v[166:169], v[198:201], v[80:83]
	v_mfma_f32_16x16x32_bf16 v[72:75], v[174:177], v[198:201], v[72:75]
	v_mfma_f32_16x16x32_bf16 v[68:71], v[166:169], v[206:209], v[68:71]
	v_mfma_f32_16x16x32_bf16 v[64:67], v[174:177], v[206:209], v[64:67]
	v_mfma_f32_16x16x32_bf16 v[112:115], v[170:173], v[186:189], v[112:115]
	v_mfma_f32_16x16x32_bf16 v[104:107], v[178:181], v[186:189], v[104:107]
	v_mfma_f32_16x16x32_bf16 v[96:99], v[170:173], v[194:197], v[96:99]
	v_mfma_f32_16x16x32_bf16 v[88:91], v[178:181], v[194:197], v[88:91]
	v_mfma_f32_16x16x32_bf16 v[80:83], v[170:173], v[202:205], v[80:83]
	v_mfma_f32_16x16x32_bf16 v[72:75], v[178:181], v[202:205], v[72:75]
	v_mfma_f32_16x16x32_bf16 v[68:71], v[170:173], v[210:213], v[68:71]
	v_mfma_f32_16x16x32_bf16 v[64:67], v[178:181], v[210:213], v[64:67]
	s_barrier
	s_add_i32 s55, s49, s3
	v_lshl_add_u64 v[142:143], s[38:39], 0, v[130:131]
	s_mov_b32 m0, s55
	ds_read_b128 v[182:185], v148 offset:16384
	ds_read_b128 v[186:189], v148 offset:17408
	ds_read_b128 v[190:193], v148 offset:18432
	ds_read_b128 v[194:197], v148 offset:19456
	ds_read_b128 v[198:201], v148 offset:20480
	ds_read_b128 v[202:205], v148 offset:21504
	ds_read_b128 v[206:209], v148 offset:22528
	ds_read_b128 v[210:213], v148 offset:23552
	global_load_lds_dwordx4 v[142:143], off
	s_add_i32 m0, s55, 0x2000
	s_add_u32 s64, s38, 0x80000
	v_lshl_add_u64 v[214:215], s[38:39], 0, v[134:135]
	s_addc_u32 s65, s39, 0
	s_add_i32 s55, s50, s3
	global_load_lds_dwordx4 v[214:215], off
	v_lshl_add_u64 v[216:217], s[64:65], 0, v[130:131]
	s_mov_b32 m0, s55
	v_lshl_add_u64 v[220:221], s[44:45], 0, v[132:133]
	global_load_lds_dwordx4 v[216:217], off
	v_lshl_add_u64 v[216:217], s[64:65], 0, v[134:135]
	s_add_i32 m0, s55, 0x2000
	s_nop 0
	global_load_lds_dwordx4 v[216:217], off
	v_lshl_add_u64 v[216:217], s[44:45], 0, v[128:129]
	s_mov_b32 m0, s2
	s_nop 0
	global_load_lds_dwordx4 v[216:217], off
	s_mov_b32 m0, s33
	s_nop 0
	global_load_lds_dwordx4 v[220:221], off
	s_waitcnt vmcnt(8)
	s_waitcnt lgkmcnt(0)
	s_barrier
	v_mfma_f32_16x16x32_bf16 v[60:63], v[150:153], v[182:185], v[60:63]
	v_mfma_f32_16x16x32_bf16 v[56:59], v[158:161], v[182:185], v[56:59]
	v_mfma_f32_16x16x32_bf16 v[52:55], v[150:153], v[190:193], v[52:55]
	v_mfma_f32_16x16x32_bf16 v[44:47], v[158:161], v[190:193], v[44:47]
	v_mfma_f32_16x16x32_bf16 v[36:39], v[150:153], v[198:201], v[36:39]
	v_mfma_f32_16x16x32_bf16 v[28:31], v[158:161], v[198:201], v[28:31]
	v_mfma_f32_16x16x32_bf16 v[20:23], v[150:153], v[206:209], v[20:23]
	v_mfma_f32_16x16x32_bf16 v[12:15], v[158:161], v[206:209], v[12:15]
	v_mfma_f32_16x16x32_bf16 v[60:63], v[154:157], v[186:189], v[60:63]
	v_mfma_f32_16x16x32_bf16 v[56:59], v[162:165], v[186:189], v[56:59]
	v_mfma_f32_16x16x32_bf16 v[52:55], v[154:157], v[194:197], v[52:55]
	v_mfma_f32_16x16x32_bf16 v[44:47], v[162:165], v[194:197], v[44:47]
	v_mfma_f32_16x16x32_bf16 v[36:39], v[154:157], v[202:205], v[36:39]
	v_mfma_f32_16x16x32_bf16 v[28:31], v[162:165], v[202:205], v[28:31]
	v_mfma_f32_16x16x32_bf16 v[20:23], v[154:157], v[210:213], v[20:23]
	v_mfma_f32_16x16x32_bf16 v[12:15], v[162:165], v[210:213], v[12:15]
	v_mfma_f32_16x16x32_bf16 v[48:51], v[166:169], v[182:185], v[48:51]
	v_mfma_f32_16x16x32_bf16 v[40:43], v[174:177], v[182:185], v[40:43]
	v_mfma_f32_16x16x32_bf16 v[32:35], v[166:169], v[190:193], v[32:35]
	v_mfma_f32_16x16x32_bf16 v[24:27], v[174:177], v[190:193], v[24:27]
	v_mfma_f32_16x16x32_bf16 v[16:19], v[166:169], v[198:201], v[16:19]
	v_mfma_f32_16x16x32_bf16 v[8:11], v[174:177], v[198:201], v[8:11]
	v_mfma_f32_16x16x32_bf16 v[4:7], v[166:169], v[206:209], v[4:7]
	v_mfma_f32_16x16x32_bf16 v[0:3], v[174:177], v[206:209], v[0:3]
	v_mfma_f32_16x16x32_bf16 v[48:51], v[170:173], v[186:189], v[48:51]
	v_mfma_f32_16x16x32_bf16 v[40:43], v[178:181], v[186:189], v[40:43]
	v_mfma_f32_16x16x32_bf16 v[32:35], v[170:173], v[194:197], v[32:35]
	v_mfma_f32_16x16x32_bf16 v[24:27], v[178:181], v[194:197], v[24:27]
	v_mfma_f32_16x16x32_bf16 v[16:19], v[170:173], v[202:205], v[16:19]
	v_mfma_f32_16x16x32_bf16 v[8:11], v[178:181], v[202:205], v[8:11]
	v_mfma_f32_16x16x32_bf16 v[4:7], v[170:173], v[210:213], v[4:7]
	v_mfma_f32_16x16x32_bf16 v[0:3], v[178:181], v[210:213], v[0:3]
	s_barrier
	s_add_i32 s55, 0, 0x18000
	v_add_u32_e32 v136, s55, v145
	s_add_i32 s64, 0, 0x1c000
	ds_read_b128 v[150:153], v136
	ds_read_b128 v[154:157], v136 offset:1024
	ds_read_b128 v[158:161], v136 offset:2048
	ds_read_b128 v[162:165], v136 offset:3072
	v_add_u32_e32 v136, s64, v145
	ds_read_b128 v[166:169], v136
	ds_read_b128 v[170:173], v136 offset:1024
	ds_read_b128 v[174:177], v136 offset:2048
	ds_read_b128 v[178:181], v136 offset:3072
	s_add_u32 s44, s44, 0x80000
	s_addc_u32 s45, s45, 0
	s_mov_b32 m0, s35
	v_lshl_add_u64 v[222:223], s[44:45], 0, v[128:129]
	ds_read_b128 v[182:185], v148 offset:32768
	ds_read_b128 v[186:189], v148 offset:33792
	ds_read_b128 v[190:193], v148 offset:34816
	ds_read_b128 v[194:197], v148 offset:35840
	ds_read_b128 v[198:201], v148 offset:36864
	ds_read_b128 v[202:205], v148 offset:37888
	ds_read_b128 v[206:209], v148 offset:38912
	ds_read_b128 v[210:213], v148 offset:39936
	global_load_lds_dwordx4 v[222:223], off
	v_lshl_add_u64 v[222:223], s[44:45], 0, v[132:133]
	s_mov_b32 m0, s40
	s_nop 0
	global_load_lds_dwordx4 v[222:223], off
	s_waitcnt vmcnt(8)
	s_waitcnt lgkmcnt(0)
	s_barrier
	v_mfma_f32_16x16x32_bf16 v[124:127], v[150:153], v[182:185], v[124:127]
	v_mfma_f32_16x16x32_bf16 v[120:123], v[158:161], v[182:185], v[120:123]
	v_mfma_f32_16x16x32_bf16 v[116:119], v[150:153], v[190:193], v[116:119]
	v_mfma_f32_16x16x32_bf16 v[108:111], v[158:161], v[190:193], v[108:111]
	v_mfma_f32_16x16x32_bf16 v[100:103], v[150:153], v[198:201], v[100:103]
	v_mfma_f32_16x16x32_bf16 v[92:95], v[158:161], v[198:201], v[92:95]
	v_mfma_f32_16x16x32_bf16 v[84:87], v[150:153], v[206:209], v[84:87]
	v_mfma_f32_16x16x32_bf16 v[76:79], v[158:161], v[206:209], v[76:79]
	v_mfma_f32_16x16x32_bf16 v[124:127], v[154:157], v[186:189], v[124:127]
	v_mfma_f32_16x16x32_bf16 v[120:123], v[162:165], v[186:189], v[120:123]
	v_mfma_f32_16x16x32_bf16 v[116:119], v[154:157], v[194:197], v[116:119]
	v_mfma_f32_16x16x32_bf16 v[108:111], v[162:165], v[194:197], v[108:111]
	v_mfma_f32_16x16x32_bf16 v[100:103], v[154:157], v[202:205], v[100:103]
	v_mfma_f32_16x16x32_bf16 v[92:95], v[162:165], v[202:205], v[92:95]
	v_mfma_f32_16x16x32_bf16 v[84:87], v[154:157], v[210:213], v[84:87]
	v_mfma_f32_16x16x32_bf16 v[76:79], v[162:165], v[210:213], v[76:79]
	v_mfma_f32_16x16x32_bf16 v[112:115], v[166:169], v[182:185], v[112:115]
	v_mfma_f32_16x16x32_bf16 v[104:107], v[174:177], v[182:185], v[104:107]
	v_mfma_f32_16x16x32_bf16 v[96:99], v[166:169], v[190:193], v[96:99]
	v_mfma_f32_16x16x32_bf16 v[88:91], v[174:177], v[190:193], v[88:91]
	v_mfma_f32_16x16x32_bf16 v[80:83], v[166:169], v[198:201], v[80:83]
	v_mfma_f32_16x16x32_bf16 v[72:75], v[174:177], v[198:201], v[72:75]
	v_mfma_f32_16x16x32_bf16 v[68:71], v[166:169], v[206:209], v[68:71]
	v_mfma_f32_16x16x32_bf16 v[64:67], v[174:177], v[206:209], v[64:67]
	v_mfma_f32_16x16x32_bf16 v[112:115], v[170:173], v[186:189], v[112:115]
	v_mfma_f32_16x16x32_bf16 v[104:107], v[178:181], v[186:189], v[104:107]
	v_mfma_f32_16x16x32_bf16 v[96:99], v[170:173], v[194:197], v[96:99]
	v_mfma_f32_16x16x32_bf16 v[88:91], v[178:181], v[194:197], v[88:91]
	v_mfma_f32_16x16x32_bf16 v[80:83], v[170:173], v[202:205], v[80:83]
	v_mfma_f32_16x16x32_bf16 v[72:75], v[178:181], v[202:205], v[72:75]
	v_mfma_f32_16x16x32_bf16 v[68:71], v[170:173], v[210:213], v[68:71]
	v_mfma_f32_16x16x32_bf16 v[64:67], v[178:181], v[210:213], v[64:67]
	s_barrier
	s_add_i32 s44, s55, s3
	v_lshl_add_u64 v[142:143], v[142:143], 0, s[6:7]
	s_mov_b32 m0, s44
	ds_read_b128 v[182:185], v148 offset:49152
	ds_read_b128 v[186:189], v148 offset:50176
	ds_read_b128 v[190:193], v148 offset:51200
	ds_read_b128 v[194:197], v148 offset:52224
	ds_read_b128 v[198:201], v148 offset:53248
	ds_read_b128 v[202:205], v148 offset:54272
	ds_read_b128 v[206:209], v148 offset:55296
	ds_read_b128 v[210:213], v148 offset:56320
	global_load_lds_dwordx4 v[142:143], off
	s_add_i32 m0, s44, 0x2000
	s_add_u32 s38, s38, 0x80080
	v_lshl_add_u64 v[142:143], v[214:215], 0, s[6:7]
	s_addc_u32 s39, s39, 0
	s_add_i32 s44, s64, s3
	global_load_lds_dwordx4 v[142:143], off
	v_lshl_add_u64 v[142:143], s[38:39], 0, v[130:131]
	s_mov_b32 m0, s44
	s_nop 0
	global_load_lds_dwordx4 v[142:143], off
	v_lshl_add_u64 v[142:143], s[38:39], 0, v[134:135]
	s_add_i32 m0, s44, 0x2000
	s_nop 0
	global_load_lds_dwordx4 v[142:143], off
	v_lshl_add_u64 v[142:143], v[216:217], 0, s[6:7]
	s_mov_b32 m0, s47
	s_nop 0
	global_load_lds_dwordx4 v[142:143], off
	v_lshl_add_u64 v[142:143], v[220:221], 0, s[6:7]
	s_mov_b32 m0, s48
	s_nop 0
	global_load_lds_dwordx4 v[142:143], off
	s_waitcnt vmcnt(8)
	s_waitcnt lgkmcnt(0)
	s_barrier
	v_mfma_f32_16x16x32_bf16 v[60:63], v[150:153], v[182:185], v[60:63]
	v_mfma_f32_16x16x32_bf16 v[56:59], v[158:161], v[182:185], v[56:59]
	v_mfma_f32_16x16x32_bf16 v[52:55], v[150:153], v[190:193], v[52:55]
	v_mfma_f32_16x16x32_bf16 v[44:47], v[158:161], v[190:193], v[44:47]
	v_mfma_f32_16x16x32_bf16 v[36:39], v[150:153], v[198:201], v[36:39]
	v_mfma_f32_16x16x32_bf16 v[28:31], v[158:161], v[198:201], v[28:31]
	v_mfma_f32_16x16x32_bf16 v[20:23], v[150:153], v[206:209], v[20:23]
	v_mfma_f32_16x16x32_bf16 v[12:15], v[158:161], v[206:209], v[12:15]
	v_mfma_f32_16x16x32_bf16 v[60:63], v[154:157], v[186:189], v[60:63]
	v_mfma_f32_16x16x32_bf16 v[56:59], v[162:165], v[186:189], v[56:59]
	v_mfma_f32_16x16x32_bf16 v[52:55], v[154:157], v[194:197], v[52:55]
	v_mfma_f32_16x16x32_bf16 v[44:47], v[162:165], v[194:197], v[44:47]
	v_mfma_f32_16x16x32_bf16 v[36:39], v[154:157], v[202:205], v[36:39]
	v_mfma_f32_16x16x32_bf16 v[28:31], v[162:165], v[202:205], v[28:31]
	v_mfma_f32_16x16x32_bf16 v[20:23], v[154:157], v[210:213], v[20:23]
	v_mfma_f32_16x16x32_bf16 v[12:15], v[162:165], v[210:213], v[12:15]
	v_mfma_f32_16x16x32_bf16 v[48:51], v[166:169], v[182:185], v[48:51]
	v_mfma_f32_16x16x32_bf16 v[40:43], v[174:177], v[182:185], v[40:43]
	v_mfma_f32_16x16x32_bf16 v[32:35], v[166:169], v[190:193], v[32:35]
	v_mfma_f32_16x16x32_bf16 v[24:27], v[174:177], v[190:193], v[24:27]
	v_mfma_f32_16x16x32_bf16 v[16:19], v[166:169], v[198:201], v[16:19]
	v_mfma_f32_16x16x32_bf16 v[8:11], v[174:177], v[198:201], v[8:11]
	v_mfma_f32_16x16x32_bf16 v[4:7], v[166:169], v[206:209], v[4:7]
	v_mfma_f32_16x16x32_bf16 v[0:3], v[174:177], v[206:209], v[0:3]
	v_mfma_f32_16x16x32_bf16 v[48:51], v[170:173], v[186:189], v[48:51]
	v_mfma_f32_16x16x32_bf16 v[40:43], v[178:181], v[186:189], v[40:43]
	v_mfma_f32_16x16x32_bf16 v[32:35], v[170:173], v[194:197], v[32:35]
	v_mfma_f32_16x16x32_bf16 v[24:27], v[178:181], v[194:197], v[24:27]
	v_mfma_f32_16x16x32_bf16 v[16:19], v[170:173], v[202:205], v[16:19]
	v_mfma_f32_16x16x32_bf16 v[8:11], v[178:181], v[202:205], v[8:11]
	v_mfma_f32_16x16x32_bf16 v[4:7], v[170:173], v[210:213], v[4:7]
	v_mfma_f32_16x16x32_bf16 v[0:3], v[178:181], v[210:213], v[0:3]
	s_barrier
	s_add_i32 s54, s54, 2
	s_add_u32 s36, s36, 0x100
	s_addc_u32 s37, s37, 0
	s_add_u32 s23, s23, 0x100
	s_addc_u32 s53, s53, 0
	s_cmp_gt_u32 s54, 29
	s_cbranch_scc0 .LBB0_314
	s_and_b64 vcc, exec, s[18:19]
	s_cbranch_vccz .LBB0_317
	s_barrier

.LBB0_334:
	ds_read_b128 v[142:145], v158
	ds_read_b128 v[146:149], v158 offset:1024
	ds_read_b128 v[150:153], v158 offset:2048
	ds_read_b128 v[162:165], v158 offset:3072
	ds_read_b128 v[166:169], v159
	ds_read_b128 v[170:173], v159 offset:1024
	ds_read_b128 v[174:177], v159 offset:2048
	ds_read_b128 v[178:181], v159 offset:3072
	s_add_u32 s6, s0, 0xfffe0080
	s_addc_u32 s7, s1, -1
	s_cmp_eq_u32 s25, 4
	s_cselect_b32 s37, s27, s7
	s_cselect_b32 s36, s26, s6
	s_cselect_b32 s7, s31, s5
	s_cselect_b32 s6, s30, s3
	v_lshl_add_u64 v[154:155], s[0:1], 0, v[138:139]
	s_add_i32 m0, s39, 0xc000
	ds_read_b128 v[182:185], v160
	ds_read_b128 v[186:189], v160 offset:1024
	ds_read_b128 v[190:193], v160 offset:2048
	ds_read_b128 v[194:197], v160 offset:3072
	ds_read_b128 v[198:201], v160 offset:4096
	ds_read_b128 v[202:205], v160 offset:5120
	ds_read_b128 v[206:209], v160 offset:6144
	ds_read_b128 v[210:213], v160 offset:7168
	global_load_lds_dwordx4 v[154:155], off
	v_lshl_add_u64 v[154:155], s[0:1], 0, v[140:141]
	s_add_i32 m0, s39, 0xe000
	s_nop 0
	global_load_lds_dwordx4 v[154:155], off
	s_waitcnt vmcnt(8)
	s_waitcnt lgkmcnt(0)
	s_barrier
	v_mfma_f32_16x16x32_bf16 v[124:127], v[142:145], v[182:185], v[124:127]
	v_mfma_f32_16x16x32_bf16 v[120:123], v[150:153], v[182:185], v[120:123]
	v_mfma_f32_16x16x32_bf16 v[108:111], v[142:145], v[190:193], v[108:111]
	v_mfma_f32_16x16x32_bf16 v[104:107], v[150:153], v[190:193], v[104:107]
	v_mfma_f32_16x16x32_bf16 v[92:95], v[142:145], v[198:201], v[92:95]
	v_mfma_f32_16x16x32_bf16 v[88:91], v[150:153], v[198:201], v[88:91]
	v_mfma_f32_16x16x32_bf16 v[76:79], v[142:145], v[206:209], v[76:79]
	v_mfma_f32_16x16x32_bf16 v[72:75], v[150:153], v[206:209], v[72:75]
	v_mfma_f32_16x16x32_bf16 v[124:127], v[146:149], v[186:189], v[124:127]
	v_mfma_f32_16x16x32_bf16 v[120:123], v[162:165], v[186:189], v[120:123]
	v_mfma_f32_16x16x32_bf16 v[108:111], v[146:149], v[194:197], v[108:111]
	v_mfma_f32_16x16x32_bf16 v[104:107], v[162:165], v[194:197], v[104:107]
	v_mfma_f32_16x16x32_bf16 v[92:95], v[146:149], v[202:205], v[92:95]
	v_mfma_f32_16x16x32_bf16 v[88:91], v[162:165], v[202:205], v[88:91]
	v_mfma_f32_16x16x32_bf16 v[76:79], v[146:149], v[210:213], v[76:79]
	v_mfma_f32_16x16x32_bf16 v[72:75], v[162:165], v[210:213], v[72:75]
	v_mfma_f32_16x16x32_bf16 v[116:119], v[166:169], v[182:185], v[116:119]
	v_mfma_f32_16x16x32_bf16 v[112:115], v[174:177], v[182:185], v[112:115]
	v_mfma_f32_16x16x32_bf16 v[100:103], v[166:169], v[190:193], v[100:103]
	v_mfma_f32_16x16x32_bf16 v[96:99], v[174:177], v[190:193], v[96:99]
	v_mfma_f32_16x16x32_bf16 v[84:87], v[166:169], v[198:201], v[84:87]
	v_mfma_f32_16x16x32_bf16 v[80:83], v[174:177], v[198:201], v[80:83]
	v_mfma_f32_16x16x32_bf16 v[68:71], v[166:169], v[206:209], v[68:71]
	v_mfma_f32_16x16x32_bf16 v[64:67], v[174:177], v[206:209], v[64:67]
	v_mfma_f32_16x16x32_bf16 v[116:119], v[170:173], v[186:189], v[116:119]
	v_mfma_f32_16x16x32_bf16 v[112:115], v[178:181], v[186:189], v[112:115]
	v_mfma_f32_16x16x32_bf16 v[100:103], v[170:173], v[194:197], v[100:103]
	v_mfma_f32_16x16x32_bf16 v[96:99], v[178:181], v[194:197], v[96:99]
	v_mfma_f32_16x16x32_bf16 v[84:87], v[170:173], v[202:205], v[84:87]
	v_mfma_f32_16x16x32_bf16 v[80:83], v[178:181], v[202:205], v[80:83]
	v_mfma_f32_16x16x32_bf16 v[68:71], v[170:173], v[210:213], v[68:71]
	v_mfma_f32_16x16x32_bf16 v[64:67], v[178:181], v[210:213], v[64:67]
	s_barrier
	s_add_i32 s40, s74, s38
	v_lshl_add_u64 v[154:155], s[6:7], 0, v[130:131]
	s_mov_b32 m0, s40
	ds_read_b128 v[182:185], v160 offset:16384
	ds_read_b128 v[186:189], v160 offset:17408
	ds_read_b128 v[190:193], v160 offset:18432
	ds_read_b128 v[194:197], v160 offset:19456
	ds_read_b128 v[198:201], v160 offset:20480
	ds_read_b128 v[202:205], v160 offset:21504
	ds_read_b128 v[206:209], v160 offset:22528
	ds_read_b128 v[210:213], v160 offset:23552
	global_load_lds_dwordx4 v[154:155], off
	s_add_i32 m0, s40, 0x2000
	s_add_u32 s40, s6, 0x20000
	v_lshl_add_u64 v[214:215], s[6:7], 0, v[134:135]
	s_addc_u32 s41, s7, 0
	s_add_i32 s42, s75, s38
	global_load_lds_dwordx4 v[214:215], off
	v_lshl_add_u64 v[216:217], s[40:41], 0, v[130:131]
	s_mov_b32 m0, s42
	v_lshl_add_u64 v[220:221], s[36:37], 0, v[132:133]
	global_load_lds_dwordx4 v[216:217], off
	v_lshl_add_u64 v[216:217], s[40:41], 0, v[134:135]
	s_add_i32 m0, s42, 0x2000
	s_nop 0
	global_load_lds_dwordx4 v[216:217], off
	v_lshl_add_u64 v[216:217], s[36:37], 0, v[128:129]
	s_mov_b32 m0, s39
	s_nop 0
	global_load_lds_dwordx4 v[216:217], off
	s_mov_b32 m0, s46
	s_nop 0
	global_load_lds_dwordx4 v[220:221], off
	s_waitcnt vmcnt(8)
	s_waitcnt lgkmcnt(0)
	s_barrier
	v_mfma_f32_16x16x32_bf16 v[60:63], v[142:145], v[182:185], v[60:63]
	v_mfma_f32_16x16x32_bf16 v[56:59], v[150:153], v[182:185], v[56:59]
	v_mfma_f32_16x16x32_bf16 v[44:47], v[142:145], v[190:193], v[44:47]
	v_mfma_f32_16x16x32_bf16 v[40:43], v[150:153], v[190:193], v[40:43]
	v_mfma_f32_16x16x32_bf16 v[28:31], v[142:145], v[198:201], v[28:31]
	v_mfma_f32_16x16x32_bf16 v[24:27], v[150:153], v[198:201], v[24:27]
	v_mfma_f32_16x16x32_bf16 v[12:15], v[142:145], v[206:209], v[12:15]
	v_mfma_f32_16x16x32_bf16 v[8:11], v[150:153], v[206:209], v[8:11]
	v_mfma_f32_16x16x32_bf16 v[60:63], v[146:149], v[186:189], v[60:63]
	v_mfma_f32_16x16x32_bf16 v[56:59], v[162:165], v[186:189], v[56:59]
	v_mfma_f32_16x16x32_bf16 v[44:47], v[146:149], v[194:197], v[44:47]
	v_mfma_f32_16x16x32_bf16 v[40:43], v[162:165], v[194:197], v[40:43]
	v_mfma_f32_16x16x32_bf16 v[28:31], v[146:149], v[202:205], v[28:31]
	v_mfma_f32_16x16x32_bf16 v[24:27], v[162:165], v[202:205], v[24:27]
	v_mfma_f32_16x16x32_bf16 v[12:15], v[146:149], v[210:213], v[12:15]
	v_mfma_f32_16x16x32_bf16 v[8:11], v[162:165], v[210:213], v[8:11]
	v_mfma_f32_16x16x32_bf16 v[52:55], v[166:169], v[182:185], v[52:55]
	v_mfma_f32_16x16x32_bf16 v[48:51], v[174:177], v[182:185], v[48:51]
	v_mfma_f32_16x16x32_bf16 v[36:39], v[166:169], v[190:193], v[36:39]
	v_mfma_f32_16x16x32_bf16 v[32:35], v[174:177], v[190:193], v[32:35]
	v_mfma_f32_16x16x32_bf16 v[20:23], v[166:169], v[198:201], v[20:23]
	v_mfma_f32_16x16x32_bf16 v[16:19], v[174:177], v[198:201], v[16:19]
	v_mfma_f32_16x16x32_bf16 v[4:7], v[166:169], v[206:209], v[4:7]
	v_mfma_f32_16x16x32_bf16 v[0:3], v[174:177], v[206:209], v[0:3]
	v_mfma_f32_16x16x32_bf16 v[52:55], v[170:173], v[186:189], v[52:55]
	v_mfma_f32_16x16x32_bf16 v[48:51], v[178:181], v[186:189], v[48:51]
	v_mfma_f32_16x16x32_bf16 v[36:39], v[170:173], v[194:197], v[36:39]
	v_mfma_f32_16x16x32_bf16 v[32:35], v[178:181], v[194:197], v[32:35]
	v_mfma_f32_16x16x32_bf16 v[20:23], v[170:173], v[202:205], v[20:23]
	v_mfma_f32_16x16x32_bf16 v[16:19], v[178:181], v[202:205], v[16:19]
	v_mfma_f32_16x16x32_bf16 v[4:7], v[170:173], v[210:213], v[4:7]
	v_mfma_f32_16x16x32_bf16 v[0:3], v[178:181], v[210:213], v[0:3]
	s_barrier
	s_add_i32 s40, 0, 0x18000
	v_add_u32_e32 v136, s40, v157
	s_add_i32 s41, 0, 0x1c000
	ds_read_b128 v[142:145], v136
	ds_read_b128 v[146:149], v136 offset:1024
	ds_read_b128 v[150:153], v136 offset:2048
	ds_read_b128 v[162:165], v136 offset:3072
	v_add_u32_e32 v136, s41, v157
	ds_read_b128 v[166:169], v136
	ds_read_b128 v[170:173], v136 offset:1024
	ds_read_b128 v[174:177], v136 offset:2048
	ds_read_b128 v[178:181], v136 offset:3072
	s_add_u32 s36, s36, 0x20000
	s_addc_u32 s37, s37, 0
	s_mov_b32 m0, s47
	v_lshl_add_u64 v[222:223], s[36:37], 0, v[128:129]
	ds_read_b128 v[182:185], v160 offset:32768
	ds_read_b128 v[186:189], v160 offset:33792
	ds_read_b128 v[190:193], v160 offset:34816
	ds_read_b128 v[194:197], v160 offset:35840
	ds_read_b128 v[198:201], v160 offset:36864
	ds_read_b128 v[202:205], v160 offset:37888
	ds_read_b128 v[206:209], v160 offset:38912
	ds_read_b128 v[210:213], v160 offset:39936
	global_load_lds_dwordx4 v[222:223], off
	v_lshl_add_u64 v[222:223], s[36:37], 0, v[132:133]
	s_mov_b32 m0, s50
	s_nop 0
	global_load_lds_dwordx4 v[222:223], off
	s_waitcnt vmcnt(8)
	s_waitcnt lgkmcnt(0)
	s_barrier
	v_mfma_f32_16x16x32_bf16 v[124:127], v[142:145], v[182:185], v[124:127]
	v_mfma_f32_16x16x32_bf16 v[120:123], v[150:153], v[182:185], v[120:123]
	v_mfma_f32_16x16x32_bf16 v[108:111], v[142:145], v[190:193], v[108:111]
	v_mfma_f32_16x16x32_bf16 v[104:107], v[150:153], v[190:193], v[104:107]
	v_mfma_f32_16x16x32_bf16 v[92:95], v[142:145], v[198:201], v[92:95]
	v_mfma_f32_16x16x32_bf16 v[88:91], v[150:153], v[198:201], v[88:91]
	v_mfma_f32_16x16x32_bf16 v[76:79], v[142:145], v[206:209], v[76:79]
	v_mfma_f32_16x16x32_bf16 v[72:75], v[150:153], v[206:209], v[72:75]
	v_mfma_f32_16x16x32_bf16 v[124:127], v[146:149], v[186:189], v[124:127]
	v_mfma_f32_16x16x32_bf16 v[120:123], v[162:165], v[186:189], v[120:123]
	v_mfma_f32_16x16x32_bf16 v[108:111], v[146:149], v[194:197], v[108:111]
	v_mfma_f32_16x16x32_bf16 v[104:107], v[162:165], v[194:197], v[104:107]
	v_mfma_f32_16x16x32_bf16 v[92:95], v[146:149], v[202:205], v[92:95]
	v_mfma_f32_16x16x32_bf16 v[88:91], v[162:165], v[202:205], v[88:91]
	v_mfma_f32_16x16x32_bf16 v[76:79], v[146:149], v[210:213], v[76:79]
	v_mfma_f32_16x16x32_bf16 v[72:75], v[162:165], v[210:213], v[72:75]
	v_mfma_f32_16x16x32_bf16 v[116:119], v[166:169], v[182:185], v[116:119]
	v_mfma_f32_16x16x32_bf16 v[112:115], v[174:177], v[182:185], v[112:115]
	v_mfma_f32_16x16x32_bf16 v[100:103], v[166:169], v[190:193], v[100:103]
	v_mfma_f32_16x16x32_bf16 v[96:99], v[174:177], v[190:193], v[96:99]
	v_mfma_f32_16x16x32_bf16 v[84:87], v[166:169], v[198:201], v[84:87]
	v_mfma_f32_16x16x32_bf16 v[80:83], v[174:177], v[198:201], v[80:83]
	v_mfma_f32_16x16x32_bf16 v[68:71], v[166:169], v[206:209], v[68:71]
	v_mfma_f32_16x16x32_bf16 v[64:67], v[174:177], v[206:209], v[64:67]
	v_mfma_f32_16x16x32_bf16 v[116:119], v[170:173], v[186:189], v[116:119]
	v_mfma_f32_16x16x32_bf16 v[112:115], v[178:181], v[186:189], v[112:115]
	v_mfma_f32_16x16x32_bf16 v[100:103], v[170:173], v[194:197], v[100:103]
	v_mfma_f32_16x16x32_bf16 v[96:99], v[178:181], v[194:197], v[96:99]
	v_mfma_f32_16x16x32_bf16 v[84:87], v[170:173], v[202:205], v[84:87]
	v_mfma_f32_16x16x32_bf16 v[80:83], v[178:181], v[202:205], v[80:83]
	v_mfma_f32_16x16x32_bf16 v[68:71], v[170:173], v[210:213], v[68:71]
	v_mfma_f32_16x16x32_bf16 v[64:67], v[178:181], v[210:213], v[64:67]
	s_barrier
	s_add_i32 s36, s40, s38
	v_lshl_add_u64 v[154:155], v[154:155], 0, s[20:21]
	s_mov_b32 m0, s36
	ds_read_b128 v[182:185], v160 offset:49152
	ds_read_b128 v[186:189], v160 offset:50176
	ds_read_b128 v[190:193], v160 offset:51200
	ds_read_b128 v[194:197], v160 offset:52224
	ds_read_b128 v[198:201], v160 offset:53248
	ds_read_b128 v[202:205], v160 offset:54272
	ds_read_b128 v[206:209], v160 offset:55296
	ds_read_b128 v[210:213], v160 offset:56320
	global_load_lds_dwordx4 v[154:155], off
	s_add_i32 m0, s36, 0x2000
	s_add_u32 s6, s6, 0x20080
	v_lshl_add_u64 v[154:155], v[214:215], 0, s[20:21]
	s_addc_u32 s7, s7, 0
	s_add_i32 s36, s41, s38
	global_load_lds_dwordx4 v[154:155], off
	v_lshl_add_u64 v[154:155], s[6:7], 0, v[130:131]
	s_mov_b32 m0, s36
	s_nop 0
	global_load_lds_dwordx4 v[154:155], off
	v_lshl_add_u64 v[154:155], s[6:7], 0, v[134:135]
	s_add_i32 m0, s36, 0x2000
	s_nop 0
	global_load_lds_dwordx4 v[154:155], off
	v_lshl_add_u64 v[154:155], v[216:217], 0, s[20:21]
	s_mov_b32 m0, s65
	s_nop 0
	global_load_lds_dwordx4 v[154:155], off
	v_lshl_add_u64 v[154:155], v[220:221], 0, s[20:21]
	s_mov_b32 m0, s66
	s_nop 0
	global_load_lds_dwordx4 v[154:155], off
	s_waitcnt vmcnt(8)
	s_waitcnt lgkmcnt(0)
	s_barrier
	v_mfma_f32_16x16x32_bf16 v[60:63], v[142:145], v[182:185], v[60:63]
	v_mfma_f32_16x16x32_bf16 v[56:59], v[150:153], v[182:185], v[56:59]
	v_mfma_f32_16x16x32_bf16 v[44:47], v[142:145], v[190:193], v[44:47]
	v_mfma_f32_16x16x32_bf16 v[40:43], v[150:153], v[190:193], v[40:43]
	v_mfma_f32_16x16x32_bf16 v[28:31], v[142:145], v[198:201], v[28:31]
	v_mfma_f32_16x16x32_bf16 v[24:27], v[150:153], v[198:201], v[24:27]
	v_mfma_f32_16x16x32_bf16 v[12:15], v[142:145], v[206:209], v[12:15]
	v_mfma_f32_16x16x32_bf16 v[8:11], v[150:153], v[206:209], v[8:11]
	v_mfma_f32_16x16x32_bf16 v[60:63], v[146:149], v[186:189], v[60:63]
	v_mfma_f32_16x16x32_bf16 v[56:59], v[162:165], v[186:189], v[56:59]
	v_mfma_f32_16x16x32_bf16 v[44:47], v[146:149], v[194:197], v[44:47]
	v_mfma_f32_16x16x32_bf16 v[40:43], v[162:165], v[194:197], v[40:43]
	v_mfma_f32_16x16x32_bf16 v[28:31], v[146:149], v[202:205], v[28:31]
	v_mfma_f32_16x16x32_bf16 v[24:27], v[162:165], v[202:205], v[24:27]
	v_mfma_f32_16x16x32_bf16 v[12:15], v[146:149], v[210:213], v[12:15]
	v_mfma_f32_16x16x32_bf16 v[8:11], v[162:165], v[210:213], v[8:11]
	v_mfma_f32_16x16x32_bf16 v[52:55], v[166:169], v[182:185], v[52:55]
	v_mfma_f32_16x16x32_bf16 v[48:51], v[174:177], v[182:185], v[48:51]
	v_mfma_f32_16x16x32_bf16 v[36:39], v[166:169], v[190:193], v[36:39]
	v_mfma_f32_16x16x32_bf16 v[32:35], v[174:177], v[190:193], v[32:35]
	v_mfma_f32_16x16x32_bf16 v[20:23], v[166:169], v[198:201], v[20:23]
	v_mfma_f32_16x16x32_bf16 v[16:19], v[174:177], v[198:201], v[16:19]
	v_mfma_f32_16x16x32_bf16 v[4:7], v[166:169], v[206:209], v[4:7]
	v_mfma_f32_16x16x32_bf16 v[0:3], v[174:177], v[206:209], v[0:3]
	v_mfma_f32_16x16x32_bf16 v[52:55], v[170:173], v[186:189], v[52:55]
	v_mfma_f32_16x16x32_bf16 v[48:51], v[178:181], v[186:189], v[48:51]
	v_mfma_f32_16x16x32_bf16 v[36:39], v[170:173], v[194:197], v[36:39]
	v_mfma_f32_16x16x32_bf16 v[32:35], v[178:181], v[194:197], v[32:35]
	v_mfma_f32_16x16x32_bf16 v[20:23], v[170:173], v[202:205], v[20:23]
	v_mfma_f32_16x16x32_bf16 v[16:19], v[178:181], v[202:205], v[16:19]
	v_mfma_f32_16x16x32_bf16 v[4:7], v[170:173], v[210:213], v[4:7]
	v_mfma_f32_16x16x32_bf16 v[0:3], v[178:181], v[210:213], v[0:3]
	s_barrier
	s_add_i32 s25, s25, 2
	s_add_u32 s0, s0, 0x100
	s_addc_u32 s1, s1, 0
	s_add_u32 s3, s3, 0x100
	s_addc_u32 s5, s5, 0
	s_cmp_gt_u32 s25, 5
	s_cbranch_scc0 .LBB0_334
	s_and_b64 vcc, exec, s[22:23]
	s_cbranch_vccz .LBB0_337
	s_barrier

.LBB0_398:
	ds_read_b128 v[0:3], v166
	ds_read_b128 v[4:7], v166 offset:1024
	ds_read_b128 v[8:11], v166 offset:2048
	ds_read_b128 v[12:15], v166 offset:3072
	ds_read_b128 v[16:19], v167
	ds_read_b128 v[20:23], v167 offset:1024
	ds_read_b128 v[24:27], v167 offset:2048
	ds_read_b128 v[28:31], v167 offset:3072
	s_and_b64 s[36:37], s[30:31], exec
	s_cselect_b32 s39, s25, s5
	s_cselect_b32 s38, s24, s4
	s_cselect_b32 s37, s27, s35
	s_cselect_b32 s36, s26, s34
	s_add_u32 s40, s4, 0x10080
	s_addc_u32 s41, s5, 0
	s_add_i32 s45, s21, 0xc000
	v_lshl_add_u64 v[64:65], s[40:41], 0, v[132:133]
	s_mov_b32 m0, s45
	s_add_i32 s3, s21, 0xe000
	ds_read_b128 v[32:35], v168
	ds_read_b128 v[36:39], v168 offset:1024
	ds_read_b128 v[40:43], v168 offset:2048
	ds_read_b128 v[44:47], v168 offset:3072
	ds_read_b128 v[48:51], v168 offset:4096
	ds_read_b128 v[52:55], v168 offset:5120
	ds_read_b128 v[56:59], v168 offset:6144
	ds_read_b128 v[60:63], v168 offset:7168
	global_load_lds_dwordx4 v[64:65], off
	v_lshl_add_u64 v[64:65], s[40:41], 0, v[136:137]
	s_mov_b32 m0, s3
	s_nop 0
	global_load_lds_dwordx4 v[64:65], off
	s_waitcnt vmcnt(8)
	s_waitcnt lgkmcnt(0)
	s_barrier
	v_mfma_f32_16x16x32_bf16 v[64:67], v[0:3], v[32:35], 0
	v_mfma_f32_16x16x32_bf16 v[68:71], v[8:11], v[32:35], 0
	v_mfma_f32_16x16x32_bf16 v[72:75], v[0:3], v[40:43], 0
	v_mfma_f32_16x16x32_bf16 v[76:79], v[8:11], v[40:43], 0
	v_mfma_f32_16x16x32_bf16 v[80:83], v[0:3], v[48:51], 0
	v_mfma_f32_16x16x32_bf16 v[84:87], v[8:11], v[48:51], 0
	v_mfma_f32_16x16x32_bf16 v[88:91], v[0:3], v[56:59], 0
	v_mfma_f32_16x16x32_bf16 v[92:95], v[8:11], v[56:59], 0
	v_mfma_f32_16x16x32_bf16 v[64:67], v[4:7], v[36:39], v[64:67]
	v_mfma_f32_16x16x32_bf16 v[68:71], v[12:15], v[36:39], v[68:71]
	v_mfma_f32_16x16x32_bf16 v[72:75], v[4:7], v[44:47], v[72:75]
	v_mfma_f32_16x16x32_bf16 v[76:79], v[12:15], v[44:47], v[76:79]
	v_mfma_f32_16x16x32_bf16 v[80:83], v[4:7], v[52:55], v[80:83]
	v_mfma_f32_16x16x32_bf16 v[84:87], v[12:15], v[52:55], v[84:87]
	v_mfma_f32_16x16x32_bf16 v[88:91], v[4:7], v[60:63], v[88:91]
	v_mfma_f32_16x16x32_bf16 v[92:95], v[12:15], v[60:63], v[92:95]
	v_mfma_f32_16x16x32_bf16 v[96:99], v[16:19], v[32:35], 0
	v_mfma_f32_16x16x32_bf16 v[32:35], v[24:27], v[32:35], 0
	v_mfma_f32_16x16x32_bf16 v[96:99], v[20:23], v[36:39], v[96:99]
	v_mfma_f32_16x16x32_bf16 v[32:35], v[28:31], v[36:39], v[32:35]
	v_mfma_f32_16x16x32_bf16 v[36:39], v[16:19], v[40:43], 0
	v_mfma_f32_16x16x32_bf16 v[40:43], v[24:27], v[40:43], 0
	v_mfma_f32_16x16x32_bf16 v[36:39], v[20:23], v[44:47], v[36:39]
	v_mfma_f32_16x16x32_bf16 v[40:43], v[28:31], v[44:47], v[40:43]
	v_mfma_f32_16x16x32_bf16 v[44:47], v[16:19], v[48:51], 0
	v_mfma_f32_16x16x32_bf16 v[48:51], v[24:27], v[48:51], 0
	v_mfma_f32_16x16x32_bf16 v[44:47], v[20:23], v[52:55], v[44:47]
	v_mfma_f32_16x16x32_bf16 v[48:51], v[28:31], v[52:55], v[48:51]
	v_mfma_f32_16x16x32_bf16 v[52:55], v[16:19], v[56:59], 0
	v_mfma_f32_16x16x32_bf16 v[56:59], v[24:27], v[56:59], 0
	v_mfma_f32_16x16x32_bf16 v[52:55], v[20:23], v[60:63], v[52:55]
	v_mfma_f32_16x16x32_bf16 v[56:59], v[28:31], v[60:63], v[56:59]
	s_barrier
	s_add_i32 s43, s67, s19
	v_lshl_add_u64 v[206:207], s[34:35], 0, v[134:135]
	s_add_i32 s40, s43, 0x2000
	v_lshl_add_u64 v[128:129], v[206:207], 0, s[14:15]
	s_mov_b32 m0, s43
	v_lshl_add_u64 v[208:209], s[34:35], 0, v[138:139]
	s_add_u32 s48, s34, 0x10100
	ds_read_b128 v[60:63], v168 offset:16384
	ds_read_b128 v[100:103], v168 offset:17408
	ds_read_b128 v[104:107], v168 offset:18432
	ds_read_b128 v[108:111], v168 offset:19456
	ds_read_b128 v[112:115], v168 offset:20480
	ds_read_b128 v[116:119], v168 offset:21504
	ds_read_b128 v[120:123], v168 offset:22528
	ds_read_b128 v[124:127], v168 offset:23552
	global_load_lds_dwordx4 v[128:129], off
	v_lshl_add_u64 v[128:129], v[208:209], 0, s[14:15]
	s_mov_b32 m0, s40
	s_addc_u32 s49, s35, 0
	s_add_i32 s41, s74, s19
	global_load_lds_dwordx4 v[128:129], off
	v_lshl_add_u64 v[128:129], s[48:49], 0, v[134:135]
	s_mov_b32 m0, s41
	s_add_i32 s42, s41, 0x2000
	global_load_lds_dwordx4 v[128:129], off
	v_lshl_add_u64 v[128:129], s[48:49], 0, v[138:139]
	s_mov_b32 m0, s42
	v_lshl_add_u64 v[210:211], s[4:5], 0, v[132:133]
	global_load_lds_dwordx4 v[128:129], off
	v_lshl_add_u64 v[128:129], v[210:211], 0, s[14:15]
	s_mov_b32 m0, s21
	v_lshl_add_u64 v[212:213], s[4:5], 0, v[136:137]
	global_load_lds_dwordx4 v[128:129], off
	v_lshl_add_u64 v[128:129], v[212:213], 0, s[14:15]
	s_mov_b32 m0, s46
	s_nop 0
	global_load_lds_dwordx4 v[128:129], off
	s_waitcnt vmcnt(8)
	s_waitcnt lgkmcnt(0)
	s_barrier
	v_mfma_f32_16x16x32_bf16 v[128:131], v[0:3], v[60:63], 0
	v_mfma_f32_16x16x32_bf16 v[144:147], v[0:3], v[104:107], 0
	v_mfma_f32_16x16x32_bf16 v[152:155], v[0:3], v[112:115], 0
	v_mfma_f32_16x16x32_bf16 v[0:3], v[0:3], v[120:123], 0
	v_mfma_f32_16x16x32_bf16 v[128:131], v[4:7], v[100:103], v[128:131]
	v_mfma_f32_16x16x32_bf16 v[144:147], v[4:7], v[108:111], v[144:147]
	v_mfma_f32_16x16x32_bf16 v[152:155], v[4:7], v[116:119], v[152:155]
	v_mfma_f32_16x16x32_bf16 v[0:3], v[4:7], v[124:127], v[0:3]
	v_mfma_f32_16x16x32_bf16 v[4:7], v[8:11], v[120:123], 0
	v_mfma_f32_16x16x32_bf16 v[140:143], v[8:11], v[60:63], 0
	v_mfma_f32_16x16x32_bf16 v[148:151], v[8:11], v[104:107], 0
	v_mfma_f32_16x16x32_bf16 v[156:159], v[8:11], v[112:115], 0
	v_mfma_f32_16x16x32_bf16 v[4:7], v[12:15], v[124:127], v[4:7]
	v_mfma_f32_16x16x32_bf16 v[140:143], v[12:15], v[100:103], v[140:143]
	v_mfma_f32_16x16x32_bf16 v[148:151], v[12:15], v[108:111], v[148:151]
	v_mfma_f32_16x16x32_bf16 v[156:159], v[12:15], v[116:119], v[156:159]
	v_mfma_f32_16x16x32_bf16 v[8:11], v[16:19], v[60:63], 0
	v_mfma_f32_16x16x32_bf16 v[12:15], v[24:27], v[60:63], 0
	v_mfma_f32_16x16x32_bf16 v[8:11], v[20:23], v[100:103], v[8:11]
	v_mfma_f32_16x16x32_bf16 v[12:15], v[28:31], v[100:103], v[12:15]
	v_mfma_f32_16x16x32_bf16 v[60:63], v[16:19], v[104:107], 0
	v_mfma_f32_16x16x32_bf16 v[100:103], v[24:27], v[104:107], 0
	v_mfma_f32_16x16x32_bf16 v[104:107], v[16:19], v[112:115], 0
	v_mfma_f32_16x16x32_bf16 v[16:19], v[16:19], v[120:123], 0
	v_mfma_f32_16x16x32_bf16 v[60:63], v[20:23], v[108:111], v[60:63]
	v_mfma_f32_16x16x32_bf16 v[100:103], v[28:31], v[108:111], v[100:103]
	v_mfma_f32_16x16x32_bf16 v[104:107], v[20:23], v[116:119], v[104:107]
	v_mfma_f32_16x16x32_bf16 v[108:111], v[24:27], v[112:115], 0
	v_mfma_f32_16x16x32_bf16 v[16:19], v[20:23], v[124:127], v[16:19]
	v_mfma_f32_16x16x32_bf16 v[20:23], v[24:27], v[120:123], 0
	v_mfma_f32_16x16x32_bf16 v[108:111], v[28:31], v[116:119], v[108:111]
	v_mfma_f32_16x16x32_bf16 v[20:23], v[28:31], v[124:127], v[20:23]
	s_barrier
	s_add_i32 s44, 0, 0x18000
	s_add_i32 s64, 0, 0x1c000
	v_add_u32_e32 v224, s44, v165
	v_add_u32_e32 v225, s64, v165
	ds_read_b128 v[24:27], v224
	ds_read_b128 v[28:31], v224 offset:1024
	ds_read_b128 v[112:115], v224 offset:2048
	ds_read_b128 v[116:119], v224 offset:3072
	ds_read_b128 v[120:123], v225
	ds_read_b128 v[124:127], v225 offset:1024
	ds_read_b128 v[160:163], v225 offset:2048
	ds_read_b128 v[170:173], v225 offset:3072
	s_add_u32 s48, s4, 0x10100
	s_addc_u32 s49, s5, 0
	s_mov_b32 m0, s47
	v_lshl_add_u64 v[214:215], s[48:49], 0, v[132:133]
	ds_read_b128 v[174:177], v168 offset:32768
	ds_read_b128 v[178:181], v168 offset:33792
	ds_read_b128 v[182:185], v168 offset:34816
	ds_read_b128 v[186:189], v168 offset:35840
	ds_read_b128 v[190:193], v168 offset:36864
	ds_read_b128 v[194:197], v168 offset:37888
	ds_read_b128 v[198:201], v168 offset:38912
	ds_read_b128 v[202:205], v168 offset:39936
	global_load_lds_dwordx4 v[214:215], off
	v_lshl_add_u64 v[214:215], s[48:49], 0, v[136:137]
	s_mov_b32 m0, s50
	s_nop 0
	global_load_lds_dwordx4 v[214:215], off
	s_waitcnt vmcnt(8)
	s_waitcnt lgkmcnt(0)
	s_barrier
	v_mfma_f32_16x16x32_bf16 v[64:67], v[24:27], v[174:177], v[64:67]
	v_mfma_f32_16x16x32_bf16 v[68:71], v[112:115], v[174:177], v[68:71]
	v_mfma_f32_16x16x32_bf16 v[72:75], v[24:27], v[182:185], v[72:75]
	v_mfma_f32_16x16x32_bf16 v[76:79], v[112:115], v[182:185], v[76:79]
	v_mfma_f32_16x16x32_bf16 v[80:83], v[24:27], v[190:193], v[80:83]
	v_mfma_f32_16x16x32_bf16 v[84:87], v[112:115], v[190:193], v[84:87]
	v_mfma_f32_16x16x32_bf16 v[88:91], v[24:27], v[198:201], v[88:91]
	v_mfma_f32_16x16x32_bf16 v[92:95], v[112:115], v[198:201], v[92:95]
	v_mfma_f32_16x16x32_bf16 v[64:67], v[28:31], v[178:181], v[64:67]
	v_mfma_f32_16x16x32_bf16 v[68:71], v[116:119], v[178:181], v[68:71]
	v_mfma_f32_16x16x32_bf16 v[72:75], v[28:31], v[186:189], v[72:75]
	v_mfma_f32_16x16x32_bf16 v[76:79], v[116:119], v[186:189], v[76:79]
	v_mfma_f32_16x16x32_bf16 v[80:83], v[28:31], v[194:197], v[80:83]
	v_mfma_f32_16x16x32_bf16 v[84:87], v[116:119], v[194:197], v[84:87]
	v_mfma_f32_16x16x32_bf16 v[88:91], v[28:31], v[202:205], v[88:91]
	v_mfma_f32_16x16x32_bf16 v[92:95], v[116:119], v[202:205], v[92:95]
	v_mfma_f32_16x16x32_bf16 v[96:99], v[120:123], v[174:177], v[96:99]
	v_mfma_f32_16x16x32_bf16 v[32:35], v[160:163], v[174:177], v[32:35]
	v_mfma_f32_16x16x32_bf16 v[36:39], v[120:123], v[182:185], v[36:39]
	v_mfma_f32_16x16x32_bf16 v[40:43], v[160:163], v[182:185], v[40:43]
	v_mfma_f32_16x16x32_bf16 v[44:47], v[120:123], v[190:193], v[44:47]
	v_mfma_f32_16x16x32_bf16 v[48:51], v[160:163], v[190:193], v[48:51]
	v_mfma_f32_16x16x32_bf16 v[52:55], v[120:123], v[198:201], v[52:55]
	v_mfma_f32_16x16x32_bf16 v[56:59], v[160:163], v[198:201], v[56:59]
	v_mfma_f32_16x16x32_bf16 v[96:99], v[124:127], v[178:181], v[96:99]
	v_mfma_f32_16x16x32_bf16 v[32:35], v[170:173], v[178:181], v[32:35]
	v_mfma_f32_16x16x32_bf16 v[36:39], v[124:127], v[186:189], v[36:39]
	v_mfma_f32_16x16x32_bf16 v[40:43], v[170:173], v[186:189], v[40:43]
	v_mfma_f32_16x16x32_bf16 v[44:47], v[124:127], v[194:197], v[44:47]
	v_mfma_f32_16x16x32_bf16 v[48:51], v[170:173], v[194:197], v[48:51]
	v_mfma_f32_16x16x32_bf16 v[52:55], v[124:127], v[202:205], v[52:55]
	v_mfma_f32_16x16x32_bf16 v[56:59], v[170:173], v[202:205], v[56:59]
	s_barrier
	s_add_i32 s48, s44, s19
	s_add_i32 s44, s48, 0x2000
	v_lshl_add_u64 v[206:207], v[206:207], 0, s[16:17]
	s_mov_b32 m0, s48
	s_add_u32 s72, s34, 0x10180
	ds_read_b128 v[174:177], v168 offset:49152
	ds_read_b128 v[178:181], v168 offset:50176
	ds_read_b128 v[182:185], v168 offset:51200
	ds_read_b128 v[186:189], v168 offset:52224
	ds_read_b128 v[190:193], v168 offset:53248
	ds_read_b128 v[194:197], v168 offset:54272
	ds_read_b128 v[198:201], v168 offset:55296
	ds_read_b128 v[202:205], v168 offset:56320
	global_load_lds_dwordx4 v[206:207], off
	v_lshl_add_u64 v[206:207], v[208:209], 0, s[16:17]
	s_mov_b32 m0, s44
	s_addc_u32 s73, s35, 0
	s_add_i32 s34, s64, s19
	global_load_lds_dwordx4 v[206:207], off
	v_lshl_add_u64 v[206:207], s[72:73], 0, v[134:135]
	s_mov_b32 m0, s34
	s_add_i32 s35, s34, 0x2000
	global_load_lds_dwordx4 v[206:207], off
	v_lshl_add_u64 v[206:207], s[72:73], 0, v[138:139]
	s_mov_b32 m0, s35
	s_nop 0
	global_load_lds_dwordx4 v[206:207], off
	v_lshl_add_u64 v[206:207], v[210:211], 0, s[16:17]
	s_mov_b32 m0, s53
	s_nop 0
	global_load_lds_dwordx4 v[206:207], off
	v_lshl_add_u64 v[206:207], v[212:213], 0, s[16:17]
	s_mov_b32 m0, s55
	s_nop 0
	global_load_lds_dwordx4 v[206:207], off
	s_waitcnt vmcnt(8)
	s_waitcnt lgkmcnt(0)
	s_barrier
	v_mfma_f32_16x16x32_bf16 v[0:3], v[24:27], v[198:201], v[0:3]
	v_mfma_f32_16x16x32_bf16 v[4:7], v[112:115], v[198:201], v[4:7]
	v_mfma_f32_16x16x32_bf16 v[128:131], v[24:27], v[174:177], v[128:131]
	v_mfma_f32_16x16x32_bf16 v[140:143], v[112:115], v[174:177], v[140:143]
	v_mfma_f32_16x16x32_bf16 v[144:147], v[24:27], v[182:185], v[144:147]
	v_mfma_f32_16x16x32_bf16 v[148:151], v[112:115], v[182:185], v[148:151]
	v_mfma_f32_16x16x32_bf16 v[152:155], v[24:27], v[190:193], v[152:155]
	v_mfma_f32_16x16x32_bf16 v[156:159], v[112:115], v[190:193], v[156:159]
	v_mfma_f32_16x16x32_bf16 v[0:3], v[28:31], v[202:205], v[0:3]
	v_mfma_f32_16x16x32_bf16 v[4:7], v[116:119], v[202:205], v[4:7]
	v_mfma_f32_16x16x32_bf16 v[128:131], v[28:31], v[178:181], v[128:131]
	v_mfma_f32_16x16x32_bf16 v[140:143], v[116:119], v[178:181], v[140:143]
	v_mfma_f32_16x16x32_bf16 v[144:147], v[28:31], v[186:189], v[144:147]
	v_mfma_f32_16x16x32_bf16 v[148:151], v[116:119], v[186:189], v[148:151]
	v_mfma_f32_16x16x32_bf16 v[152:155], v[28:31], v[194:197], v[152:155]
	v_mfma_f32_16x16x32_bf16 v[156:159], v[116:119], v[194:197], v[156:159]
	v_mfma_f32_16x16x32_bf16 v[8:11], v[120:123], v[174:177], v[8:11]
	v_mfma_f32_16x16x32_bf16 v[12:15], v[160:163], v[174:177], v[12:15]
	v_mfma_f32_16x16x32_bf16 v[24:27], v[120:123], v[182:185], v[60:63]
	v_mfma_f32_16x16x32_bf16 v[28:31], v[160:163], v[182:185], v[100:103]
	v_mfma_f32_16x16x32_bf16 v[60:63], v[120:123], v[190:193], v[104:107]
	v_mfma_f32_16x16x32_bf16 v[100:103], v[160:163], v[190:193], v[108:111]
	v_mfma_f32_16x16x32_bf16 v[16:19], v[120:123], v[198:201], v[16:19]
	v_mfma_f32_16x16x32_bf16 v[20:23], v[160:163], v[198:201], v[20:23]
	v_mfma_f32_16x16x32_bf16 v[8:11], v[124:127], v[178:181], v[8:11]
	v_mfma_f32_16x16x32_bf16 v[12:15], v[170:173], v[178:181], v[12:15]
	v_mfma_f32_16x16x32_bf16 v[24:27], v[124:127], v[186:189], v[24:27]
	v_mfma_f32_16x16x32_bf16 v[28:31], v[170:173], v[186:189], v[28:31]
	v_mfma_f32_16x16x32_bf16 v[60:63], v[124:127], v[194:197], v[60:63]
	v_mfma_f32_16x16x32_bf16 v[100:103], v[170:173], v[194:197], v[100:103]
	v_mfma_f32_16x16x32_bf16 v[16:19], v[124:127], v[202:205], v[16:19]
	v_mfma_f32_16x16x32_bf16 v[20:23], v[170:173], v[202:205], v[20:23]
	s_barrier
	ds_read_b128 v[104:107], v166
	ds_read_b128 v[108:111], v166 offset:1024
	ds_read_b128 v[112:115], v166 offset:2048
	ds_read_b128 v[116:119], v166 offset:3072
	ds_read_b128 v[120:123], v167
	ds_read_b128 v[124:127], v167 offset:1024
	ds_read_b128 v[160:163], v167 offset:2048
	ds_read_b128 v[170:173], v167 offset:3072
	s_add_u32 s4, s4, 0x10180
	s_addc_u32 s5, s5, 0
	s_mov_b32 m0, s45
	v_lshl_add_u64 v[206:207], s[4:5], 0, v[132:133]
	ds_read_b128 v[174:177], v168
	ds_read_b128 v[178:181], v168 offset:1024
	ds_read_b128 v[182:185], v168 offset:2048
	ds_read_b128 v[186:189], v168 offset:3072
	ds_read_b128 v[190:193], v168 offset:4096
	ds_read_b128 v[194:197], v168 offset:5120
	ds_read_b128 v[198:201], v168 offset:6144
	ds_read_b128 v[202:205], v168 offset:7168
	global_load_lds_dwordx4 v[206:207], off
	v_lshl_add_u64 v[206:207], s[4:5], 0, v[136:137]
	s_mov_b32 m0, s3
	s_nop 0
	global_load_lds_dwordx4 v[206:207], off
	s_waitcnt vmcnt(8)
	s_waitcnt lgkmcnt(0)
	s_barrier
	v_mfma_f32_16x16x32_bf16 v[64:67], v[104:107], v[174:177], v[64:67]
	v_mfma_f32_16x16x32_bf16 v[68:71], v[112:115], v[174:177], v[68:71]
	v_mfma_f32_16x16x32_bf16 v[72:75], v[104:107], v[182:185], v[72:75]
	v_mfma_f32_16x16x32_bf16 v[76:79], v[112:115], v[182:185], v[76:79]
	v_mfma_f32_16x16x32_bf16 v[80:83], v[104:107], v[190:193], v[80:83]
	v_mfma_f32_16x16x32_bf16 v[84:87], v[112:115], v[190:193], v[84:87]
	v_mfma_f32_16x16x32_bf16 v[88:91], v[104:107], v[198:201], v[88:91]
	v_mfma_f32_16x16x32_bf16 v[64:67], v[108:111], v[178:181], v[64:67]
	v_mfma_f32_16x16x32_bf16 v[68:71], v[116:119], v[178:181], v[68:71]
	v_mfma_f32_16x16x32_bf16 v[72:75], v[108:111], v[186:189], v[72:75]
	v_mfma_f32_16x16x32_bf16 v[76:79], v[116:119], v[186:189], v[76:79]
	v_mfma_f32_16x16x32_bf16 v[80:83], v[108:111], v[194:197], v[80:83]
	v_mfma_f32_16x16x32_bf16 v[84:87], v[116:119], v[194:197], v[84:87]
	v_mfma_f32_16x16x32_bf16 v[206:209], v[108:111], v[202:205], v[88:91]
	v_mfma_f32_16x16x32_bf16 v[88:91], v[112:115], v[198:201], v[92:95]
	v_mfma_f32_16x16x32_bf16 v[210:213], v[116:119], v[202:205], v[88:91]
	v_mfma_f32_16x16x32_bf16 v[32:35], v[160:163], v[174:177], v[32:35]
	v_mfma_f32_16x16x32_bf16 v[36:39], v[120:123], v[182:185], v[36:39]
	v_mfma_f32_16x16x32_bf16 v[40:43], v[160:163], v[182:185], v[40:43]
	v_mfma_f32_16x16x32_bf16 v[44:47], v[120:123], v[190:193], v[44:47]
	v_mfma_f32_16x16x32_bf16 v[48:51], v[160:163], v[190:193], v[48:51]
	v_mfma_f32_16x16x32_bf16 v[52:55], v[120:123], v[198:201], v[52:55]
	v_mfma_f32_16x16x32_bf16 v[56:59], v[160:163], v[198:201], v[56:59]
	v_mfma_f32_16x16x32_bf16 v[88:91], v[120:123], v[174:177], v[96:99]
	v_mfma_f32_16x16x32_bf16 v[32:35], v[170:173], v[178:181], v[32:35]
	v_mfma_f32_16x16x32_bf16 v[36:39], v[124:127], v[186:189], v[36:39]
	v_mfma_f32_16x16x32_bf16 v[40:43], v[170:173], v[186:189], v[40:43]
	v_mfma_f32_16x16x32_bf16 v[44:47], v[124:127], v[194:197], v[44:47]
	v_mfma_f32_16x16x32_bf16 v[48:51], v[170:173], v[194:197], v[48:51]
	v_mfma_f32_16x16x32_bf16 v[52:55], v[124:127], v[202:205], v[52:55]
	v_mfma_f32_16x16x32_bf16 v[56:59], v[170:173], v[202:205], v[56:59]
	v_mfma_f32_16x16x32_bf16 v[214:217], v[124:127], v[178:181], v[88:91]
	s_barrier
	s_mov_b32 m0, s43
	v_lshl_add_u64 v[244:245], s[36:37], 0, v[134:135]
	s_add_u32 s4, s36, 0x10000
	ds_read_b128 v[88:91], v168 offset:16384
	ds_read_b128 v[92:95], v168 offset:17408
	ds_read_b128 v[96:99], v168 offset:18432
	ds_read_b128 v[174:177], v168 offset:19456
	ds_read_b128 v[178:181], v168 offset:20480
	ds_read_b128 v[182:185], v168 offset:21504
	ds_read_b128 v[186:189], v168 offset:22528
	ds_read_b128 v[190:193], v168 offset:23552
	global_load_lds_dwordx4 v[244:245], off
	v_lshl_add_u64 v[246:247], s[36:37], 0, v[138:139]
	s_mov_b32 m0, s40
	s_addc_u32 s5, s37, 0
	global_load_lds_dwordx4 v[246:247], off
	v_lshl_add_u64 v[194:195], s[4:5], 0, v[134:135]
	s_mov_b32 m0, s41
	v_lshl_add_u64 v[248:249], s[38:39], 0, v[132:133]
	global_load_lds_dwordx4 v[194:195], off
	v_lshl_add_u64 v[194:195], s[4:5], 0, v[138:139]
	s_mov_b32 m0, s42
	v_lshl_add_u64 v[250:251], s[38:39], 0, v[136:137]
	global_load_lds_dwordx4 v[194:195], off
	s_mov_b32 m0, s21
	s_nop 0
	global_load_lds_dwordx4 v[248:249], off
	s_mov_b32 m0, s46
	s_nop 0
	global_load_lds_dwordx4 v[250:251], off
	s_waitcnt vmcnt(8)
	s_waitcnt lgkmcnt(0)
	s_barrier
	v_mfma_f32_16x16x32_bf16 v[0:3], v[104:107], v[186:189], v[0:3]
	v_mfma_f32_16x16x32_bf16 v[4:7], v[112:115], v[186:189], v[4:7]
	v_mfma_f32_16x16x32_bf16 v[128:131], v[104:107], v[88:91], v[128:131]
	v_mfma_f32_16x16x32_bf16 v[140:143], v[112:115], v[88:91], v[140:143]
	v_mfma_f32_16x16x32_bf16 v[144:147], v[104:107], v[96:99], v[144:147]
	v_mfma_f32_16x16x32_bf16 v[148:151], v[112:115], v[96:99], v[148:151]
	v_mfma_f32_16x16x32_bf16 v[152:155], v[104:107], v[178:181], v[152:155]
	v_mfma_f32_16x16x32_bf16 v[156:159], v[112:115], v[178:181], v[156:159]
	v_mfma_f32_16x16x32_bf16 v[0:3], v[108:111], v[190:193], v[0:3]
	v_mfma_f32_16x16x32_bf16 v[4:7], v[116:119], v[190:193], v[4:7]
	v_mfma_f32_16x16x32_bf16 v[128:131], v[108:111], v[92:95], v[128:131]
	v_mfma_f32_16x16x32_bf16 v[140:143], v[116:119], v[92:95], v[140:143]
	v_mfma_f32_16x16x32_bf16 v[144:147], v[108:111], v[174:177], v[144:147]
	v_mfma_f32_16x16x32_bf16 v[148:151], v[116:119], v[174:177], v[148:151]
	v_mfma_f32_16x16x32_bf16 v[152:155], v[108:111], v[182:185], v[152:155]
	v_mfma_f32_16x16x32_bf16 v[156:159], v[116:119], v[182:185], v[156:159]
	v_mfma_f32_16x16x32_bf16 v[8:11], v[120:123], v[88:91], v[8:11]
	v_mfma_f32_16x16x32_bf16 v[194:197], v[124:127], v[92:95], v[8:11]
	v_mfma_f32_16x16x32_bf16 v[8:11], v[160:163], v[88:91], v[12:15]
	v_mfma_f32_16x16x32_bf16 v[198:201], v[170:173], v[92:95], v[8:11]
	v_mfma_f32_16x16x32_bf16 v[8:11], v[120:123], v[96:99], v[24:27]
	v_mfma_f32_16x16x32_bf16 v[202:205], v[124:127], v[174:177], v[8:11]
	v_mfma_f32_16x16x32_bf16 v[8:11], v[160:163], v[96:99], v[28:31]
	v_mfma_f32_16x16x32_bf16 v[174:177], v[170:173], v[174:177], v[8:11]
	v_mfma_f32_16x16x32_bf16 v[8:11], v[120:123], v[178:181], v[60:63]
	v_mfma_f32_16x16x32_bf16 v[220:223], v[124:127], v[182:185], v[8:11]
	v_mfma_f32_16x16x32_bf16 v[8:11], v[160:163], v[178:181], v[100:103]
	v_mfma_f32_16x16x32_bf16 v[178:181], v[170:173], v[182:185], v[8:11]
	v_mfma_f32_16x16x32_bf16 v[8:11], v[120:123], v[186:189], v[16:19]
	v_mfma_f32_16x16x32_bf16 v[182:185], v[124:127], v[190:193], v[8:11]
	v_mfma_f32_16x16x32_bf16 v[8:11], v[160:163], v[186:189], v[20:23]
	v_mfma_f32_16x16x32_bf16 v[160:163], v[170:173], v[190:193], v[8:11]
	s_barrier
	s_nop 4
	ds_read_b128 v[8:11], v224
	ds_read_b128 v[12:15], v224 offset:1024
	ds_read_b128 v[16:19], v224 offset:2048
	ds_read_b128 v[20:23], v224 offset:3072
	ds_read_b128 v[170:173], v225
	ds_read_b128 v[186:189], v225 offset:1024
	ds_read_b128 v[190:193], v225 offset:2048
	ds_read_b128 v[224:227], v225 offset:3072
	s_add_u32 s4, s38, 0x10000
	s_addc_u32 s5, s39, 0
	s_mov_b32 m0, s47
	v_lshl_add_u64 v[88:89], s[4:5], 0, v[132:133]
	ds_read_b128 v[24:27], v168 offset:32768
	ds_read_b128 v[28:31], v168 offset:33792
	ds_read_b128 v[60:63], v168 offset:34816
	ds_read_b128 v[108:111], v168 offset:35840
	ds_read_b128 v[228:231], v168 offset:36864
	ds_read_b128 v[232:235], v168 offset:37888
	ds_read_b128 v[236:239], v168 offset:38912
	ds_read_b128 v[240:243], v168 offset:39936
	global_load_lds_dwordx4 v[88:89], off
	v_lshl_add_u64 v[88:89], s[4:5], 0, v[136:137]
	s_mov_b32 m0, s50
	s_nop 0
	global_load_lds_dwordx4 v[88:89], off
	s_waitcnt vmcnt(8)
	s_waitcnt lgkmcnt(0)
	s_barrier
	v_mfma_f32_16x16x32_bf16 v[64:67], v[8:11], v[24:27], v[64:67]
	v_mfma_f32_16x16x32_bf16 v[112:115], v[12:15], v[28:31], v[64:67]
	v_mfma_f32_16x16x32_bf16 v[64:67], v[16:19], v[24:27], v[68:71]
	v_mfma_f32_16x16x32_bf16 v[116:119], v[20:23], v[28:31], v[64:67]
	v_mfma_f32_16x16x32_bf16 v[64:67], v[8:11], v[60:63], v[72:75]
	v_mfma_f32_16x16x32_bf16 v[96:99], v[12:15], v[108:111], v[64:67]
	v_mfma_f32_16x16x32_bf16 v[64:67], v[16:19], v[60:63], v[76:79]
	v_mfma_f32_16x16x32_bf16 v[100:103], v[20:23], v[108:111], v[64:67]
	v_mfma_f32_16x16x32_bf16 v[64:67], v[8:11], v[228:231], v[80:83]
	v_mfma_f32_16x16x32_bf16 v[92:95], v[12:15], v[232:235], v[64:67]
	v_mfma_f32_16x16x32_bf16 v[64:67], v[16:19], v[228:231], v[84:87]
	v_mfma_f32_16x16x32_bf16 v[88:91], v[20:23], v[232:235], v[64:67]
	v_mfma_f32_16x16x32_bf16 v[64:67], v[8:11], v[236:239], v[206:209]
	v_mfma_f32_16x16x32_bf16 v[76:79], v[12:15], v[240:243], v[64:67]
	v_mfma_f32_16x16x32_bf16 v[64:67], v[16:19], v[236:239], v[210:213]
	v_mfma_f32_16x16x32_bf16 v[72:75], v[20:23], v[240:243], v[64:67]
	v_mfma_f32_16x16x32_bf16 v[64:67], v[170:173], v[24:27], v[214:217]
	v_mfma_f32_16x16x32_bf16 v[24:27], v[190:193], v[24:27], v[32:35]
	v_mfma_f32_16x16x32_bf16 v[124:127], v[224:227], v[28:31], v[24:27]
	v_mfma_f32_16x16x32_bf16 v[24:27], v[170:173], v[60:63], v[36:39]
	v_mfma_f32_16x16x32_bf16 v[104:107], v[186:189], v[108:111], v[24:27]
	v_mfma_f32_16x16x32_bf16 v[24:27], v[190:193], v[60:63], v[40:43]
	v_mfma_f32_16x16x32_bf16 v[108:111], v[224:227], v[108:111], v[24:27]
	v_mfma_f32_16x16x32_bf16 v[24:27], v[170:173], v[228:231], v[44:47]
	v_mfma_f32_16x16x32_bf16 v[84:87], v[186:189], v[232:235], v[24:27]
	v_mfma_f32_16x16x32_bf16 v[24:27], v[190:193], v[228:231], v[48:51]
	v_mfma_f32_16x16x32_bf16 v[80:83], v[224:227], v[232:235], v[24:27]
	v_mfma_f32_16x16x32_bf16 v[24:27], v[170:173], v[236:239], v[52:55]
	v_mfma_f32_16x16x32_bf16 v[68:71], v[186:189], v[240:243], v[24:27]
	v_mfma_f32_16x16x32_bf16 v[24:27], v[190:193], v[236:239], v[56:59]
	v_mfma_f32_16x16x32_bf16 v[120:123], v[186:189], v[28:31], v[64:67]
	v_mfma_f32_16x16x32_bf16 v[64:67], v[224:227], v[240:243], v[24:27]
	s_barrier
	s_mov_b32 m0, s48
	s_nop 2
	v_lshl_add_u64 v[24:25], v[244:245], 0, s[10:11]
	s_add_u32 s4, s36, 0x10080
	ds_read_b128 v[32:35], v168 offset:49152
	ds_read_b128 v[36:39], v168 offset:50176
	ds_read_b128 v[206:209], v168 offset:51200
	ds_read_b128 v[210:213], v168 offset:52224
	ds_read_b128 v[214:217], v168 offset:53248
	ds_read_b128 v[228:231], v168 offset:54272
	ds_read_b128 v[232:235], v168 offset:55296
	ds_read_b128 v[236:239], v168 offset:56320
	global_load_lds_dwordx4 v[24:25], off
	v_lshl_add_u64 v[24:25], v[246:247], 0, s[10:11]
	s_mov_b32 m0, s44
	s_addc_u32 s5, s37, 0
	global_load_lds_dwordx4 v[24:25], off
	v_lshl_add_u64 v[24:25], s[4:5], 0, v[134:135]
	s_mov_b32 m0, s34
	s_nop 0
	global_load_lds_dwordx4 v[24:25], off
	v_lshl_add_u64 v[24:25], s[4:5], 0, v[138:139]
	s_mov_b32 m0, s35
	s_nop 0
	global_load_lds_dwordx4 v[24:25], off
	v_lshl_add_u64 v[24:25], v[248:249], 0, s[10:11]
	s_mov_b32 m0, s53
	s_nop 0
	global_load_lds_dwordx4 v[24:25], off
	v_lshl_add_u64 v[24:25], v[250:251], 0, s[10:11]
	s_mov_b32 m0, s55
	s_nop 0
	global_load_lds_dwordx4 v[24:25], off
	s_waitcnt vmcnt(8)
	s_waitcnt lgkmcnt(0)
	s_barrier
	v_mfma_f32_16x16x32_bf16 v[24:27], v[8:11], v[32:35], v[128:131]
	v_mfma_f32_16x16x32_bf16 v[60:63], v[12:15], v[36:39], v[24:27]
	v_mfma_f32_16x16x32_bf16 v[24:27], v[16:19], v[32:35], v[140:143]
	v_mfma_f32_16x16x32_bf16 v[56:59], v[20:23], v[36:39], v[24:27]
	v_mfma_f32_16x16x32_bf16 v[24:27], v[8:11], v[206:209], v[144:147]
	v_mfma_f32_16x16x32_bf16 v[44:47], v[12:15], v[210:213], v[24:27]
	v_mfma_f32_16x16x32_bf16 v[24:27], v[16:19], v[206:209], v[148:151]
	v_mfma_f32_16x16x32_bf16 v[40:43], v[20:23], v[210:213], v[24:27]
	v_mfma_f32_16x16x32_bf16 v[24:27], v[8:11], v[214:217], v[152:155]
	v_mfma_f32_16x16x32_bf16 v[0:3], v[8:11], v[232:235], v[0:3]
	v_mfma_f32_16x16x32_bf16 v[28:31], v[12:15], v[228:231], v[24:27]
	v_mfma_f32_16x16x32_bf16 v[24:27], v[16:19], v[214:217], v[156:159]
	v_mfma_f32_16x16x32_bf16 v[12:15], v[12:15], v[236:239], v[0:3]
	v_mfma_f32_16x16x32_bf16 v[0:3], v[16:19], v[232:235], v[4:7]
	v_mfma_f32_16x16x32_bf16 v[24:27], v[20:23], v[228:231], v[24:27]
	v_mfma_f32_16x16x32_bf16 v[8:11], v[20:23], v[236:239], v[0:3]
	v_mfma_f32_16x16x32_bf16 v[0:3], v[170:173], v[32:35], v[194:197]
	v_mfma_f32_16x16x32_bf16 v[52:55], v[186:189], v[36:39], v[0:3]
	v_mfma_f32_16x16x32_bf16 v[0:3], v[190:193], v[32:35], v[198:201]
	v_mfma_f32_16x16x32_bf16 v[48:51], v[224:227], v[36:39], v[0:3]
	v_mfma_f32_16x16x32_bf16 v[0:3], v[170:173], v[206:209], v[202:205]
	v_mfma_f32_16x16x32_bf16 v[36:39], v[186:189], v[210:213], v[0:3]
	v_mfma_f32_16x16x32_bf16 v[0:3], v[190:193], v[206:209], v[174:177]
	v_mfma_f32_16x16x32_bf16 v[32:35], v[224:227], v[210:213], v[0:3]
	v_mfma_f32_16x16x32_bf16 v[0:3], v[170:173], v[214:217], v[220:223]
	v_mfma_f32_16x16x32_bf16 v[20:23], v[186:189], v[228:231], v[0:3]
	v_mfma_f32_16x16x32_bf16 v[0:3], v[190:193], v[214:217], v[178:181]
	v_mfma_f32_16x16x32_bf16 v[16:19], v[224:227], v[228:231], v[0:3]
	v_mfma_f32_16x16x32_bf16 v[0:3], v[170:173], v[232:235], v[182:185]
	v_mfma_f32_16x16x32_bf16 v[4:7], v[186:189], v[236:239], v[0:3]
	v_mfma_f32_16x16x32_bf16 v[0:3], v[190:193], v[232:235], v[160:163]
	v_mfma_f32_16x16x32_bf16 v[0:3], v[224:227], v[236:239], v[0:3]
	s_barrier
	s_andn2_b64 vcc, exec, s[12:13]
	s_cbranch_vccnz .LBB0_400
	s_barrier

.LBB0_479:
	ds_read_b128 v[128:131], v160
	ds_read_b128 v[144:147], v160 offset:1024
	ds_read_b128 v[148:151], v160 offset:2048
	ds_read_b128 v[152:155], v160 offset:3072
	ds_read_b128 v[164:167], v161
	ds_read_b128 v[168:171], v161 offset:1024
	ds_read_b128 v[172:175], v161 offset:2048
	ds_read_b128 v[176:179], v161 offset:3072
	s_add_u32 s18, s16, 0xfff80080
	s_addc_u32 s19, s17, -1
	s_cmp_eq_u32 s47, 4
	s_cselect_b32 s21, s11, s19
	s_cselect_b32 s20, s10, s18
	s_cselect_b32 s19, s13, s45
	s_cselect_b32 s18, s12, s44
	v_lshl_add_u64 v[156:157], s[16:17], 0, v[140:141]
	s_add_i32 m0, s24, 0xc000
	ds_read_b128 v[180:183], v162
	ds_read_b128 v[184:187], v162 offset:1024
	ds_read_b128 v[188:191], v162 offset:2048
	ds_read_b128 v[192:195], v162 offset:3072
	ds_read_b128 v[196:199], v162 offset:4096
	ds_read_b128 v[200:203], v162 offset:5120
	ds_read_b128 v[204:207], v162 offset:6144
	ds_read_b128 v[208:211], v162 offset:7168
	global_load_lds_dwordx4 v[156:157], off
	v_lshl_add_u64 v[156:157], s[16:17], 0, v[142:143]
	s_add_i32 m0, s24, 0xe000
	s_nop 0
	global_load_lds_dwordx4 v[156:157], off
	s_waitcnt vmcnt(8)
	s_waitcnt lgkmcnt(0)
	s_barrier
	v_mfma_f32_16x16x32_bf16 v[124:127], v[128:131], v[180:183], v[124:127]
	v_mfma_f32_16x16x32_bf16 v[120:123], v[148:151], v[180:183], v[120:123]
	v_mfma_f32_16x16x32_bf16 v[116:119], v[128:131], v[188:191], v[116:119]
	v_mfma_f32_16x16x32_bf16 v[108:111], v[148:151], v[188:191], v[108:111]
	v_mfma_f32_16x16x32_bf16 v[100:103], v[128:131], v[196:199], v[100:103]
	v_mfma_f32_16x16x32_bf16 v[92:95], v[148:151], v[196:199], v[92:95]
	v_mfma_f32_16x16x32_bf16 v[84:87], v[128:131], v[204:207], v[84:87]
	v_mfma_f32_16x16x32_bf16 v[76:79], v[148:151], v[204:207], v[76:79]
	v_mfma_f32_16x16x32_bf16 v[124:127], v[144:147], v[184:187], v[124:127]
	v_mfma_f32_16x16x32_bf16 v[120:123], v[152:155], v[184:187], v[120:123]
	v_mfma_f32_16x16x32_bf16 v[116:119], v[144:147], v[192:195], v[116:119]
	v_mfma_f32_16x16x32_bf16 v[108:111], v[152:155], v[192:195], v[108:111]
	v_mfma_f32_16x16x32_bf16 v[100:103], v[144:147], v[200:203], v[100:103]
	v_mfma_f32_16x16x32_bf16 v[92:95], v[152:155], v[200:203], v[92:95]
	v_mfma_f32_16x16x32_bf16 v[84:87], v[144:147], v[208:211], v[84:87]
	v_mfma_f32_16x16x32_bf16 v[76:79], v[152:155], v[208:211], v[76:79]
	v_mfma_f32_16x16x32_bf16 v[112:115], v[164:167], v[180:183], v[112:115]
	v_mfma_f32_16x16x32_bf16 v[104:107], v[172:175], v[180:183], v[104:107]
	v_mfma_f32_16x16x32_bf16 v[96:99], v[164:167], v[188:191], v[96:99]
	v_mfma_f32_16x16x32_bf16 v[88:91], v[172:175], v[188:191], v[88:91]
	v_mfma_f32_16x16x32_bf16 v[80:83], v[164:167], v[196:199], v[80:83]
	v_mfma_f32_16x16x32_bf16 v[72:75], v[172:175], v[196:199], v[72:75]
	v_mfma_f32_16x16x32_bf16 v[68:71], v[164:167], v[204:207], v[68:71]
	v_mfma_f32_16x16x32_bf16 v[64:67], v[172:175], v[204:207], v[64:67]
	v_mfma_f32_16x16x32_bf16 v[112:115], v[168:171], v[184:187], v[112:115]
	v_mfma_f32_16x16x32_bf16 v[104:107], v[176:179], v[184:187], v[104:107]
	v_mfma_f32_16x16x32_bf16 v[96:99], v[168:171], v[192:195], v[96:99]
	v_mfma_f32_16x16x32_bf16 v[88:91], v[176:179], v[192:195], v[88:91]
	v_mfma_f32_16x16x32_bf16 v[80:83], v[168:171], v[200:203], v[80:83]
	v_mfma_f32_16x16x32_bf16 v[72:75], v[176:179], v[200:203], v[72:75]
	v_mfma_f32_16x16x32_bf16 v[68:71], v[168:171], v[208:211], v[68:71]
	v_mfma_f32_16x16x32_bf16 v[64:67], v[176:179], v[208:211], v[64:67]
	s_barrier
	s_add_i32 s48, s36, s3
	v_lshl_add_u64 v[156:157], s[18:19], 0, v[134:135]
	s_mov_b32 m0, s48
	ds_read_b128 v[180:183], v162 offset:16384
	ds_read_b128 v[184:187], v162 offset:17408
	ds_read_b128 v[188:191], v162 offset:18432
	ds_read_b128 v[192:195], v162 offset:19456
	ds_read_b128 v[196:199], v162 offset:20480
	ds_read_b128 v[200:203], v162 offset:21504
	ds_read_b128 v[204:207], v162 offset:22528
	ds_read_b128 v[208:211], v162 offset:23552
	global_load_lds_dwordx4 v[156:157], off
	s_add_i32 m0, s48, 0x2000
	s_add_u32 s48, s18, 0x80000
	v_lshl_add_u64 v[212:213], s[18:19], 0, v[138:139]
	s_addc_u32 s49, s19, 0
	s_add_i32 s50, s37, s3
	global_load_lds_dwordx4 v[212:213], off
	v_lshl_add_u64 v[214:215], s[48:49], 0, v[134:135]
	s_mov_b32 m0, s50
	v_lshl_add_u64 v[216:217], s[20:21], 0, v[136:137]
	global_load_lds_dwordx4 v[214:215], off
	v_lshl_add_u64 v[214:215], s[48:49], 0, v[138:139]
	s_add_i32 m0, s50, 0x2000
	s_nop 0
	global_load_lds_dwordx4 v[214:215], off
	v_lshl_add_u64 v[214:215], s[20:21], 0, v[132:133]
	s_mov_b32 m0, s24
	s_nop 0
	global_load_lds_dwordx4 v[214:215], off
	s_mov_b32 m0, s25
	s_nop 0
	global_load_lds_dwordx4 v[216:217], off
	s_waitcnt vmcnt(8)
	s_waitcnt lgkmcnt(0)
	s_barrier
	v_mfma_f32_16x16x32_bf16 v[60:63], v[128:131], v[180:183], v[60:63]
	v_mfma_f32_16x16x32_bf16 v[56:59], v[148:151], v[180:183], v[56:59]
	v_mfma_f32_16x16x32_bf16 v[52:55], v[128:131], v[188:191], v[52:55]
	v_mfma_f32_16x16x32_bf16 v[44:47], v[148:151], v[188:191], v[44:47]
	v_mfma_f32_16x16x32_bf16 v[36:39], v[128:131], v[196:199], v[36:39]
	v_mfma_f32_16x16x32_bf16 v[28:31], v[148:151], v[196:199], v[28:31]
	v_mfma_f32_16x16x32_bf16 v[20:23], v[128:131], v[204:207], v[20:23]
	v_mfma_f32_16x16x32_bf16 v[12:15], v[148:151], v[204:207], v[12:15]
	v_mfma_f32_16x16x32_bf16 v[60:63], v[144:147], v[184:187], v[60:63]
	v_mfma_f32_16x16x32_bf16 v[56:59], v[152:155], v[184:187], v[56:59]
	v_mfma_f32_16x16x32_bf16 v[52:55], v[144:147], v[192:195], v[52:55]
	v_mfma_f32_16x16x32_bf16 v[44:47], v[152:155], v[192:195], v[44:47]
	v_mfma_f32_16x16x32_bf16 v[36:39], v[144:147], v[200:203], v[36:39]
	v_mfma_f32_16x16x32_bf16 v[28:31], v[152:155], v[200:203], v[28:31]
	v_mfma_f32_16x16x32_bf16 v[20:23], v[144:147], v[208:211], v[20:23]
	v_mfma_f32_16x16x32_bf16 v[12:15], v[152:155], v[208:211], v[12:15]
	v_mfma_f32_16x16x32_bf16 v[48:51], v[164:167], v[180:183], v[48:51]
	v_mfma_f32_16x16x32_bf16 v[40:43], v[172:175], v[180:183], v[40:43]
	v_mfma_f32_16x16x32_bf16 v[32:35], v[164:167], v[188:191], v[32:35]
	v_mfma_f32_16x16x32_bf16 v[24:27], v[172:175], v[188:191], v[24:27]
	v_mfma_f32_16x16x32_bf16 v[16:19], v[164:167], v[196:199], v[16:19]
	v_mfma_f32_16x16x32_bf16 v[8:11], v[172:175], v[196:199], v[8:11]
	v_mfma_f32_16x16x32_bf16 v[4:7], v[164:167], v[204:207], v[4:7]
	v_mfma_f32_16x16x32_bf16 v[0:3], v[172:175], v[204:207], v[0:3]
	v_mfma_f32_16x16x32_bf16 v[48:51], v[168:171], v[184:187], v[48:51]
	v_mfma_f32_16x16x32_bf16 v[40:43], v[176:179], v[184:187], v[40:43]
	v_mfma_f32_16x16x32_bf16 v[32:35], v[168:171], v[192:195], v[32:35]
	v_mfma_f32_16x16x32_bf16 v[24:27], v[176:179], v[192:195], v[24:27]
	v_mfma_f32_16x16x32_bf16 v[16:19], v[168:171], v[200:203], v[16:19]
	v_mfma_f32_16x16x32_bf16 v[8:11], v[176:179], v[200:203], v[8:11]
	v_mfma_f32_16x16x32_bf16 v[4:7], v[168:171], v[208:211], v[4:7]
	v_mfma_f32_16x16x32_bf16 v[0:3], v[176:179], v[208:211], v[0:3]
	s_barrier
	s_add_i32 s48, 0, 0x18000
	s_add_i32 s49, 0, 0x1c000
	v_add_u32_e32 v152, s48, v159
	v_add_u32_e32 v163, s49, v159
	ds_read_b128 v[128:131], v152
	ds_read_b128 v[144:147], v152 offset:1024
	ds_read_b128 v[148:151], v152 offset:2048
	ds_read_b128 v[152:155], v152 offset:3072
	ds_read_b128 v[164:167], v163
	ds_read_b128 v[168:171], v163 offset:1024
	ds_read_b128 v[172:175], v163 offset:2048
	ds_read_b128 v[176:179], v163 offset:3072
	s_add_u32 s20, s20, 0x80000
	s_addc_u32 s21, s21, 0
	s_mov_b32 m0, s26
	v_lshl_add_u64 v[220:221], s[20:21], 0, v[132:133]
	ds_read_b128 v[180:183], v162 offset:32768
	ds_read_b128 v[184:187], v162 offset:33792
	ds_read_b128 v[188:191], v162 offset:34816
	ds_read_b128 v[192:195], v162 offset:35840
	ds_read_b128 v[196:199], v162 offset:36864
	ds_read_b128 v[200:203], v162 offset:37888
	ds_read_b128 v[204:207], v162 offset:38912
	ds_read_b128 v[208:211], v162 offset:39936
	global_load_lds_dwordx4 v[220:221], off
	v_lshl_add_u64 v[220:221], s[20:21], 0, v[136:137]
	s_mov_b32 m0, s27
	s_nop 0
	global_load_lds_dwordx4 v[220:221], off
	s_waitcnt vmcnt(8)
	s_waitcnt lgkmcnt(0)
	s_barrier
	v_mfma_f32_16x16x32_bf16 v[124:127], v[128:131], v[180:183], v[124:127]
	v_mfma_f32_16x16x32_bf16 v[120:123], v[148:151], v[180:183], v[120:123]
	v_mfma_f32_16x16x32_bf16 v[116:119], v[128:131], v[188:191], v[116:119]
	v_mfma_f32_16x16x32_bf16 v[108:111], v[148:151], v[188:191], v[108:111]
	v_mfma_f32_16x16x32_bf16 v[100:103], v[128:131], v[196:199], v[100:103]
	v_mfma_f32_16x16x32_bf16 v[92:95], v[148:151], v[196:199], v[92:95]
	v_mfma_f32_16x16x32_bf16 v[84:87], v[128:131], v[204:207], v[84:87]
	v_mfma_f32_16x16x32_bf16 v[76:79], v[148:151], v[204:207], v[76:79]
	v_mfma_f32_16x16x32_bf16 v[124:127], v[144:147], v[184:187], v[124:127]
	v_mfma_f32_16x16x32_bf16 v[120:123], v[152:155], v[184:187], v[120:123]
	v_mfma_f32_16x16x32_bf16 v[116:119], v[144:147], v[192:195], v[116:119]
	v_mfma_f32_16x16x32_bf16 v[108:111], v[152:155], v[192:195], v[108:111]
	v_mfma_f32_16x16x32_bf16 v[100:103], v[144:147], v[200:203], v[100:103]
	v_mfma_f32_16x16x32_bf16 v[92:95], v[152:155], v[200:203], v[92:95]
	v_mfma_f32_16x16x32_bf16 v[84:87], v[144:147], v[208:211], v[84:87]
	v_mfma_f32_16x16x32_bf16 v[76:79], v[152:155], v[208:211], v[76:79]
	v_mfma_f32_16x16x32_bf16 v[112:115], v[164:167], v[180:183], v[112:115]
	v_mfma_f32_16x16x32_bf16 v[104:107], v[172:175], v[180:183], v[104:107]
	v_mfma_f32_16x16x32_bf16 v[96:99], v[164:167], v[188:191], v[96:99]
	v_mfma_f32_16x16x32_bf16 v[88:91], v[172:175], v[188:191], v[88:91]
	v_mfma_f32_16x16x32_bf16 v[80:83], v[164:167], v[196:199], v[80:83]
	v_mfma_f32_16x16x32_bf16 v[72:75], v[172:175], v[196:199], v[72:75]
	v_mfma_f32_16x16x32_bf16 v[68:71], v[164:167], v[204:207], v[68:71]
	v_mfma_f32_16x16x32_bf16 v[64:67], v[172:175], v[204:207], v[64:67]
	v_mfma_f32_16x16x32_bf16 v[112:115], v[168:171], v[184:187], v[112:115]
	v_mfma_f32_16x16x32_bf16 v[104:107], v[176:179], v[184:187], v[104:107]
	v_mfma_f32_16x16x32_bf16 v[96:99], v[168:171], v[192:195], v[96:99]
	v_mfma_f32_16x16x32_bf16 v[88:91], v[176:179], v[192:195], v[88:91]
	v_mfma_f32_16x16x32_bf16 v[80:83], v[168:171], v[200:203], v[80:83]
	v_mfma_f32_16x16x32_bf16 v[72:75], v[176:179], v[200:203], v[72:75]
	v_mfma_f32_16x16x32_bf16 v[68:71], v[168:171], v[208:211], v[68:71]
	v_mfma_f32_16x16x32_bf16 v[64:67], v[176:179], v[208:211], v[64:67]
	s_barrier
	s_add_i32 s20, s48, s3
	v_lshl_add_u64 v[156:157], v[156:157], 0, s[4:5]
	s_mov_b32 m0, s20
	ds_read_b128 v[180:183], v162 offset:49152
	ds_read_b128 v[184:187], v162 offset:50176
	ds_read_b128 v[188:191], v162 offset:51200
	ds_read_b128 v[192:195], v162 offset:52224
	ds_read_b128 v[196:199], v162 offset:53248
	ds_read_b128 v[200:203], v162 offset:54272
	ds_read_b128 v[204:207], v162 offset:55296
	ds_read_b128 v[208:211], v162 offset:56320
	global_load_lds_dwordx4 v[156:157], off
	s_add_i32 m0, s20, 0x2000
	s_add_u32 s18, s18, 0x80080
	v_lshl_add_u64 v[156:157], v[212:213], 0, s[4:5]
	s_addc_u32 s19, s19, 0
	s_add_i32 s20, s49, s3
	global_load_lds_dwordx4 v[156:157], off
	v_lshl_add_u64 v[156:157], s[18:19], 0, v[134:135]
	s_mov_b32 m0, s20
	s_nop 0
	global_load_lds_dwordx4 v[156:157], off
	v_lshl_add_u64 v[156:157], s[18:19], 0, v[138:139]
	s_add_i32 m0, s20, 0x2000
	s_nop 0
	global_load_lds_dwordx4 v[156:157], off
	v_lshl_add_u64 v[156:157], v[214:215], 0, s[4:5]
	s_mov_b32 m0, s34
	s_nop 0
	global_load_lds_dwordx4 v[156:157], off
	v_lshl_add_u64 v[156:157], v[216:217], 0, s[4:5]
	s_mov_b32 m0, s35
	s_nop 0
	global_load_lds_dwordx4 v[156:157], off
	s_waitcnt vmcnt(8)
	s_waitcnt lgkmcnt(0)
	s_barrier
	v_mfma_f32_16x16x32_bf16 v[60:63], v[128:131], v[180:183], v[60:63]
	v_mfma_f32_16x16x32_bf16 v[56:59], v[148:151], v[180:183], v[56:59]
	v_mfma_f32_16x16x32_bf16 v[52:55], v[128:131], v[188:191], v[52:55]
	v_mfma_f32_16x16x32_bf16 v[44:47], v[148:151], v[188:191], v[44:47]
	v_mfma_f32_16x16x32_bf16 v[36:39], v[128:131], v[196:199], v[36:39]
	v_mfma_f32_16x16x32_bf16 v[28:31], v[148:151], v[196:199], v[28:31]
	v_mfma_f32_16x16x32_bf16 v[20:23], v[128:131], v[204:207], v[20:23]
	v_mfma_f32_16x16x32_bf16 v[12:15], v[148:151], v[204:207], v[12:15]
	v_mfma_f32_16x16x32_bf16 v[60:63], v[144:147], v[184:187], v[60:63]
	v_mfma_f32_16x16x32_bf16 v[56:59], v[152:155], v[184:187], v[56:59]
	v_mfma_f32_16x16x32_bf16 v[52:55], v[144:147], v[192:195], v[52:55]
	v_mfma_f32_16x16x32_bf16 v[44:47], v[152:155], v[192:195], v[44:47]
	v_mfma_f32_16x16x32_bf16 v[36:39], v[144:147], v[200:203], v[36:39]
	v_mfma_f32_16x16x32_bf16 v[28:31], v[152:155], v[200:203], v[28:31]
	v_mfma_f32_16x16x32_bf16 v[20:23], v[144:147], v[208:211], v[20:23]
	v_mfma_f32_16x16x32_bf16 v[12:15], v[152:155], v[208:211], v[12:15]
	v_mfma_f32_16x16x32_bf16 v[48:51], v[164:167], v[180:183], v[48:51]
	v_mfma_f32_16x16x32_bf16 v[40:43], v[172:175], v[180:183], v[40:43]
	v_mfma_f32_16x16x32_bf16 v[32:35], v[164:167], v[188:191], v[32:35]
	v_mfma_f32_16x16x32_bf16 v[24:27], v[172:175], v[188:191], v[24:27]
	v_mfma_f32_16x16x32_bf16 v[16:19], v[164:167], v[196:199], v[16:19]
	v_mfma_f32_16x16x32_bf16 v[8:11], v[172:175], v[196:199], v[8:11]
	v_mfma_f32_16x16x32_bf16 v[4:7], v[164:167], v[204:207], v[4:7]
	v_mfma_f32_16x16x32_bf16 v[0:3], v[172:175], v[204:207], v[0:3]
	v_mfma_f32_16x16x32_bf16 v[48:51], v[168:171], v[184:187], v[48:51]
	v_mfma_f32_16x16x32_bf16 v[40:43], v[176:179], v[184:187], v[40:43]
	v_mfma_f32_16x16x32_bf16 v[32:35], v[168:171], v[192:195], v[32:35]
	v_mfma_f32_16x16x32_bf16 v[24:27], v[176:179], v[192:195], v[24:27]
	v_mfma_f32_16x16x32_bf16 v[16:19], v[168:171], v[200:203], v[16:19]
	v_mfma_f32_16x16x32_bf16 v[8:11], v[176:179], v[200:203], v[8:11]
	v_mfma_f32_16x16x32_bf16 v[4:7], v[168:171], v[208:211], v[4:7]
	v_mfma_f32_16x16x32_bf16 v[0:3], v[176:179], v[208:211], v[0:3]
	s_barrier
	s_add_i32 s47, s47, 2
	s_add_u32 s16, s16, 0x100
	s_addc_u32 s17, s17, 0
	s_add_u32 s44, s44, 0x100
	s_addc_u32 s45, s45, 0
	s_cmp_gt_u32 s47, 5
	s_cbranch_scc0 .LBB0_479
	s_and_b64 vcc, exec, s[6:7]
	s_cbranch_vccz .LBB0_482
	s_barrier

.LBB0_620:
	v_add_u32_e32 v1, s67, v221
	ds_read_b128 v[136:139], v1
	ds_read_b128 v[140:143], v1 offset:1024
	ds_read_b128 v[144:147], v1 offset:2048
	ds_read_b128 v[148:151], v1 offset:3072
	v_add_u32_e32 v1, s68, v221
	s_add_u32 s4, s0, s52
	ds_read_b128 v[152:155], v1
	ds_read_b128 v[156:159], v1 offset:1024
	ds_read_b128 v[160:163], v1 offset:2048
	ds_read_b128 v[164:167], v1 offset:3072
	s_addc_u32 s5, s1, s53
	s_add_u32 s4, s4, 0x100
	s_addc_u32 s5, s5, 0
	s_add_u32 s10, s40, s52
	s_addc_u32 s11, s41, s53
	s_cmpk_eq_i32 s52, 0xf00
	s_cselect_b32 s7, s39, s5
	s_cselect_b32 s6, s38, s4
	s_cselect_b32 s5, s47, s11
	s_cselect_b32 s4, s46, s10
	v_lshl_add_u64 v[2:3], v[132:133], 0, s[52:53]
	s_add_i32 m0, s27, 0xc000
	ds_read_b128 v[168:171], v222
	ds_read_b128 v[172:175], v222 offset:1024
	ds_read_b128 v[176:179], v222 offset:2048
	ds_read_b128 v[180:183], v222 offset:3072
	ds_read_b128 v[184:187], v222 offset:4096
	ds_read_b128 v[188:191], v222 offset:5120
	ds_read_b128 v[192:195], v222 offset:6144
	ds_read_b128 v[208:211], v222 offset:7168
	global_load_lds_dwordx4 v[2:3], off
	v_lshl_add_u64 v[2:3], v[134:135], 0, s[52:53]
	s_add_i32 m0, s27, 0xe000
	s_nop 0
	global_load_lds_dwordx4 v[2:3], off
	s_waitcnt vmcnt(8)
	s_waitcnt lgkmcnt(0)
	s_barrier
	v_mfma_f32_16x16x32_bf16 v[128:131], v[136:139], v[168:171], v[128:131]
	v_mfma_f32_16x16x32_bf16 v[124:127], v[144:147], v[168:171], v[124:127]
	v_mfma_f32_16x16x32_bf16 v[112:115], v[136:139], v[176:179], v[112:115]
	v_mfma_f32_16x16x32_bf16 v[108:111], v[144:147], v[176:179], v[108:111]
	v_mfma_f32_16x16x32_bf16 v[96:99], v[136:139], v[184:187], v[96:99]
	v_mfma_f32_16x16x32_bf16 v[92:95], v[144:147], v[184:187], v[92:95]
	v_mfma_f32_16x16x32_bf16 v[80:83], v[136:139], v[192:195], v[80:83]
	v_mfma_f32_16x16x32_bf16 v[76:79], v[144:147], v[192:195], v[76:79]
	v_mfma_f32_16x16x32_bf16 v[128:131], v[140:143], v[172:175], v[128:131]
	v_mfma_f32_16x16x32_bf16 v[124:127], v[148:151], v[172:175], v[124:127]
	v_mfma_f32_16x16x32_bf16 v[112:115], v[140:143], v[180:183], v[112:115]
	v_mfma_f32_16x16x32_bf16 v[108:111], v[148:151], v[180:183], v[108:111]
	v_mfma_f32_16x16x32_bf16 v[96:99], v[140:143], v[188:191], v[96:99]
	v_mfma_f32_16x16x32_bf16 v[92:95], v[148:151], v[188:191], v[92:95]
	v_mfma_f32_16x16x32_bf16 v[80:83], v[140:143], v[208:211], v[80:83]
	v_mfma_f32_16x16x32_bf16 v[76:79], v[148:151], v[208:211], v[76:79]
	v_mfma_f32_16x16x32_bf16 v[120:123], v[152:155], v[168:171], v[120:123]
	v_mfma_f32_16x16x32_bf16 v[116:119], v[160:163], v[168:171], v[116:119]
	v_mfma_f32_16x16x32_bf16 v[104:107], v[152:155], v[176:179], v[104:107]
	v_mfma_f32_16x16x32_bf16 v[100:103], v[160:163], v[176:179], v[100:103]
	v_mfma_f32_16x16x32_bf16 v[88:91], v[152:155], v[184:187], v[88:91]
	v_mfma_f32_16x16x32_bf16 v[84:87], v[160:163], v[184:187], v[84:87]
	v_mfma_f32_16x16x32_bf16 v[72:75], v[152:155], v[192:195], v[72:75]
	v_mfma_f32_16x16x32_bf16 v[68:71], v[160:163], v[192:195], v[68:71]
	v_mfma_f32_16x16x32_bf16 v[120:123], v[156:159], v[172:175], v[120:123]
	v_mfma_f32_16x16x32_bf16 v[116:119], v[164:167], v[172:175], v[116:119]
	v_mfma_f32_16x16x32_bf16 v[104:107], v[156:159], v[180:183], v[104:107]
	v_mfma_f32_16x16x32_bf16 v[100:103], v[164:167], v[180:183], v[100:103]
	v_mfma_f32_16x16x32_bf16 v[88:91], v[156:159], v[188:191], v[88:91]
	v_mfma_f32_16x16x32_bf16 v[84:87], v[164:167], v[188:191], v[84:87]
	v_mfma_f32_16x16x32_bf16 v[72:75], v[156:159], v[208:211], v[72:75]
	v_mfma_f32_16x16x32_bf16 v[68:71], v[164:167], v[208:211], v[68:71]
	s_barrier
	s_add_i32 s10, s67, s2
	v_lshl_add_u64 v[212:213], s[4:5], 0, v[198:199]
	s_mov_b32 m0, s10
	ds_read_b128 v[168:171], v222 offset:16384
	ds_read_b128 v[172:175], v222 offset:17408
	ds_read_b128 v[176:179], v222 offset:18432
	ds_read_b128 v[180:183], v222 offset:19456
	ds_read_b128 v[184:187], v222 offset:20480
	ds_read_b128 v[188:191], v222 offset:21504
	ds_read_b128 v[192:195], v222 offset:22528
	ds_read_b128 v[208:211], v222 offset:23552
	global_load_lds_dwordx4 v[212:213], off
	s_add_i32 m0, s10, 0x2000
	s_add_u32 s10, s4, 0x80000
	v_lshl_add_u64 v[214:215], s[4:5], 0, v[202:203]
	s_addc_u32 s11, s5, 0
	s_add_i32 s12, s68, s2
	global_load_lds_dwordx4 v[214:215], off
	v_lshl_add_u64 v[2:3], s[10:11], 0, v[198:199]
	s_mov_b32 m0, s12
	v_lshl_add_u64 v[216:217], s[6:7], 0, v[196:197]
	global_load_lds_dwordx4 v[2:3], off
	v_lshl_add_u64 v[2:3], s[10:11], 0, v[202:203]
	s_add_i32 m0, s12, 0x2000
	v_lshl_add_u64 v[224:225], s[6:7], 0, v[200:201]
	global_load_lds_dwordx4 v[2:3], off
	s_mov_b32 m0, s27
	s_nop 0
	global_load_lds_dwordx4 v[216:217], off
	s_mov_b32 m0, s29
	s_nop 0
	global_load_lds_dwordx4 v[224:225], off
	s_waitcnt vmcnt(8)
	s_waitcnt lgkmcnt(0)
	s_barrier
	v_mfma_f32_16x16x32_bf16 v[64:67], v[136:139], v[168:171], v[64:67]
	v_mfma_f32_16x16x32_bf16 v[60:63], v[144:147], v[168:171], v[60:63]
	v_mfma_f32_16x16x32_bf16 v[48:51], v[136:139], v[176:179], v[48:51]
	v_mfma_f32_16x16x32_bf16 v[44:47], v[144:147], v[176:179], v[44:47]
	v_mfma_f32_16x16x32_bf16 v[32:35], v[136:139], v[184:187], v[32:35]
	v_mfma_f32_16x16x32_bf16 v[28:31], v[144:147], v[184:187], v[28:31]
	v_mfma_f32_16x16x32_bf16 v[16:19], v[136:139], v[192:195], v[16:19]
	v_mfma_f32_16x16x32_bf16 v[12:15], v[144:147], v[192:195], v[12:15]
	v_mfma_f32_16x16x32_bf16 v[64:67], v[140:143], v[172:175], v[64:67]
	v_mfma_f32_16x16x32_bf16 v[60:63], v[148:151], v[172:175], v[60:63]
	v_mfma_f32_16x16x32_bf16 v[48:51], v[140:143], v[180:183], v[48:51]
	v_mfma_f32_16x16x32_bf16 v[44:47], v[148:151], v[180:183], v[44:47]
	v_mfma_f32_16x16x32_bf16 v[32:35], v[140:143], v[188:191], v[32:35]
	v_mfma_f32_16x16x32_bf16 v[28:31], v[148:151], v[188:191], v[28:31]
	v_mfma_f32_16x16x32_bf16 v[16:19], v[140:143], v[208:211], v[16:19]
	v_mfma_f32_16x16x32_bf16 v[12:15], v[148:151], v[208:211], v[12:15]
	v_mfma_f32_16x16x32_bf16 v[56:59], v[152:155], v[168:171], v[56:59]
	v_mfma_f32_16x16x32_bf16 v[52:55], v[160:163], v[168:171], v[52:55]
	v_mfma_f32_16x16x32_bf16 v[40:43], v[152:155], v[176:179], v[40:43]
	v_mfma_f32_16x16x32_bf16 v[36:39], v[160:163], v[176:179], v[36:39]
	v_mfma_f32_16x16x32_bf16 v[24:27], v[152:155], v[184:187], v[24:27]
	v_mfma_f32_16x16x32_bf16 v[20:23], v[160:163], v[184:187], v[20:23]
	v_mfma_f32_16x16x32_bf16 v[8:11], v[152:155], v[192:195], v[8:11]
	v_mfma_f32_16x16x32_bf16 v[2:5], v[160:163], v[192:195], v[4:7]
	v_mfma_f32_16x16x32_bf16 v[56:59], v[156:159], v[172:175], v[56:59]
	v_mfma_f32_16x16x32_bf16 v[52:55], v[164:167], v[172:175], v[52:55]
	v_mfma_f32_16x16x32_bf16 v[40:43], v[156:159], v[180:183], v[40:43]
	v_mfma_f32_16x16x32_bf16 v[36:39], v[164:167], v[180:183], v[36:39]
	v_mfma_f32_16x16x32_bf16 v[24:27], v[156:159], v[188:191], v[24:27]
	v_mfma_f32_16x16x32_bf16 v[20:23], v[164:167], v[188:191], v[20:23]
	v_mfma_f32_16x16x32_bf16 v[8:11], v[156:159], v[208:211], v[8:11]
	v_mfma_f32_16x16x32_bf16 v[2:5], v[164:167], v[208:211], v[2:5]
	s_barrier
	s_add_i32 s10, 0, 0x18000
	v_add_u32_e32 v1, s10, v221
	s_add_i32 s11, 0, 0x1c000
	ds_read_b128 v[136:139], v1
	ds_read_b128 v[140:143], v1 offset:1024
	ds_read_b128 v[144:147], v1 offset:2048
	ds_read_b128 v[148:151], v1 offset:3072
	v_add_u32_e32 v1, s11, v221
	ds_read_b128 v[152:155], v1
	ds_read_b128 v[156:159], v1 offset:1024
	ds_read_b128 v[160:163], v1 offset:2048
	ds_read_b128 v[164:167], v1 offset:3072
	s_add_u32 s6, s6, 0x80000
	s_addc_u32 s7, s7, 0
	s_mov_b32 m0, s31
	v_lshl_add_u64 v[6:7], s[6:7], 0, v[196:197]
	ds_read_b128 v[168:171], v222 offset:32768
	ds_read_b128 v[172:175], v222 offset:33792
	ds_read_b128 v[176:179], v222 offset:34816
	ds_read_b128 v[180:183], v222 offset:35840
	ds_read_b128 v[184:187], v222 offset:36864
	ds_read_b128 v[188:191], v222 offset:37888
	ds_read_b128 v[192:195], v222 offset:38912
	ds_read_b128 v[208:211], v222 offset:39936
	global_load_lds_dwordx4 v[6:7], off
	v_lshl_add_u64 v[6:7], s[6:7], 0, v[200:201]
	s_mov_b32 m0, s33
	s_nop 0
	global_load_lds_dwordx4 v[6:7], off
	s_waitcnt vmcnt(8)
	s_waitcnt lgkmcnt(0)
	s_barrier
	v_mfma_f32_16x16x32_bf16 v[128:131], v[136:139], v[168:171], v[128:131]
	v_mfma_f32_16x16x32_bf16 v[124:127], v[144:147], v[168:171], v[124:127]
	v_mfma_f32_16x16x32_bf16 v[112:115], v[136:139], v[176:179], v[112:115]
	v_mfma_f32_16x16x32_bf16 v[108:111], v[144:147], v[176:179], v[108:111]
	v_mfma_f32_16x16x32_bf16 v[96:99], v[136:139], v[184:187], v[96:99]
	v_mfma_f32_16x16x32_bf16 v[92:95], v[144:147], v[184:187], v[92:95]
	v_mfma_f32_16x16x32_bf16 v[80:83], v[136:139], v[192:195], v[80:83]
	v_mfma_f32_16x16x32_bf16 v[76:79], v[144:147], v[192:195], v[76:79]
	v_mfma_f32_16x16x32_bf16 v[128:131], v[140:143], v[172:175], v[128:131]
	v_mfma_f32_16x16x32_bf16 v[124:127], v[148:151], v[172:175], v[124:127]
	v_mfma_f32_16x16x32_bf16 v[112:115], v[140:143], v[180:183], v[112:115]
	v_mfma_f32_16x16x32_bf16 v[108:111], v[148:151], v[180:183], v[108:111]
	v_mfma_f32_16x16x32_bf16 v[96:99], v[140:143], v[188:191], v[96:99]
	v_mfma_f32_16x16x32_bf16 v[92:95], v[148:151], v[188:191], v[92:95]
	v_mfma_f32_16x16x32_bf16 v[80:83], v[140:143], v[208:211], v[80:83]
	v_mfma_f32_16x16x32_bf16 v[76:79], v[148:151], v[208:211], v[76:79]
	v_mfma_f32_16x16x32_bf16 v[120:123], v[152:155], v[168:171], v[120:123]
	v_mfma_f32_16x16x32_bf16 v[116:119], v[160:163], v[168:171], v[116:119]
	v_mfma_f32_16x16x32_bf16 v[104:107], v[152:155], v[176:179], v[104:107]
	v_mfma_f32_16x16x32_bf16 v[100:103], v[160:163], v[176:179], v[100:103]
	v_mfma_f32_16x16x32_bf16 v[88:91], v[152:155], v[184:187], v[88:91]
	v_mfma_f32_16x16x32_bf16 v[84:87], v[160:163], v[184:187], v[84:87]
	v_mfma_f32_16x16x32_bf16 v[72:75], v[152:155], v[192:195], v[72:75]
	v_mfma_f32_16x16x32_bf16 v[68:71], v[160:163], v[192:195], v[68:71]
	v_mfma_f32_16x16x32_bf16 v[120:123], v[156:159], v[172:175], v[120:123]
	v_mfma_f32_16x16x32_bf16 v[116:119], v[164:167], v[172:175], v[116:119]
	v_mfma_f32_16x16x32_bf16 v[104:107], v[156:159], v[180:183], v[104:107]
	v_mfma_f32_16x16x32_bf16 v[100:103], v[164:167], v[180:183], v[100:103]
	v_mfma_f32_16x16x32_bf16 v[88:91], v[156:159], v[188:191], v[88:91]
	v_mfma_f32_16x16x32_bf16 v[84:87], v[164:167], v[188:191], v[84:87]
	v_mfma_f32_16x16x32_bf16 v[72:75], v[156:159], v[208:211], v[72:75]
	v_mfma_f32_16x16x32_bf16 v[68:71], v[164:167], v[208:211], v[68:71]
	s_barrier
	s_add_i32 s6, s10, s2
	v_lshl_add_u64 v[6:7], v[212:213], 0, s[18:19]
	s_mov_b32 m0, s6
	ds_read_b128 v[168:171], v222 offset:49152
	ds_read_b128 v[172:175], v222 offset:50176
	ds_read_b128 v[176:179], v222 offset:51200
	ds_read_b128 v[180:183], v222 offset:52224
	ds_read_b128 v[184:187], v222 offset:53248
	ds_read_b128 v[188:191], v222 offset:54272
	ds_read_b128 v[192:195], v222 offset:55296
	ds_read_b128 v[208:211], v222 offset:56320
	global_load_lds_dwordx4 v[6:7], off
	s_add_i32 m0, s6, 0x2000
	s_add_u32 s4, s4, 0x80080
	v_lshl_add_u64 v[6:7], v[214:215], 0, s[18:19]
	s_addc_u32 s5, s5, 0
	s_add_i32 s6, s11, s2
	global_load_lds_dwordx4 v[6:7], off
	v_lshl_add_u64 v[6:7], s[4:5], 0, v[198:199]
	s_mov_b32 m0, s6
	s_nop 0
	global_load_lds_dwordx4 v[6:7], off
	v_lshl_add_u64 v[6:7], s[4:5], 0, v[202:203]
	s_add_i32 m0, s6, 0x2000
	s_nop 0
	global_load_lds_dwordx4 v[6:7], off
	v_lshl_add_u64 v[6:7], v[216:217], 0, s[18:19]
	s_mov_b32 m0, s55
	s_nop 0
	global_load_lds_dwordx4 v[6:7], off
	v_lshl_add_u64 v[6:7], v[224:225], 0, s[18:19]
	s_mov_b32 m0, s65
	s_nop 0
	global_load_lds_dwordx4 v[6:7], off
	s_waitcnt vmcnt(8)
	s_waitcnt lgkmcnt(0)
	s_barrier
	v_mfma_f32_16x16x32_bf16 v[64:67], v[136:139], v[168:171], v[64:67]
	v_mfma_f32_16x16x32_bf16 v[60:63], v[144:147], v[168:171], v[60:63]
	v_mfma_f32_16x16x32_bf16 v[48:51], v[136:139], v[176:179], v[48:51]
	v_mfma_f32_16x16x32_bf16 v[44:47], v[144:147], v[176:179], v[44:47]
	v_mfma_f32_16x16x32_bf16 v[32:35], v[136:139], v[184:187], v[32:35]
	v_mfma_f32_16x16x32_bf16 v[28:31], v[144:147], v[184:187], v[28:31]
	v_mfma_f32_16x16x32_bf16 v[16:19], v[136:139], v[192:195], v[16:19]
	v_mfma_f32_16x16x32_bf16 v[12:15], v[144:147], v[192:195], v[12:15]
	v_mfma_f32_16x16x32_bf16 v[64:67], v[140:143], v[172:175], v[64:67]
	v_mfma_f32_16x16x32_bf16 v[60:63], v[148:151], v[172:175], v[60:63]
	v_mfma_f32_16x16x32_bf16 v[48:51], v[140:143], v[180:183], v[48:51]
	v_mfma_f32_16x16x32_bf16 v[44:47], v[148:151], v[180:183], v[44:47]
	v_mfma_f32_16x16x32_bf16 v[32:35], v[140:143], v[188:191], v[32:35]
	v_mfma_f32_16x16x32_bf16 v[28:31], v[148:151], v[188:191], v[28:31]
	v_mfma_f32_16x16x32_bf16 v[16:19], v[140:143], v[208:211], v[16:19]
	v_mfma_f32_16x16x32_bf16 v[12:15], v[148:151], v[208:211], v[12:15]
	v_mfma_f32_16x16x32_bf16 v[56:59], v[152:155], v[168:171], v[56:59]
	v_mfma_f32_16x16x32_bf16 v[52:55], v[160:163], v[168:171], v[52:55]
	v_mfma_f32_16x16x32_bf16 v[40:43], v[152:155], v[176:179], v[40:43]
	v_mfma_f32_16x16x32_bf16 v[36:39], v[160:163], v[176:179], v[36:39]
	v_mfma_f32_16x16x32_bf16 v[24:27], v[152:155], v[184:187], v[24:27]
	v_mfma_f32_16x16x32_bf16 v[20:23], v[160:163], v[184:187], v[20:23]
	v_mfma_f32_16x16x32_bf16 v[6:9], v[152:155], v[192:195], v[8:11]
	v_mfma_f32_16x16x32_bf16 v[2:5], v[160:163], v[192:195], v[2:5]
	v_mfma_f32_16x16x32_bf16 v[56:59], v[156:159], v[172:175], v[56:59]
	v_mfma_f32_16x16x32_bf16 v[52:55], v[164:167], v[172:175], v[52:55]
	v_mfma_f32_16x16x32_bf16 v[40:43], v[156:159], v[180:183], v[40:43]
	v_mfma_f32_16x16x32_bf16 v[36:39], v[164:167], v[180:183], v[36:39]
	v_mfma_f32_16x16x32_bf16 v[24:27], v[156:159], v[188:191], v[24:27]
	v_mfma_f32_16x16x32_bf16 v[20:23], v[164:167], v[188:191], v[20:23]
	v_mfma_f32_16x16x32_bf16 v[8:11], v[156:159], v[208:211], v[6:9]
	v_mfma_f32_16x16x32_bf16 v[4:7], v[164:167], v[208:211], v[2:5]
	s_barrier
	s_add_i32 s42, s42, 2
	s_add_u32 s52, s52, 0x100
	s_addc_u32 s53, s53, 0
	s_cmp_gt_u32 s42, 29
	s_cbranch_scc1 .LBB0_623

.LBB0_801:
	v_add_u32_e32 v143, s36, v141
	ds_read_b128 v[144:147], v143
	ds_read_b128 v[148:151], v143 offset:1024
	ds_read_b128 v[152:155], v143 offset:2048
	ds_read_b128 v[156:159], v143 offset:3072
	v_add_u32_e32 v143, s37, v141
	s_add_u32 s22, s18, s20
	ds_read_b128 v[160:163], v143
	ds_read_b128 v[164:167], v143 offset:1024
	ds_read_b128 v[168:171], v143 offset:2048
	ds_read_b128 v[172:175], v143 offset:3072
	s_addc_u32 s23, s19, s21
	s_add_u32 s22, s22, 0x19800100
	s_addc_u32 s23, s23, 0
	s_add_u32 s45, s34, s20
	s_addc_u32 s54, s35, s21
	s_cmpk_eq_i32 s20, 0xf00
	s_cselect_b32 s25, s5, s23
	s_cselect_b32 s24, s4, s22
	s_cselect_b32 s23, s7, s54
	s_cselect_b32 s22, s6, s45
	s_mov_b32 m0, s38
	v_lshl_add_u64 v[208:209], v[136:137], 0, s[20:21]
	ds_read_b128 v[176:179], v142
	ds_read_b128 v[180:183], v142 offset:1024
	ds_read_b128 v[184:187], v142 offset:2048
	ds_read_b128 v[188:191], v142 offset:3072
	ds_read_b128 v[192:195], v142 offset:4096
	ds_read_b128 v[196:199], v142 offset:5120
	ds_read_b128 v[200:203], v142 offset:6144
	ds_read_b128 v[204:207], v142 offset:7168
	global_load_lds_dwordx4 v[208:209], off
	v_lshl_add_u64 v[208:209], v[138:139], 0, s[20:21]
	s_mov_b32 m0, s39
	s_nop 0
	global_load_lds_dwordx4 v[208:209], off
	s_waitcnt vmcnt(8)
	s_waitcnt lgkmcnt(0)
	s_barrier
	v_mfma_f32_16x16x32_bf16 v[124:127], v[144:147], v[176:179], v[124:127]
	v_mfma_f32_16x16x32_bf16 v[120:123], v[152:155], v[176:179], v[120:123]
	v_mfma_f32_16x16x32_bf16 v[108:111], v[144:147], v[184:187], v[108:111]
	v_mfma_f32_16x16x32_bf16 v[104:107], v[152:155], v[184:187], v[104:107]
	v_mfma_f32_16x16x32_bf16 v[92:95], v[144:147], v[192:195], v[92:95]
	v_mfma_f32_16x16x32_bf16 v[88:91], v[152:155], v[192:195], v[88:91]
	v_mfma_f32_16x16x32_bf16 v[80:83], v[144:147], v[200:203], v[80:83]
	v_mfma_f32_16x16x32_bf16 v[72:75], v[152:155], v[200:203], v[72:75]
	v_mfma_f32_16x16x32_bf16 v[124:127], v[148:151], v[180:183], v[124:127]
	v_mfma_f32_16x16x32_bf16 v[120:123], v[156:159], v[180:183], v[120:123]
	v_mfma_f32_16x16x32_bf16 v[108:111], v[148:151], v[188:191], v[108:111]
	v_mfma_f32_16x16x32_bf16 v[104:107], v[156:159], v[188:191], v[104:107]
	v_mfma_f32_16x16x32_bf16 v[92:95], v[148:151], v[196:199], v[92:95]
	v_mfma_f32_16x16x32_bf16 v[88:91], v[156:159], v[196:199], v[88:91]
	v_mfma_f32_16x16x32_bf16 v[80:83], v[148:151], v[204:207], v[80:83]
	v_mfma_f32_16x16x32_bf16 v[72:75], v[156:159], v[204:207], v[72:75]
	v_mfma_f32_16x16x32_bf16 v[116:119], v[160:163], v[176:179], v[116:119]
	v_mfma_f32_16x16x32_bf16 v[112:115], v[168:171], v[176:179], v[112:115]
	v_mfma_f32_16x16x32_bf16 v[100:103], v[160:163], v[184:187], v[100:103]
	v_mfma_f32_16x16x32_bf16 v[96:99], v[168:171], v[184:187], v[96:99]
	v_mfma_f32_16x16x32_bf16 v[84:87], v[160:163], v[192:195], v[84:87]
	v_mfma_f32_16x16x32_bf16 v[76:79], v[168:171], v[192:195], v[76:79]
	v_mfma_f32_16x16x32_bf16 v[68:71], v[160:163], v[200:203], v[68:71]
	v_mfma_f32_16x16x32_bf16 v[64:67], v[168:171], v[200:203], v[64:67]
	v_mfma_f32_16x16x32_bf16 v[116:119], v[164:167], v[180:183], v[116:119]
	v_mfma_f32_16x16x32_bf16 v[112:115], v[172:175], v[180:183], v[112:115]
	v_mfma_f32_16x16x32_bf16 v[100:103], v[164:167], v[188:191], v[100:103]
	v_mfma_f32_16x16x32_bf16 v[96:99], v[172:175], v[188:191], v[96:99]
	v_mfma_f32_16x16x32_bf16 v[84:87], v[164:167], v[196:199], v[84:87]
	v_mfma_f32_16x16x32_bf16 v[76:79], v[172:175], v[196:199], v[76:79]
	v_mfma_f32_16x16x32_bf16 v[68:71], v[164:167], v[204:207], v[68:71]
	v_mfma_f32_16x16x32_bf16 v[64:67], v[172:175], v[204:207], v[64:67]
	s_barrier
	s_mov_b32 m0, s40
	v_lshl_add_u64 v[208:209], s[22:23], 0, v[132:133]
	s_add_u32 s54, s22, 0x80000
	ds_read_b128 v[176:179], v142 offset:16384
	ds_read_b128 v[180:183], v142 offset:17408
	ds_read_b128 v[184:187], v142 offset:18432
	ds_read_b128 v[188:191], v142 offset:19456
	ds_read_b128 v[192:195], v142 offset:20480
	ds_read_b128 v[196:199], v142 offset:21504
	ds_read_b128 v[200:203], v142 offset:22528
	ds_read_b128 v[204:207], v142 offset:23552
	global_load_lds_dwordx4 v[208:209], off
	v_lshl_add_u64 v[210:211], s[22:23], 0, v[128:129]
	s_mov_b32 m0, s41
	s_addc_u32 s55, s23, 0
	global_load_lds_dwordx4 v[210:211], off
	v_lshl_add_u64 v[212:213], s[54:55], 0, v[132:133]
	s_mov_b32 m0, s46
	v_lshl_add_u64 v[214:215], s[24:25], 0, v[130:131]
	global_load_lds_dwordx4 v[212:213], off
	v_lshl_add_u64 v[212:213], s[54:55], 0, v[128:129]
	s_mov_b32 m0, s47
	s_nop 0
	global_load_lds_dwordx4 v[212:213], off
	v_lshl_add_u64 v[212:213], s[24:25], 0, v[134:135]
	s_mov_b32 m0, s3
	s_nop 0
	global_load_lds_dwordx4 v[212:213], off
	s_mov_b32 m0, s27
	s_nop 0
	global_load_lds_dwordx4 v[214:215], off
	s_waitcnt vmcnt(8)
	s_waitcnt lgkmcnt(0)
	s_barrier
	v_mfma_f32_16x16x32_bf16 v[60:63], v[144:147], v[176:179], v[60:63]
	v_mfma_f32_16x16x32_bf16 v[56:59], v[152:155], v[176:179], v[56:59]
	v_mfma_f32_16x16x32_bf16 v[48:51], v[144:147], v[184:187], v[48:51]
	v_mfma_f32_16x16x32_bf16 v[40:43], v[152:155], v[184:187], v[40:43]
	v_mfma_f32_16x16x32_bf16 v[28:31], v[144:147], v[192:195], v[28:31]
	v_mfma_f32_16x16x32_bf16 v[24:27], v[152:155], v[192:195], v[24:27]
	v_mfma_f32_16x16x32_bf16 v[16:19], v[144:147], v[200:203], v[16:19]
	v_mfma_f32_16x16x32_bf16 v[8:11], v[152:155], v[200:203], v[8:11]
	v_mfma_f32_16x16x32_bf16 v[60:63], v[148:151], v[180:183], v[60:63]
	v_mfma_f32_16x16x32_bf16 v[56:59], v[156:159], v[180:183], v[56:59]
	v_mfma_f32_16x16x32_bf16 v[48:51], v[148:151], v[188:191], v[48:51]
	v_mfma_f32_16x16x32_bf16 v[40:43], v[156:159], v[188:191], v[40:43]
	v_mfma_f32_16x16x32_bf16 v[28:31], v[148:151], v[196:199], v[28:31]
	v_mfma_f32_16x16x32_bf16 v[24:27], v[156:159], v[196:199], v[24:27]
	v_mfma_f32_16x16x32_bf16 v[16:19], v[148:151], v[204:207], v[16:19]
	v_mfma_f32_16x16x32_bf16 v[8:11], v[156:159], v[204:207], v[8:11]
	v_mfma_f32_16x16x32_bf16 v[52:55], v[160:163], v[176:179], v[52:55]
	v_mfma_f32_16x16x32_bf16 v[44:47], v[168:171], v[176:179], v[44:47]
	v_mfma_f32_16x16x32_bf16 v[36:39], v[160:163], v[184:187], v[36:39]
	v_mfma_f32_16x16x32_bf16 v[32:35], v[168:171], v[184:187], v[32:35]
	v_mfma_f32_16x16x32_bf16 v[20:23], v[160:163], v[192:195], v[20:23]
	v_mfma_f32_16x16x32_bf16 v[12:15], v[168:171], v[192:195], v[12:15]
	v_mfma_f32_16x16x32_bf16 v[4:7], v[160:163], v[200:203], v[4:7]
	v_mfma_f32_16x16x32_bf16 v[0:3], v[168:171], v[200:203], v[0:3]
	v_mfma_f32_16x16x32_bf16 v[52:55], v[164:167], v[180:183], v[52:55]
	v_mfma_f32_16x16x32_bf16 v[44:47], v[172:175], v[180:183], v[44:47]
	v_mfma_f32_16x16x32_bf16 v[36:39], v[164:167], v[188:191], v[36:39]
	v_mfma_f32_16x16x32_bf16 v[32:35], v[172:175], v[188:191], v[32:35]
	v_mfma_f32_16x16x32_bf16 v[20:23], v[164:167], v[196:199], v[20:23]
	v_mfma_f32_16x16x32_bf16 v[12:15], v[172:175], v[196:199], v[12:15]
	v_mfma_f32_16x16x32_bf16 v[4:7], v[164:167], v[204:207], v[4:7]
	v_mfma_f32_16x16x32_bf16 v[0:3], v[172:175], v[204:207], v[0:3]
	s_barrier
	v_add_u32_e32 v143, s48, v141
	ds_read_b128 v[144:147], v143
	ds_read_b128 v[148:151], v143 offset:1024
	ds_read_b128 v[152:155], v143 offset:2048
	ds_read_b128 v[156:159], v143 offset:3072
	v_add_u32_e32 v143, s49, v141
	ds_read_b128 v[160:163], v143
	ds_read_b128 v[164:167], v143 offset:1024
	ds_read_b128 v[168:171], v143 offset:2048
	ds_read_b128 v[172:175], v143 offset:3072
	s_add_u32 s24, s24, 0x80000
	s_addc_u32 s25, s25, 0
	s_mov_b32 m0, s28
	v_lshl_add_u64 v[216:217], s[24:25], 0, v[134:135]
	ds_read_b128 v[176:179], v142 offset:32768
	ds_read_b128 v[180:183], v142 offset:33792
	ds_read_b128 v[184:187], v142 offset:34816
	ds_read_b128 v[188:191], v142 offset:35840
	ds_read_b128 v[192:195], v142 offset:36864
	ds_read_b128 v[196:199], v142 offset:37888
	ds_read_b128 v[200:203], v142 offset:38912
	ds_read_b128 v[204:207], v142 offset:39936
	global_load_lds_dwordx4 v[216:217], off
	v_lshl_add_u64 v[216:217], s[24:25], 0, v[130:131]
	s_mov_b32 m0, s29
	s_nop 0
	global_load_lds_dwordx4 v[216:217], off
	s_waitcnt vmcnt(8)
	s_waitcnt lgkmcnt(0)
	s_barrier
	v_mfma_f32_16x16x32_bf16 v[124:127], v[144:147], v[176:179], v[124:127]
	v_mfma_f32_16x16x32_bf16 v[120:123], v[152:155], v[176:179], v[120:123]
	v_mfma_f32_16x16x32_bf16 v[108:111], v[144:147], v[184:187], v[108:111]
	v_mfma_f32_16x16x32_bf16 v[104:107], v[152:155], v[184:187], v[104:107]
	v_mfma_f32_16x16x32_bf16 v[92:95], v[144:147], v[192:195], v[92:95]
	v_mfma_f32_16x16x32_bf16 v[88:91], v[152:155], v[192:195], v[88:91]
	v_mfma_f32_16x16x32_bf16 v[80:83], v[144:147], v[200:203], v[80:83]
	v_mfma_f32_16x16x32_bf16 v[72:75], v[152:155], v[200:203], v[72:75]
	v_mfma_f32_16x16x32_bf16 v[124:127], v[148:151], v[180:183], v[124:127]
	v_mfma_f32_16x16x32_bf16 v[120:123], v[156:159], v[180:183], v[120:123]
	v_mfma_f32_16x16x32_bf16 v[108:111], v[148:151], v[188:191], v[108:111]
	v_mfma_f32_16x16x32_bf16 v[104:107], v[156:159], v[188:191], v[104:107]
	v_mfma_f32_16x16x32_bf16 v[92:95], v[148:151], v[196:199], v[92:95]
	v_mfma_f32_16x16x32_bf16 v[88:91], v[156:159], v[196:199], v[88:91]
	v_mfma_f32_16x16x32_bf16 v[80:83], v[148:151], v[204:207], v[80:83]
	v_mfma_f32_16x16x32_bf16 v[72:75], v[156:159], v[204:207], v[72:75]
	v_mfma_f32_16x16x32_bf16 v[116:119], v[160:163], v[176:179], v[116:119]
	v_mfma_f32_16x16x32_bf16 v[112:115], v[168:171], v[176:179], v[112:115]
	v_mfma_f32_16x16x32_bf16 v[100:103], v[160:163], v[184:187], v[100:103]
	v_mfma_f32_16x16x32_bf16 v[96:99], v[168:171], v[184:187], v[96:99]
	v_mfma_f32_16x16x32_bf16 v[84:87], v[160:163], v[192:195], v[84:87]
	v_mfma_f32_16x16x32_bf16 v[76:79], v[168:171], v[192:195], v[76:79]
	v_mfma_f32_16x16x32_bf16 v[68:71], v[160:163], v[200:203], v[68:71]
	v_mfma_f32_16x16x32_bf16 v[64:67], v[168:171], v[200:203], v[64:67]
	v_mfma_f32_16x16x32_bf16 v[116:119], v[164:167], v[180:183], v[116:119]
	v_mfma_f32_16x16x32_bf16 v[112:115], v[172:175], v[180:183], v[112:115]
	v_mfma_f32_16x16x32_bf16 v[100:103], v[164:167], v[188:191], v[100:103]
	v_mfma_f32_16x16x32_bf16 v[96:99], v[172:175], v[188:191], v[96:99]
	v_mfma_f32_16x16x32_bf16 v[84:87], v[164:167], v[196:199], v[84:87]
	v_mfma_f32_16x16x32_bf16 v[76:79], v[172:175], v[196:199], v[76:79]
	v_mfma_f32_16x16x32_bf16 v[68:71], v[164:167], v[204:207], v[68:71]
	v_mfma_f32_16x16x32_bf16 v[64:67], v[172:175], v[204:207], v[64:67]
	s_barrier
	s_mov_b32 m0, s50
	v_lshl_add_u64 v[208:209], v[208:209], 0, s[14:15]
	s_add_u32 s22, s22, 0x80080
	ds_read_b128 v[176:179], v142 offset:49152
	ds_read_b128 v[180:183], v142 offset:50176
	ds_read_b128 v[184:187], v142 offset:51200
	ds_read_b128 v[188:191], v142 offset:52224
	ds_read_b128 v[192:195], v142 offset:53248
	ds_read_b128 v[196:199], v142 offset:54272
	ds_read_b128 v[200:203], v142 offset:55296
	ds_read_b128 v[204:207], v142 offset:56320
	global_load_lds_dwordx4 v[208:209], off
	v_lshl_add_u64 v[208:209], v[210:211], 0, s[14:15]
	s_mov_b32 m0, s51
	s_addc_u32 s23, s23, 0
	global_load_lds_dwordx4 v[208:209], off
	v_lshl_add_u64 v[208:209], s[22:23], 0, v[132:133]
	s_mov_b32 m0, s52
	s_nop 0
	global_load_lds_dwordx4 v[208:209], off
	v_lshl_add_u64 v[208:209], s[22:23], 0, v[128:129]
	s_mov_b32 m0, s53
	s_nop 0
	global_load_lds_dwordx4 v[208:209], off
	v_lshl_add_u64 v[208:209], v[212:213], 0, s[14:15]
	s_mov_b32 m0, s31
	s_nop 0
	global_load_lds_dwordx4 v[208:209], off
	v_lshl_add_u64 v[208:209], v[214:215], 0, s[14:15]
	s_mov_b32 m0, s33
	s_nop 0
	global_load_lds_dwordx4 v[208:209], off
	s_waitcnt vmcnt(8)
	s_waitcnt lgkmcnt(0)
	s_barrier
	v_mfma_f32_16x16x32_bf16 v[60:63], v[144:147], v[176:179], v[60:63]
	v_mfma_f32_16x16x32_bf16 v[56:59], v[152:155], v[176:179], v[56:59]
	v_mfma_f32_16x16x32_bf16 v[48:51], v[144:147], v[184:187], v[48:51]
	v_mfma_f32_16x16x32_bf16 v[40:43], v[152:155], v[184:187], v[40:43]
	v_mfma_f32_16x16x32_bf16 v[28:31], v[144:147], v[192:195], v[28:31]
	v_mfma_f32_16x16x32_bf16 v[24:27], v[152:155], v[192:195], v[24:27]
	v_mfma_f32_16x16x32_bf16 v[16:19], v[144:147], v[200:203], v[16:19]
	v_mfma_f32_16x16x32_bf16 v[8:11], v[152:155], v[200:203], v[8:11]
	v_mfma_f32_16x16x32_bf16 v[60:63], v[148:151], v[180:183], v[60:63]
	v_mfma_f32_16x16x32_bf16 v[56:59], v[156:159], v[180:183], v[56:59]
	v_mfma_f32_16x16x32_bf16 v[48:51], v[148:151], v[188:191], v[48:51]
	v_mfma_f32_16x16x32_bf16 v[40:43], v[156:159], v[188:191], v[40:43]
	v_mfma_f32_16x16x32_bf16 v[28:31], v[148:151], v[196:199], v[28:31]
	v_mfma_f32_16x16x32_bf16 v[24:27], v[156:159], v[196:199], v[24:27]
	v_mfma_f32_16x16x32_bf16 v[16:19], v[148:151], v[204:207], v[16:19]
	v_mfma_f32_16x16x32_bf16 v[8:11], v[156:159], v[204:207], v[8:11]
	v_mfma_f32_16x16x32_bf16 v[52:55], v[160:163], v[176:179], v[52:55]
	v_mfma_f32_16x16x32_bf16 v[44:47], v[168:171], v[176:179], v[44:47]
	v_mfma_f32_16x16x32_bf16 v[36:39], v[160:163], v[184:187], v[36:39]
	v_mfma_f32_16x16x32_bf16 v[32:35], v[168:171], v[184:187], v[32:35]
	v_mfma_f32_16x16x32_bf16 v[20:23], v[160:163], v[192:195], v[20:23]
	v_mfma_f32_16x16x32_bf16 v[12:15], v[168:171], v[192:195], v[12:15]
	v_mfma_f32_16x16x32_bf16 v[4:7], v[160:163], v[200:203], v[4:7]
	v_mfma_f32_16x16x32_bf16 v[0:3], v[168:171], v[200:203], v[0:3]
	v_mfma_f32_16x16x32_bf16 v[52:55], v[164:167], v[180:183], v[52:55]
	v_mfma_f32_16x16x32_bf16 v[44:47], v[172:175], v[180:183], v[44:47]
	v_mfma_f32_16x16x32_bf16 v[36:39], v[164:167], v[188:191], v[36:39]
	v_mfma_f32_16x16x32_bf16 v[32:35], v[172:175], v[188:191], v[32:35]
	v_mfma_f32_16x16x32_bf16 v[20:23], v[164:167], v[196:199], v[20:23]
	v_mfma_f32_16x16x32_bf16 v[12:15], v[172:175], v[196:199], v[12:15]
	v_mfma_f32_16x16x32_bf16 v[4:7], v[164:167], v[204:207], v[4:7]
	v_mfma_f32_16x16x32_bf16 v[0:3], v[172:175], v[204:207], v[0:3]
	s_barrier
	s_add_i32 s44, s44, 2
	s_add_u32 s20, s20, 0x100
	s_addc_u32 s21, s21, 0
	s_cmp_gt_u32 s44, 29
	s_cbranch_scc0 .LBB0_801
	s_and_b64 vcc, exec, s[16:17]
	s_cbranch_vccz .LBB0_804
	s_barrier
	s_cmp_gt_i32 s43, 0
	s_cselect_b64 s[20:21], -1, 0
	s_and_b64 vcc, exec, s[20:21]
	s_cbranch_vccnz .LBB0_799
	s_branch .LBB0_805

.LBB0_913:
	ds_read_b128 v[128:131], v184
	ds_read_b128 v[132:135], v184 offset:1024
	ds_read_b128 v[136:139], v184 offset:2048
	ds_read_b128 v[140:143], v184 offset:3072
	ds_read_b128 v[144:147], v185
	ds_read_b128 v[148:151], v185 offset:1024
	ds_read_b128 v[164:167], v185 offset:2048
	ds_read_b128 v[168:171], v185 offset:3072
	s_add_u32 s26, s4, 0xfffc0080
	s_addc_u32 s27, s5, -1
	s_cmp_eq_u32 s42, 12
	s_cselect_b32 s29, s23, s27
	s_cselect_b32 s28, s22, s26
	s_cselect_b32 s27, s25, s21
	s_cselect_b32 s26, s24, s1
	s_mov_b32 m0, s46
	v_lshl_add_u64 v[180:181], s[4:5], 0, v[160:161]
	ds_read_b128 v[172:175], v186
	ds_read_b128 v[176:179], v186 offset:1024
	ds_read_b128 v[188:191], v186 offset:2048
	ds_read_b128 v[192:195], v186 offset:3072
	ds_read_b128 v[196:199], v186 offset:4096
	ds_read_b128 v[200:203], v186 offset:5120
	ds_read_b128 v[204:207], v186 offset:6144
	ds_read_b128 v[208:211], v186 offset:7168
	global_load_lds_dwordx4 v[180:181], off
	v_lshl_add_u64 v[180:181], s[4:5], 0, v[162:163]
	s_add_i32 m0, s30, 0xe000
	s_nop 0
	global_load_lds_dwordx4 v[180:181], off
	s_waitcnt vmcnt(8)
	s_waitcnt lgkmcnt(0)
	s_barrier
	v_mfma_f32_16x16x32_bf16 v[124:127], v[128:131], v[172:175], v[124:127]
	v_mfma_f32_16x16x32_bf16 v[120:123], v[136:139], v[172:175], v[120:123]
	v_mfma_f32_16x16x32_bf16 v[108:111], v[128:131], v[188:191], v[108:111]
	v_mfma_f32_16x16x32_bf16 v[104:107], v[136:139], v[188:191], v[104:107]
	v_mfma_f32_16x16x32_bf16 v[92:95], v[128:131], v[196:199], v[92:95]
	v_mfma_f32_16x16x32_bf16 v[88:91], v[136:139], v[196:199], v[88:91]
	v_mfma_f32_16x16x32_bf16 v[76:79], v[128:131], v[204:207], v[76:79]
	v_mfma_f32_16x16x32_bf16 v[72:75], v[136:139], v[204:207], v[72:75]
	v_mfma_f32_16x16x32_bf16 v[124:127], v[132:135], v[176:179], v[124:127]
	v_mfma_f32_16x16x32_bf16 v[120:123], v[140:143], v[176:179], v[120:123]
	v_mfma_f32_16x16x32_bf16 v[108:111], v[132:135], v[192:195], v[108:111]
	v_mfma_f32_16x16x32_bf16 v[104:107], v[140:143], v[192:195], v[104:107]
	v_mfma_f32_16x16x32_bf16 v[92:95], v[132:135], v[200:203], v[92:95]
	v_mfma_f32_16x16x32_bf16 v[88:91], v[140:143], v[200:203], v[88:91]
	v_mfma_f32_16x16x32_bf16 v[76:79], v[132:135], v[208:211], v[76:79]
	v_mfma_f32_16x16x32_bf16 v[72:75], v[140:143], v[208:211], v[72:75]
	v_mfma_f32_16x16x32_bf16 v[116:119], v[144:147], v[172:175], v[116:119]
	v_mfma_f32_16x16x32_bf16 v[112:115], v[164:167], v[172:175], v[112:115]
	v_mfma_f32_16x16x32_bf16 v[100:103], v[144:147], v[188:191], v[100:103]
	v_mfma_f32_16x16x32_bf16 v[96:99], v[164:167], v[188:191], v[96:99]
	v_mfma_f32_16x16x32_bf16 v[84:87], v[144:147], v[196:199], v[84:87]
	v_mfma_f32_16x16x32_bf16 v[80:83], v[164:167], v[196:199], v[80:83]
	v_mfma_f32_16x16x32_bf16 v[68:71], v[144:147], v[204:207], v[68:71]
	v_mfma_f32_16x16x32_bf16 v[64:67], v[164:167], v[204:207], v[64:67]
	v_mfma_f32_16x16x32_bf16 v[116:119], v[148:151], v[176:179], v[116:119]
	v_mfma_f32_16x16x32_bf16 v[112:115], v[168:171], v[176:179], v[112:115]
	v_mfma_f32_16x16x32_bf16 v[100:103], v[148:151], v[192:195], v[100:103]
	v_mfma_f32_16x16x32_bf16 v[96:99], v[168:171], v[192:195], v[96:99]
	v_mfma_f32_16x16x32_bf16 v[84:87], v[148:151], v[200:203], v[84:87]
	v_mfma_f32_16x16x32_bf16 v[80:83], v[168:171], v[200:203], v[80:83]
	v_mfma_f32_16x16x32_bf16 v[68:71], v[148:151], v[208:211], v[68:71]
	v_mfma_f32_16x16x32_bf16 v[64:67], v[168:171], v[208:211], v[64:67]
	s_barrier
	s_add_i32 s43, s40, s2
	v_lshl_add_u64 v[180:181], s[26:27], 0, v[154:155]
	s_mov_b32 m0, s43
	ds_read_b128 v[172:175], v186 offset:16384
	ds_read_b128 v[176:179], v186 offset:17408
	ds_read_b128 v[188:191], v186 offset:18432
	ds_read_b128 v[192:195], v186 offset:19456
	ds_read_b128 v[196:199], v186 offset:20480
	ds_read_b128 v[200:203], v186 offset:21504
	ds_read_b128 v[204:207], v186 offset:22528
	ds_read_b128 v[208:211], v186 offset:23552
	global_load_lds_dwordx4 v[180:181], off
	s_add_i32 m0, s43, 0x2000
	s_add_u32 s44, s26, 0x40000
	v_lshl_add_u64 v[212:213], s[26:27], 0, v[158:159]
	s_addc_u32 s45, s27, 0
	s_add_i32 s43, s41, s2
	global_load_lds_dwordx4 v[212:213], off
	v_lshl_add_u64 v[214:215], s[44:45], 0, v[154:155]
	s_mov_b32 m0, s43
	v_lshl_add_u64 v[216:217], s[28:29], 0, v[156:157]
	global_load_lds_dwordx4 v[214:215], off
	v_lshl_add_u64 v[214:215], s[44:45], 0, v[158:159]
	s_add_i32 m0, s43, 0x2000
	s_nop 0
	global_load_lds_dwordx4 v[214:215], off
	v_lshl_add_u64 v[214:215], s[28:29], 0, v[152:153]
	s_mov_b32 m0, s30
	s_nop 0
	global_load_lds_dwordx4 v[214:215], off
	s_mov_b32 m0, s31
	s_nop 0
	global_load_lds_dwordx4 v[216:217], off
	s_waitcnt vmcnt(8)
	s_waitcnt lgkmcnt(0)
	s_barrier
	v_mfma_f32_16x16x32_bf16 v[60:63], v[128:131], v[172:175], v[60:63]
	v_mfma_f32_16x16x32_bf16 v[56:59], v[136:139], v[172:175], v[56:59]
	v_mfma_f32_16x16x32_bf16 v[44:47], v[128:131], v[188:191], v[44:47]
	v_mfma_f32_16x16x32_bf16 v[40:43], v[136:139], v[188:191], v[40:43]
	v_mfma_f32_16x16x32_bf16 v[28:31], v[128:131], v[196:199], v[28:31]
	v_mfma_f32_16x16x32_bf16 v[24:27], v[136:139], v[196:199], v[24:27]
	v_mfma_f32_16x16x32_bf16 v[12:15], v[128:131], v[204:207], v[12:15]
	v_mfma_f32_16x16x32_bf16 v[8:11], v[136:139], v[204:207], v[8:11]
	v_mfma_f32_16x16x32_bf16 v[60:63], v[132:135], v[176:179], v[60:63]
	v_mfma_f32_16x16x32_bf16 v[56:59], v[140:143], v[176:179], v[56:59]
	v_mfma_f32_16x16x32_bf16 v[44:47], v[132:135], v[192:195], v[44:47]
	v_mfma_f32_16x16x32_bf16 v[40:43], v[140:143], v[192:195], v[40:43]
	v_mfma_f32_16x16x32_bf16 v[28:31], v[132:135], v[200:203], v[28:31]
	v_mfma_f32_16x16x32_bf16 v[24:27], v[140:143], v[200:203], v[24:27]
	v_mfma_f32_16x16x32_bf16 v[12:15], v[132:135], v[208:211], v[12:15]
	v_mfma_f32_16x16x32_bf16 v[8:11], v[140:143], v[208:211], v[8:11]
	v_mfma_f32_16x16x32_bf16 v[52:55], v[144:147], v[172:175], v[52:55]
	v_mfma_f32_16x16x32_bf16 v[48:51], v[164:167], v[172:175], v[48:51]
	v_mfma_f32_16x16x32_bf16 v[36:39], v[144:147], v[188:191], v[36:39]
	v_mfma_f32_16x16x32_bf16 v[32:35], v[164:167], v[188:191], v[32:35]
	v_mfma_f32_16x16x32_bf16 v[20:23], v[144:147], v[196:199], v[20:23]
	v_mfma_f32_16x16x32_bf16 v[16:19], v[164:167], v[196:199], v[16:19]
	v_mfma_f32_16x16x32_bf16 v[4:7], v[144:147], v[204:207], v[4:7]
	v_mfma_f32_16x16x32_bf16 v[0:3], v[164:167], v[204:207], v[0:3]
	v_mfma_f32_16x16x32_bf16 v[52:55], v[148:151], v[176:179], v[52:55]
	v_mfma_f32_16x16x32_bf16 v[48:51], v[168:171], v[176:179], v[48:51]
	v_mfma_f32_16x16x32_bf16 v[36:39], v[148:151], v[192:195], v[36:39]
	v_mfma_f32_16x16x32_bf16 v[32:35], v[168:171], v[192:195], v[32:35]
	v_mfma_f32_16x16x32_bf16 v[20:23], v[148:151], v[200:203], v[20:23]
	v_mfma_f32_16x16x32_bf16 v[16:19], v[168:171], v[200:203], v[16:19]
	v_mfma_f32_16x16x32_bf16 v[4:7], v[148:151], v[208:211], v[4:7]
	v_mfma_f32_16x16x32_bf16 v[0:3], v[168:171], v[208:211], v[0:3]
	s_barrier
	s_add_i32 s43, 0, 0x18000
	s_add_i32 s44, 0, 0x1c000
	v_add_u32_e32 v140, s43, v183
	v_add_u32_e32 v168, s44, v183
	ds_read_b128 v[128:131], v140
	ds_read_b128 v[132:135], v140 offset:1024
	ds_read_b128 v[136:139], v140 offset:2048
	ds_read_b128 v[140:143], v140 offset:3072
	ds_read_b128 v[144:147], v168
	ds_read_b128 v[148:151], v168 offset:1024
	ds_read_b128 v[164:167], v168 offset:2048
	ds_read_b128 v[168:171], v168 offset:3072
	s_add_u32 s28, s28, 0x40000
	s_addc_u32 s29, s29, 0
	s_mov_b32 m0, s33
	v_lshl_add_u64 v[220:221], s[28:29], 0, v[152:153]
	ds_read_b128 v[172:175], v186 offset:32768
	ds_read_b128 v[176:179], v186 offset:33792
	ds_read_b128 v[188:191], v186 offset:34816
	ds_read_b128 v[192:195], v186 offset:35840
	ds_read_b128 v[196:199], v186 offset:36864
	ds_read_b128 v[200:203], v186 offset:37888
	ds_read_b128 v[204:207], v186 offset:38912
	ds_read_b128 v[208:211], v186 offset:39936
	global_load_lds_dwordx4 v[220:221], off
	v_lshl_add_u64 v[220:221], s[28:29], 0, v[156:157]
	s_mov_b32 m0, s34
	s_nop 0
	global_load_lds_dwordx4 v[220:221], off
	s_waitcnt vmcnt(8)
	s_waitcnt lgkmcnt(0)
	s_barrier
	v_mfma_f32_16x16x32_bf16 v[124:127], v[128:131], v[172:175], v[124:127]
	v_mfma_f32_16x16x32_bf16 v[120:123], v[136:139], v[172:175], v[120:123]
	v_mfma_f32_16x16x32_bf16 v[108:111], v[128:131], v[188:191], v[108:111]
	v_mfma_f32_16x16x32_bf16 v[104:107], v[136:139], v[188:191], v[104:107]
	v_mfma_f32_16x16x32_bf16 v[92:95], v[128:131], v[196:199], v[92:95]
	v_mfma_f32_16x16x32_bf16 v[88:91], v[136:139], v[196:199], v[88:91]
	v_mfma_f32_16x16x32_bf16 v[76:79], v[128:131], v[204:207], v[76:79]
	v_mfma_f32_16x16x32_bf16 v[72:75], v[136:139], v[204:207], v[72:75]
	v_mfma_f32_16x16x32_bf16 v[124:127], v[132:135], v[176:179], v[124:127]
	v_mfma_f32_16x16x32_bf16 v[120:123], v[140:143], v[176:179], v[120:123]
	v_mfma_f32_16x16x32_bf16 v[108:111], v[132:135], v[192:195], v[108:111]
	v_mfma_f32_16x16x32_bf16 v[104:107], v[140:143], v[192:195], v[104:107]
	v_mfma_f32_16x16x32_bf16 v[92:95], v[132:135], v[200:203], v[92:95]
	v_mfma_f32_16x16x32_bf16 v[88:91], v[140:143], v[200:203], v[88:91]
	v_mfma_f32_16x16x32_bf16 v[76:79], v[132:135], v[208:211], v[76:79]
	v_mfma_f32_16x16x32_bf16 v[72:75], v[140:143], v[208:211], v[72:75]
	v_mfma_f32_16x16x32_bf16 v[116:119], v[144:147], v[172:175], v[116:119]
	v_mfma_f32_16x16x32_bf16 v[112:115], v[164:167], v[172:175], v[112:115]
	v_mfma_f32_16x16x32_bf16 v[100:103], v[144:147], v[188:191], v[100:103]
	v_mfma_f32_16x16x32_bf16 v[96:99], v[164:167], v[188:191], v[96:99]
	v_mfma_f32_16x16x32_bf16 v[84:87], v[144:147], v[196:199], v[84:87]
	v_mfma_f32_16x16x32_bf16 v[80:83], v[164:167], v[196:199], v[80:83]
	v_mfma_f32_16x16x32_bf16 v[68:71], v[144:147], v[204:207], v[68:71]
	v_mfma_f32_16x16x32_bf16 v[64:67], v[164:167], v[204:207], v[64:67]
	v_mfma_f32_16x16x32_bf16 v[116:119], v[148:151], v[176:179], v[116:119]
	v_mfma_f32_16x16x32_bf16 v[112:115], v[168:171], v[176:179], v[112:115]
	v_mfma_f32_16x16x32_bf16 v[100:103], v[148:151], v[192:195], v[100:103]
	v_mfma_f32_16x16x32_bf16 v[96:99], v[168:171], v[192:195], v[96:99]
	v_mfma_f32_16x16x32_bf16 v[84:87], v[148:151], v[200:203], v[84:87]
	v_mfma_f32_16x16x32_bf16 v[80:83], v[168:171], v[200:203], v[80:83]
	v_mfma_f32_16x16x32_bf16 v[68:71], v[148:151], v[208:211], v[68:71]
	v_mfma_f32_16x16x32_bf16 v[64:67], v[168:171], v[208:211], v[64:67]
	s_barrier
	s_add_i32 s28, s43, s2
	v_lshl_add_u64 v[180:181], v[180:181], 0, s[14:15]
	s_mov_b32 m0, s28
	ds_read_b128 v[172:175], v186 offset:49152
	ds_read_b128 v[176:179], v186 offset:50176
	ds_read_b128 v[188:191], v186 offset:51200
	ds_read_b128 v[192:195], v186 offset:52224
	ds_read_b128 v[196:199], v186 offset:53248
	ds_read_b128 v[200:203], v186 offset:54272
	ds_read_b128 v[204:207], v186 offset:55296
	ds_read_b128 v[208:211], v186 offset:56320
	global_load_lds_dwordx4 v[180:181], off
	s_add_i32 m0, s28, 0x2000
	s_add_u32 s26, s26, 0x40080
	v_lshl_add_u64 v[180:181], v[212:213], 0, s[14:15]
	s_addc_u32 s27, s27, 0
	s_add_i32 s28, s44, s2
	global_load_lds_dwordx4 v[180:181], off
	v_lshl_add_u64 v[180:181], s[26:27], 0, v[154:155]
	s_mov_b32 m0, s28
	s_nop 0
	global_load_lds_dwordx4 v[180:181], off
	v_lshl_add_u64 v[180:181], s[26:27], 0, v[158:159]
	s_add_i32 m0, s28, 0x2000
	s_nop 0
	global_load_lds_dwordx4 v[180:181], off
	v_lshl_add_u64 v[180:181], v[214:215], 0, s[14:15]
	s_mov_b32 m0, s38
	s_nop 0
	global_load_lds_dwordx4 v[180:181], off
	v_lshl_add_u64 v[180:181], v[216:217], 0, s[14:15]
	s_mov_b32 m0, s39
	s_nop 0
	global_load_lds_dwordx4 v[180:181], off
	s_waitcnt vmcnt(8)
	s_waitcnt lgkmcnt(0)
	s_barrier
	v_mfma_f32_16x16x32_bf16 v[60:63], v[128:131], v[172:175], v[60:63]
	v_mfma_f32_16x16x32_bf16 v[56:59], v[136:139], v[172:175], v[56:59]
	v_mfma_f32_16x16x32_bf16 v[44:47], v[128:131], v[188:191], v[44:47]
	v_mfma_f32_16x16x32_bf16 v[40:43], v[136:139], v[188:191], v[40:43]
	v_mfma_f32_16x16x32_bf16 v[28:31], v[128:131], v[196:199], v[28:31]
	v_mfma_f32_16x16x32_bf16 v[24:27], v[136:139], v[196:199], v[24:27]
	v_mfma_f32_16x16x32_bf16 v[12:15], v[128:131], v[204:207], v[12:15]
	v_mfma_f32_16x16x32_bf16 v[8:11], v[136:139], v[204:207], v[8:11]
	v_mfma_f32_16x16x32_bf16 v[60:63], v[132:135], v[176:179], v[60:63]
	v_mfma_f32_16x16x32_bf16 v[56:59], v[140:143], v[176:179], v[56:59]
	v_mfma_f32_16x16x32_bf16 v[44:47], v[132:135], v[192:195], v[44:47]
	v_mfma_f32_16x16x32_bf16 v[40:43], v[140:143], v[192:195], v[40:43]
	v_mfma_f32_16x16x32_bf16 v[28:31], v[132:135], v[200:203], v[28:31]
	v_mfma_f32_16x16x32_bf16 v[24:27], v[140:143], v[200:203], v[24:27]
	v_mfma_f32_16x16x32_bf16 v[12:15], v[132:135], v[208:211], v[12:15]
	v_mfma_f32_16x16x32_bf16 v[8:11], v[140:143], v[208:211], v[8:11]
	v_mfma_f32_16x16x32_bf16 v[52:55], v[144:147], v[172:175], v[52:55]
	v_mfma_f32_16x16x32_bf16 v[48:51], v[164:167], v[172:175], v[48:51]
	v_mfma_f32_16x16x32_bf16 v[36:39], v[144:147], v[188:191], v[36:39]
	v_mfma_f32_16x16x32_bf16 v[32:35], v[164:167], v[188:191], v[32:35]
	v_mfma_f32_16x16x32_bf16 v[20:23], v[144:147], v[196:199], v[20:23]
	v_mfma_f32_16x16x32_bf16 v[16:19], v[164:167], v[196:199], v[16:19]
	v_mfma_f32_16x16x32_bf16 v[4:7], v[144:147], v[204:207], v[4:7]
	v_mfma_f32_16x16x32_bf16 v[0:3], v[164:167], v[204:207], v[0:3]
	v_mfma_f32_16x16x32_bf16 v[52:55], v[148:151], v[176:179], v[52:55]
	v_mfma_f32_16x16x32_bf16 v[48:51], v[168:171], v[176:179], v[48:51]
	v_mfma_f32_16x16x32_bf16 v[36:39], v[148:151], v[192:195], v[36:39]
	v_mfma_f32_16x16x32_bf16 v[32:35], v[168:171], v[192:195], v[32:35]
	v_mfma_f32_16x16x32_bf16 v[20:23], v[148:151], v[200:203], v[20:23]
	v_mfma_f32_16x16x32_bf16 v[16:19], v[168:171], v[200:203], v[16:19]
	v_mfma_f32_16x16x32_bf16 v[4:7], v[148:151], v[208:211], v[4:7]
	v_mfma_f32_16x16x32_bf16 v[0:3], v[168:171], v[208:211], v[0:3]
	s_barrier
	s_add_i32 s42, s42, 2
	s_add_u32 s4, s4, 0x100
	s_addc_u32 s5, s5, 0
	s_add_u32 s1, s1, 0x100
	s_addc_u32 s21, s21, 0
	s_cmp_gt_u32 s42, 13
	s_cbranch_scc0 .LBB0_913
	s_and_b64 vcc, exec, s[16:17]
	s_cbranch_vccz .LBB0_916
	s_barrier

.LBB0_1005:
	ds_read_b128 v[140:143], v146
	ds_read_b128 v[150:153], v146 offset:1024
	ds_read_b128 v[154:157], v146 offset:2048
	ds_read_b128 v[158:161], v146 offset:3072
	ds_read_b128 v[162:165], v147
	ds_read_b128 v[166:169], v147 offset:1024
	ds_read_b128 v[170:173], v147 offset:2048
	ds_read_b128 v[174:177], v147 offset:3072
	s_add_u32 s36, s34, 0xfff80080
	s_addc_u32 s37, s35, -1
	s_cmp_eq_u32 s43, 28
	s_cselect_b32 s39, s29, s37
	s_cselect_b32 s38, s28, s36
	s_cselect_b32 s37, s31, s42
	s_cselect_b32 s36, s30, s27
	v_lshl_add_u64 v[210:211], s[34:35], 0, v[136:137]
	s_add_i32 m0, s3, 0xc000
	ds_read_b128 v[178:181], v148
	ds_read_b128 v[182:185], v148 offset:1024
	ds_read_b128 v[186:189], v148 offset:2048
	ds_read_b128 v[190:193], v148 offset:3072
	ds_read_b128 v[194:197], v148 offset:4096
	ds_read_b128 v[198:201], v148 offset:5120
	ds_read_b128 v[202:205], v148 offset:6144
	ds_read_b128 v[206:209], v148 offset:7168
	global_load_lds_dwordx4 v[210:211], off
	v_lshl_add_u64 v[210:211], s[34:35], 0, v[138:139]
	s_add_i32 m0, s3, 0xe000
	s_nop 0
	global_load_lds_dwordx4 v[210:211], off
	s_waitcnt vmcnt(8)
	s_waitcnt lgkmcnt(0)
	s_barrier
	v_mfma_f32_16x16x32_bf16 v[124:127], v[140:143], v[178:181], v[124:127]
	v_mfma_f32_16x16x32_bf16 v[120:123], v[154:157], v[178:181], v[120:123]
	v_mfma_f32_16x16x32_bf16 v[116:119], v[140:143], v[186:189], v[116:119]
	v_mfma_f32_16x16x32_bf16 v[104:107], v[154:157], v[186:189], v[104:107]
	v_mfma_f32_16x16x32_bf16 v[92:95], v[140:143], v[194:197], v[92:95]
	v_mfma_f32_16x16x32_bf16 v[88:91], v[154:157], v[194:197], v[88:91]
	v_mfma_f32_16x16x32_bf16 v[76:79], v[140:143], v[202:205], v[76:79]
	v_mfma_f32_16x16x32_bf16 v[72:75], v[154:157], v[202:205], v[72:75]
	v_mfma_f32_16x16x32_bf16 v[124:127], v[150:153], v[182:185], v[124:127]
	v_mfma_f32_16x16x32_bf16 v[120:123], v[158:161], v[182:185], v[120:123]
	v_mfma_f32_16x16x32_bf16 v[116:119], v[150:153], v[190:193], v[116:119]
	v_mfma_f32_16x16x32_bf16 v[104:107], v[158:161], v[190:193], v[104:107]
	v_mfma_f32_16x16x32_bf16 v[92:95], v[150:153], v[198:201], v[92:95]
	v_mfma_f32_16x16x32_bf16 v[88:91], v[158:161], v[198:201], v[88:91]
	v_mfma_f32_16x16x32_bf16 v[76:79], v[150:153], v[206:209], v[76:79]
	v_mfma_f32_16x16x32_bf16 v[72:75], v[158:161], v[206:209], v[72:75]
	v_mfma_f32_16x16x32_bf16 v[112:115], v[162:165], v[178:181], v[112:115]
	v_mfma_f32_16x16x32_bf16 v[108:111], v[170:173], v[178:181], v[108:111]
	v_mfma_f32_16x16x32_bf16 v[100:103], v[162:165], v[186:189], v[100:103]
	v_mfma_f32_16x16x32_bf16 v[96:99], v[170:173], v[186:189], v[96:99]
	v_mfma_f32_16x16x32_bf16 v[84:87], v[162:165], v[194:197], v[84:87]
	v_mfma_f32_16x16x32_bf16 v[80:83], v[170:173], v[194:197], v[80:83]
	v_mfma_f32_16x16x32_bf16 v[68:71], v[162:165], v[202:205], v[68:71]
	v_mfma_f32_16x16x32_bf16 v[64:67], v[170:173], v[202:205], v[64:67]
	v_mfma_f32_16x16x32_bf16 v[112:115], v[166:169], v[182:185], v[112:115]
	v_mfma_f32_16x16x32_bf16 v[108:111], v[174:177], v[182:185], v[108:111]
	v_mfma_f32_16x16x32_bf16 v[100:103], v[166:169], v[190:193], v[100:103]
	v_mfma_f32_16x16x32_bf16 v[96:99], v[174:177], v[190:193], v[96:99]
	v_mfma_f32_16x16x32_bf16 v[84:87], v[166:169], v[198:201], v[84:87]
	v_mfma_f32_16x16x32_bf16 v[80:83], v[174:177], v[198:201], v[80:83]
	v_mfma_f32_16x16x32_bf16 v[68:71], v[166:169], v[206:209], v[68:71]
	v_mfma_f32_16x16x32_bf16 v[64:67], v[174:177], v[206:209], v[64:67]
	s_barrier
	s_add_i32 s65, s49, s2
	v_lshl_add_u64 v[210:211], s[36:37], 0, v[130:131]
	s_mov_b32 m0, s65
	ds_read_b128 v[178:181], v148 offset:16384
	ds_read_b128 v[182:185], v148 offset:17408
	ds_read_b128 v[186:189], v148 offset:18432
	ds_read_b128 v[190:193], v148 offset:19456
	ds_read_b128 v[194:197], v148 offset:20480
	ds_read_b128 v[198:201], v148 offset:21504
	ds_read_b128 v[202:205], v148 offset:22528
	ds_read_b128 v[206:209], v148 offset:23552
	global_load_lds_dwordx4 v[210:211], off
	s_add_i32 m0, s65, 0x2000
	s_add_u32 s66, s36, 0x80000
	v_lshl_add_u64 v[212:213], s[36:37], 0, v[134:135]
	s_addc_u32 s67, s37, 0
	s_add_i32 s65, s50, s2
	global_load_lds_dwordx4 v[212:213], off
	v_lshl_add_u64 v[214:215], s[66:67], 0, v[130:131]
	s_mov_b32 m0, s65
	v_lshl_add_u64 v[216:217], s[38:39], 0, v[132:133]
	global_load_lds_dwordx4 v[214:215], off
	v_lshl_add_u64 v[214:215], s[66:67], 0, v[134:135]
	s_add_i32 m0, s65, 0x2000
	s_nop 0
	global_load_lds_dwordx4 v[214:215], off
	v_lshl_add_u64 v[214:215], s[38:39], 0, v[128:129]
	s_mov_b32 m0, s3
	s_nop 0
	global_load_lds_dwordx4 v[214:215], off
	s_mov_b32 m0, s33
	s_nop 0
	global_load_lds_dwordx4 v[216:217], off
	s_waitcnt vmcnt(8)
	s_waitcnt lgkmcnt(0)
	s_barrier
	v_mfma_f32_16x16x32_bf16 v[60:63], v[140:143], v[178:181], v[60:63]
	v_mfma_f32_16x16x32_bf16 v[56:59], v[154:157], v[178:181], v[56:59]
	v_mfma_f32_16x16x32_bf16 v[44:47], v[140:143], v[186:189], v[44:47]
	v_mfma_f32_16x16x32_bf16 v[40:43], v[154:157], v[186:189], v[40:43]
	v_mfma_f32_16x16x32_bf16 v[28:31], v[140:143], v[194:197], v[28:31]
	v_mfma_f32_16x16x32_bf16 v[24:27], v[154:157], v[194:197], v[24:27]
	v_mfma_f32_16x16x32_bf16 v[12:15], v[140:143], v[202:205], v[12:15]
	v_mfma_f32_16x16x32_bf16 v[8:11], v[154:157], v[202:205], v[8:11]
	v_mfma_f32_16x16x32_bf16 v[60:63], v[150:153], v[182:185], v[60:63]
	v_mfma_f32_16x16x32_bf16 v[56:59], v[158:161], v[182:185], v[56:59]
	v_mfma_f32_16x16x32_bf16 v[44:47], v[150:153], v[190:193], v[44:47]
	v_mfma_f32_16x16x32_bf16 v[40:43], v[158:161], v[190:193], v[40:43]
	v_mfma_f32_16x16x32_bf16 v[28:31], v[150:153], v[198:201], v[28:31]
	v_mfma_f32_16x16x32_bf16 v[24:27], v[158:161], v[198:201], v[24:27]
	v_mfma_f32_16x16x32_bf16 v[12:15], v[150:153], v[206:209], v[12:15]
	v_mfma_f32_16x16x32_bf16 v[8:11], v[158:161], v[206:209], v[8:11]
	v_mfma_f32_16x16x32_bf16 v[52:55], v[162:165], v[178:181], v[52:55]
	v_mfma_f32_16x16x32_bf16 v[48:51], v[170:173], v[178:181], v[48:51]
	v_mfma_f32_16x16x32_bf16 v[36:39], v[162:165], v[186:189], v[36:39]
	v_mfma_f32_16x16x32_bf16 v[32:35], v[170:173], v[186:189], v[32:35]
	v_mfma_f32_16x16x32_bf16 v[20:23], v[162:165], v[194:197], v[20:23]
	v_mfma_f32_16x16x32_bf16 v[16:19], v[170:173], v[194:197], v[16:19]
	v_mfma_f32_16x16x32_bf16 v[4:7], v[162:165], v[202:205], v[4:7]
	v_mfma_f32_16x16x32_bf16 v[0:3], v[170:173], v[202:205], v[0:3]
	v_mfma_f32_16x16x32_bf16 v[52:55], v[166:169], v[182:185], v[52:55]
	v_mfma_f32_16x16x32_bf16 v[48:51], v[174:177], v[182:185], v[48:51]
	v_mfma_f32_16x16x32_bf16 v[36:39], v[166:169], v[190:193], v[36:39]
	v_mfma_f32_16x16x32_bf16 v[32:35], v[174:177], v[190:193], v[32:35]
	v_mfma_f32_16x16x32_bf16 v[20:23], v[166:169], v[198:201], v[20:23]
	v_mfma_f32_16x16x32_bf16 v[16:19], v[174:177], v[198:201], v[16:19]
	v_mfma_f32_16x16x32_bf16 v[4:7], v[166:169], v[206:209], v[4:7]
	v_mfma_f32_16x16x32_bf16 v[0:3], v[174:177], v[206:209], v[0:3]
	s_barrier
	s_add_i32 s65, 0, 0x18000
	s_add_i32 s66, 0, 0x1c000
	v_add_u32_e32 v158, s65, v145
	v_add_u32_e32 v174, s66, v145
	ds_read_b128 v[140:143], v158
	ds_read_b128 v[150:153], v158 offset:1024
	ds_read_b128 v[154:157], v158 offset:2048
	ds_read_b128 v[158:161], v158 offset:3072
	ds_read_b128 v[162:165], v174
	ds_read_b128 v[166:169], v174 offset:1024
	ds_read_b128 v[170:173], v174 offset:2048
	ds_read_b128 v[174:177], v174 offset:3072
	s_add_u32 s38, s38, 0x80000
	s_addc_u32 s39, s39, 0
	s_mov_b32 m0, s40
	v_lshl_add_u64 v[220:221], s[38:39], 0, v[128:129]
	ds_read_b128 v[178:181], v148 offset:32768
	ds_read_b128 v[182:185], v148 offset:33792
	ds_read_b128 v[186:189], v148 offset:34816
	ds_read_b128 v[190:193], v148 offset:35840
	ds_read_b128 v[194:197], v148 offset:36864
	ds_read_b128 v[198:201], v148 offset:37888
	ds_read_b128 v[202:205], v148 offset:38912
	ds_read_b128 v[206:209], v148 offset:39936
	global_load_lds_dwordx4 v[220:221], off
	v_lshl_add_u64 v[220:221], s[38:39], 0, v[132:133]
	s_mov_b32 m0, s41
	s_nop 0
	global_load_lds_dwordx4 v[220:221], off
	s_waitcnt vmcnt(8)
	s_waitcnt lgkmcnt(0)
	s_barrier
	v_mfma_f32_16x16x32_bf16 v[124:127], v[140:143], v[178:181], v[124:127]
	v_mfma_f32_16x16x32_bf16 v[120:123], v[154:157], v[178:181], v[120:123]
	v_mfma_f32_16x16x32_bf16 v[116:119], v[140:143], v[186:189], v[116:119]
	v_mfma_f32_16x16x32_bf16 v[104:107], v[154:157], v[186:189], v[104:107]
	v_mfma_f32_16x16x32_bf16 v[92:95], v[140:143], v[194:197], v[92:95]
	v_mfma_f32_16x16x32_bf16 v[88:91], v[154:157], v[194:197], v[88:91]
	v_mfma_f32_16x16x32_bf16 v[76:79], v[140:143], v[202:205], v[76:79]
	v_mfma_f32_16x16x32_bf16 v[72:75], v[154:157], v[202:205], v[72:75]
	v_mfma_f32_16x16x32_bf16 v[124:127], v[150:153], v[182:185], v[124:127]
	v_mfma_f32_16x16x32_bf16 v[120:123], v[158:161], v[182:185], v[120:123]
	v_mfma_f32_16x16x32_bf16 v[116:119], v[150:153], v[190:193], v[116:119]
	v_mfma_f32_16x16x32_bf16 v[104:107], v[158:161], v[190:193], v[104:107]
	v_mfma_f32_16x16x32_bf16 v[92:95], v[150:153], v[198:201], v[92:95]
	v_mfma_f32_16x16x32_bf16 v[88:91], v[158:161], v[198:201], v[88:91]
	v_mfma_f32_16x16x32_bf16 v[76:79], v[150:153], v[206:209], v[76:79]
	v_mfma_f32_16x16x32_bf16 v[72:75], v[158:161], v[206:209], v[72:75]
	v_mfma_f32_16x16x32_bf16 v[112:115], v[162:165], v[178:181], v[112:115]
	v_mfma_f32_16x16x32_bf16 v[108:111], v[170:173], v[178:181], v[108:111]
	v_mfma_f32_16x16x32_bf16 v[100:103], v[162:165], v[186:189], v[100:103]
	v_mfma_f32_16x16x32_bf16 v[96:99], v[170:173], v[186:189], v[96:99]
	v_mfma_f32_16x16x32_bf16 v[84:87], v[162:165], v[194:197], v[84:87]
	v_mfma_f32_16x16x32_bf16 v[80:83], v[170:173], v[194:197], v[80:83]
	v_mfma_f32_16x16x32_bf16 v[68:71], v[162:165], v[202:205], v[68:71]
	v_mfma_f32_16x16x32_bf16 v[64:67], v[170:173], v[202:205], v[64:67]
	v_mfma_f32_16x16x32_bf16 v[112:115], v[166:169], v[182:185], v[112:115]
	v_mfma_f32_16x16x32_bf16 v[108:111], v[174:177], v[182:185], v[108:111]
	v_mfma_f32_16x16x32_bf16 v[100:103], v[166:169], v[190:193], v[100:103]
	v_mfma_f32_16x16x32_bf16 v[96:99], v[174:177], v[190:193], v[96:99]
	v_mfma_f32_16x16x32_bf16 v[84:87], v[166:169], v[198:201], v[84:87]
	v_mfma_f32_16x16x32_bf16 v[80:83], v[174:177], v[198:201], v[80:83]
	v_mfma_f32_16x16x32_bf16 v[68:71], v[166:169], v[206:209], v[68:71]
	v_mfma_f32_16x16x32_bf16 v[64:67], v[174:177], v[206:209], v[64:67]
	s_barrier
	s_add_i32 s38, s65, s2
	v_lshl_add_u64 v[210:211], v[210:211], 0, s[12:13]
	s_mov_b32 m0, s38
	ds_read_b128 v[178:181], v148 offset:49152
	ds_read_b128 v[182:185], v148 offset:50176
	ds_read_b128 v[186:189], v148 offset:51200
	ds_read_b128 v[190:193], v148 offset:52224
	ds_read_b128 v[194:197], v148 offset:53248
	ds_read_b128 v[198:201], v148 offset:54272
	ds_read_b128 v[202:205], v148 offset:55296
	ds_read_b128 v[206:209], v148 offset:56320
	global_load_lds_dwordx4 v[210:211], off
	s_add_i32 m0, s38, 0x2000
	s_add_u32 s36, s36, 0x80080
	v_lshl_add_u64 v[210:211], v[212:213], 0, s[12:13]
	s_addc_u32 s37, s37, 0
	s_add_i32 s38, s66, s2
	global_load_lds_dwordx4 v[210:211], off
	v_lshl_add_u64 v[210:211], s[36:37], 0, v[130:131]
	s_mov_b32 m0, s38
	s_nop 0
	global_load_lds_dwordx4 v[210:211], off
	v_lshl_add_u64 v[210:211], s[36:37], 0, v[134:135]
	s_add_i32 m0, s38, 0x2000
	s_nop 0
	global_load_lds_dwordx4 v[210:211], off
	v_lshl_add_u64 v[210:211], v[214:215], 0, s[12:13]
	s_mov_b32 m0, s47
	s_nop 0
	global_load_lds_dwordx4 v[210:211], off
	v_lshl_add_u64 v[210:211], v[216:217], 0, s[12:13]
	s_mov_b32 m0, s48
	s_nop 0
	global_load_lds_dwordx4 v[210:211], off
	s_waitcnt vmcnt(8)
	s_waitcnt lgkmcnt(0)
	s_barrier
	v_mfma_f32_16x16x32_bf16 v[60:63], v[140:143], v[178:181], v[60:63]
	v_mfma_f32_16x16x32_bf16 v[56:59], v[154:157], v[178:181], v[56:59]
	v_mfma_f32_16x16x32_bf16 v[44:47], v[140:143], v[186:189], v[44:47]
	v_mfma_f32_16x16x32_bf16 v[40:43], v[154:157], v[186:189], v[40:43]
	v_mfma_f32_16x16x32_bf16 v[28:31], v[140:143], v[194:197], v[28:31]
	v_mfma_f32_16x16x32_bf16 v[24:27], v[154:157], v[194:197], v[24:27]
	v_mfma_f32_16x16x32_bf16 v[12:15], v[140:143], v[202:205], v[12:15]
	v_mfma_f32_16x16x32_bf16 v[8:11], v[154:157], v[202:205], v[8:11]
	v_mfma_f32_16x16x32_bf16 v[60:63], v[150:153], v[182:185], v[60:63]
	v_mfma_f32_16x16x32_bf16 v[56:59], v[158:161], v[182:185], v[56:59]
	v_mfma_f32_16x16x32_bf16 v[44:47], v[150:153], v[190:193], v[44:47]
	v_mfma_f32_16x16x32_bf16 v[40:43], v[158:161], v[190:193], v[40:43]
	v_mfma_f32_16x16x32_bf16 v[28:31], v[150:153], v[198:201], v[28:31]
	v_mfma_f32_16x16x32_bf16 v[24:27], v[158:161], v[198:201], v[24:27]
	v_mfma_f32_16x16x32_bf16 v[12:15], v[150:153], v[206:209], v[12:15]
	v_mfma_f32_16x16x32_bf16 v[8:11], v[158:161], v[206:209], v[8:11]
	v_mfma_f32_16x16x32_bf16 v[52:55], v[162:165], v[178:181], v[52:55]
	v_mfma_f32_16x16x32_bf16 v[48:51], v[170:173], v[178:181], v[48:51]
	v_mfma_f32_16x16x32_bf16 v[36:39], v[162:165], v[186:189], v[36:39]
	v_mfma_f32_16x16x32_bf16 v[32:35], v[170:173], v[186:189], v[32:35]
	v_mfma_f32_16x16x32_bf16 v[20:23], v[162:165], v[194:197], v[20:23]
	v_mfma_f32_16x16x32_bf16 v[16:19], v[170:173], v[194:197], v[16:19]
	v_mfma_f32_16x16x32_bf16 v[4:7], v[162:165], v[202:205], v[4:7]
	v_mfma_f32_16x16x32_bf16 v[0:3], v[170:173], v[202:205], v[0:3]
	v_mfma_f32_16x16x32_bf16 v[52:55], v[166:169], v[182:185], v[52:55]
	v_mfma_f32_16x16x32_bf16 v[48:51], v[174:177], v[182:185], v[48:51]
	v_mfma_f32_16x16x32_bf16 v[36:39], v[166:169], v[190:193], v[36:39]
	v_mfma_f32_16x16x32_bf16 v[32:35], v[174:177], v[190:193], v[32:35]
	v_mfma_f32_16x16x32_bf16 v[20:23], v[166:169], v[198:201], v[20:23]
	v_mfma_f32_16x16x32_bf16 v[16:19], v[174:177], v[198:201], v[16:19]
	v_mfma_f32_16x16x32_bf16 v[4:7], v[166:169], v[206:209], v[4:7]
	v_mfma_f32_16x16x32_bf16 v[0:3], v[174:177], v[206:209], v[0:3]
	s_barrier
	s_add_i32 s43, s43, 2
	s_add_u32 s34, s34, 0x100
	s_addc_u32 s35, s35, 0
	s_add_u32 s27, s27, 0x100
	s_addc_u32 s42, s42, 0
	s_cmp_gt_u32 s43, 29
	s_cbranch_scc0 .LBB0_1005
	s_and_b64 vcc, exec, s[14:15]
	s_cbranch_vccz .LBB0_1008
	s_barrier

.LBB0_1081:
	ds_read_b128 v[128:131], v156
	ds_read_b128 v[132:135], v156 offset:1024
	ds_read_b128 v[148:151], v156 offset:2048
	ds_read_b128 v[160:163], v156 offset:3072
	ds_read_b128 v[164:167], v157
	ds_read_b128 v[168:171], v157 offset:1024
	ds_read_b128 v[172:175], v157 offset:2048
	ds_read_b128 v[176:179], v157 offset:3072
	s_add_u32 s30, s28, 0xffe00080
	s_addc_u32 s31, s29, -1
	s_cmpk_eq_i32 s51, 0x7c
	s_cselect_b32 s35, s23, s31
	s_cselect_b32 s34, s22, s30
	s_cselect_b32 s31, s25, s43
	s_cselect_b32 s30, s24, s21
	v_lshl_add_u64 v[152:153], s[28:29], 0, v[144:145]
	s_add_i32 m0, s3, 0xc000
	ds_read_b128 v[180:183], v158
	ds_read_b128 v[184:187], v158 offset:1024
	ds_read_b128 v[188:191], v158 offset:2048
	ds_read_b128 v[192:195], v158 offset:3072
	ds_read_b128 v[196:199], v158 offset:4096
	ds_read_b128 v[200:203], v158 offset:5120
	ds_read_b128 v[204:207], v158 offset:6144
	ds_read_b128 v[208:211], v158 offset:7168
	global_load_lds_dwordx4 v[152:153], off
	v_lshl_add_u64 v[152:153], s[28:29], 0, v[146:147]
	s_add_i32 m0, s3, 0xe000
	s_nop 0
	global_load_lds_dwordx4 v[152:153], off
	s_waitcnt vmcnt(8)
	s_waitcnt lgkmcnt(0)
	s_barrier
	v_mfma_f32_16x16x32_bf16 v[124:127], v[128:131], v[180:183], v[124:127]
	v_mfma_f32_16x16x32_bf16 v[120:123], v[148:151], v[180:183], v[120:123]
	v_mfma_f32_16x16x32_bf16 v[108:111], v[128:131], v[188:191], v[108:111]
	v_mfma_f32_16x16x32_bf16 v[104:107], v[148:151], v[188:191], v[104:107]
	v_mfma_f32_16x16x32_bf16 v[92:95], v[128:131], v[196:199], v[92:95]
	v_mfma_f32_16x16x32_bf16 v[88:91], v[148:151], v[196:199], v[88:91]
	v_mfma_f32_16x16x32_bf16 v[76:79], v[128:131], v[204:207], v[76:79]
	v_mfma_f32_16x16x32_bf16 v[72:75], v[148:151], v[204:207], v[72:75]
	v_mfma_f32_16x16x32_bf16 v[124:127], v[132:135], v[184:187], v[124:127]
	v_mfma_f32_16x16x32_bf16 v[120:123], v[160:163], v[184:187], v[120:123]
	v_mfma_f32_16x16x32_bf16 v[108:111], v[132:135], v[192:195], v[108:111]
	v_mfma_f32_16x16x32_bf16 v[104:107], v[160:163], v[192:195], v[104:107]
	v_mfma_f32_16x16x32_bf16 v[92:95], v[132:135], v[200:203], v[92:95]
	v_mfma_f32_16x16x32_bf16 v[88:91], v[160:163], v[200:203], v[88:91]
	v_mfma_f32_16x16x32_bf16 v[76:79], v[132:135], v[208:211], v[76:79]
	v_mfma_f32_16x16x32_bf16 v[72:75], v[160:163], v[208:211], v[72:75]
	v_mfma_f32_16x16x32_bf16 v[116:119], v[164:167], v[180:183], v[116:119]
	v_mfma_f32_16x16x32_bf16 v[112:115], v[172:175], v[180:183], v[112:115]
	v_mfma_f32_16x16x32_bf16 v[100:103], v[164:167], v[188:191], v[100:103]
	v_mfma_f32_16x16x32_bf16 v[96:99], v[172:175], v[188:191], v[96:99]
	v_mfma_f32_16x16x32_bf16 v[84:87], v[164:167], v[196:199], v[84:87]
	v_mfma_f32_16x16x32_bf16 v[80:83], v[172:175], v[196:199], v[80:83]
	v_mfma_f32_16x16x32_bf16 v[68:71], v[164:167], v[204:207], v[68:71]
	v_mfma_f32_16x16x32_bf16 v[64:67], v[172:175], v[204:207], v[64:67]
	v_mfma_f32_16x16x32_bf16 v[116:119], v[168:171], v[184:187], v[116:119]
	v_mfma_f32_16x16x32_bf16 v[112:115], v[176:179], v[184:187], v[112:115]
	v_mfma_f32_16x16x32_bf16 v[100:103], v[168:171], v[192:195], v[100:103]
	v_mfma_f32_16x16x32_bf16 v[96:99], v[176:179], v[192:195], v[96:99]
	v_mfma_f32_16x16x32_bf16 v[84:87], v[168:171], v[200:203], v[84:87]
	v_mfma_f32_16x16x32_bf16 v[80:83], v[176:179], v[200:203], v[80:83]
	v_mfma_f32_16x16x32_bf16 v[68:71], v[168:171], v[208:211], v[68:71]
	v_mfma_f32_16x16x32_bf16 v[64:67], v[176:179], v[208:211], v[64:67]
	s_barrier
	s_add_i32 s52, s44, s2
	v_lshl_add_u64 v[152:153], s[30:31], 0, v[138:139]
	s_mov_b32 m0, s52
	ds_read_b128 v[180:183], v158 offset:16384
	ds_read_b128 v[184:187], v158 offset:17408
	ds_read_b128 v[188:191], v158 offset:18432
	ds_read_b128 v[192:195], v158 offset:19456
	ds_read_b128 v[196:199], v158 offset:20480
	ds_read_b128 v[200:203], v158 offset:21504
	ds_read_b128 v[204:207], v158 offset:22528
	ds_read_b128 v[208:211], v158 offset:23552
	global_load_lds_dwordx4 v[152:153], off
	s_add_i32 m0, s52, 0x2000
	s_add_u32 s52, s30, 0x200000
	v_lshl_add_u64 v[212:213], s[30:31], 0, v[142:143]
	s_addc_u32 s53, s31, 0
	s_add_i32 s54, s45, s2
	global_load_lds_dwordx4 v[212:213], off
	v_lshl_add_u64 v[214:215], s[52:53], 0, v[138:139]
	s_mov_b32 m0, s54
	v_lshl_add_u64 v[216:217], s[34:35], 0, v[140:141]
	global_load_lds_dwordx4 v[214:215], off
	v_lshl_add_u64 v[214:215], s[52:53], 0, v[142:143]
	s_add_i32 m0, s54, 0x2000
	s_nop 0
	global_load_lds_dwordx4 v[214:215], off
	v_lshl_add_u64 v[214:215], s[34:35], 0, v[136:137]
	s_mov_b32 m0, s3
	s_nop 0
	global_load_lds_dwordx4 v[214:215], off
	s_mov_b32 m0, s27
	s_nop 0
	global_load_lds_dwordx4 v[216:217], off
	s_waitcnt vmcnt(8)
	s_waitcnt lgkmcnt(0)
	s_barrier
	v_mfma_f32_16x16x32_bf16 v[60:63], v[128:131], v[180:183], v[60:63]
	v_mfma_f32_16x16x32_bf16 v[56:59], v[148:151], v[180:183], v[56:59]
	v_mfma_f32_16x16x32_bf16 v[44:47], v[128:131], v[188:191], v[44:47]
	v_mfma_f32_16x16x32_bf16 v[40:43], v[148:151], v[188:191], v[40:43]
	v_mfma_f32_16x16x32_bf16 v[28:31], v[128:131], v[196:199], v[28:31]
	v_mfma_f32_16x16x32_bf16 v[24:27], v[148:151], v[196:199], v[24:27]
	v_mfma_f32_16x16x32_bf16 v[12:15], v[128:131], v[204:207], v[12:15]
	v_mfma_f32_16x16x32_bf16 v[8:11], v[148:151], v[204:207], v[8:11]
	v_mfma_f32_16x16x32_bf16 v[60:63], v[132:135], v[184:187], v[60:63]
	v_mfma_f32_16x16x32_bf16 v[56:59], v[160:163], v[184:187], v[56:59]
	v_mfma_f32_16x16x32_bf16 v[44:47], v[132:135], v[192:195], v[44:47]
	v_mfma_f32_16x16x32_bf16 v[40:43], v[160:163], v[192:195], v[40:43]
	v_mfma_f32_16x16x32_bf16 v[28:31], v[132:135], v[200:203], v[28:31]
	v_mfma_f32_16x16x32_bf16 v[24:27], v[160:163], v[200:203], v[24:27]
	v_mfma_f32_16x16x32_bf16 v[12:15], v[132:135], v[208:211], v[12:15]
	v_mfma_f32_16x16x32_bf16 v[8:11], v[160:163], v[208:211], v[8:11]
	v_mfma_f32_16x16x32_bf16 v[52:55], v[164:167], v[180:183], v[52:55]
	v_mfma_f32_16x16x32_bf16 v[48:51], v[172:175], v[180:183], v[48:51]
	v_mfma_f32_16x16x32_bf16 v[36:39], v[164:167], v[188:191], v[36:39]
	v_mfma_f32_16x16x32_bf16 v[32:35], v[172:175], v[188:191], v[32:35]
	v_mfma_f32_16x16x32_bf16 v[20:23], v[164:167], v[196:199], v[20:23]
	v_mfma_f32_16x16x32_bf16 v[16:19], v[172:175], v[196:199], v[16:19]
	v_mfma_f32_16x16x32_bf16 v[4:7], v[164:167], v[204:207], v[4:7]
	v_mfma_f32_16x16x32_bf16 v[0:3], v[172:175], v[204:207], v[0:3]
	v_mfma_f32_16x16x32_bf16 v[52:55], v[168:171], v[184:187], v[52:55]
	v_mfma_f32_16x16x32_bf16 v[48:51], v[176:179], v[184:187], v[48:51]
	v_mfma_f32_16x16x32_bf16 v[36:39], v[168:171], v[192:195], v[36:39]
	v_mfma_f32_16x16x32_bf16 v[32:35], v[176:179], v[192:195], v[32:35]
	v_mfma_f32_16x16x32_bf16 v[20:23], v[168:171], v[200:203], v[20:23]
	v_mfma_f32_16x16x32_bf16 v[16:19], v[176:179], v[200:203], v[16:19]
	v_mfma_f32_16x16x32_bf16 v[4:7], v[168:171], v[208:211], v[4:7]
	v_mfma_f32_16x16x32_bf16 v[0:3], v[176:179], v[208:211], v[0:3]
	s_barrier
	s_add_i32 s52, 0, 0x18000
	v_add_u32_e32 v159, s52, v155
	s_add_i32 s53, 0, 0x1c000
	ds_read_b128 v[128:131], v159
	ds_read_b128 v[132:135], v159 offset:1024
	ds_read_b128 v[148:151], v159 offset:2048
	ds_read_b128 v[160:163], v159 offset:3072
	v_add_u32_e32 v159, s53, v155
	ds_read_b128 v[164:167], v159
	ds_read_b128 v[168:171], v159 offset:1024
	ds_read_b128 v[172:175], v159 offset:2048
	ds_read_b128 v[176:179], v159 offset:3072
	s_add_u32 s34, s34, 0x200000
	s_addc_u32 s35, s35, 0
	s_mov_b32 m0, s33
	v_lshl_add_u64 v[220:221], s[34:35], 0, v[136:137]
	ds_read_b128 v[180:183], v158 offset:32768
	ds_read_b128 v[184:187], v158 offset:33792
	ds_read_b128 v[188:191], v158 offset:34816
	ds_read_b128 v[192:195], v158 offset:35840
	ds_read_b128 v[196:199], v158 offset:36864
	ds_read_b128 v[200:203], v158 offset:37888
	ds_read_b128 v[204:207], v158 offset:38912
	ds_read_b128 v[208:211], v158 offset:39936
	global_load_lds_dwordx4 v[220:221], off
	v_lshl_add_u64 v[220:221], s[34:35], 0, v[140:141]
	s_mov_b32 m0, s36
	s_nop 0
	global_load_lds_dwordx4 v[220:221], off
	s_waitcnt vmcnt(8)
	s_waitcnt lgkmcnt(0)
	s_barrier
	v_mfma_f32_16x16x32_bf16 v[124:127], v[128:131], v[180:183], v[124:127]
	v_mfma_f32_16x16x32_bf16 v[120:123], v[148:151], v[180:183], v[120:123]
	v_mfma_f32_16x16x32_bf16 v[108:111], v[128:131], v[188:191], v[108:111]
	v_mfma_f32_16x16x32_bf16 v[104:107], v[148:151], v[188:191], v[104:107]
	v_mfma_f32_16x16x32_bf16 v[92:95], v[128:131], v[196:199], v[92:95]
	v_mfma_f32_16x16x32_bf16 v[88:91], v[148:151], v[196:199], v[88:91]
	v_mfma_f32_16x16x32_bf16 v[76:79], v[128:131], v[204:207], v[76:79]
	v_mfma_f32_16x16x32_bf16 v[72:75], v[148:151], v[204:207], v[72:75]
	v_mfma_f32_16x16x32_bf16 v[124:127], v[132:135], v[184:187], v[124:127]
	v_mfma_f32_16x16x32_bf16 v[120:123], v[160:163], v[184:187], v[120:123]
	v_mfma_f32_16x16x32_bf16 v[108:111], v[132:135], v[192:195], v[108:111]
	v_mfma_f32_16x16x32_bf16 v[104:107], v[160:163], v[192:195], v[104:107]
	v_mfma_f32_16x16x32_bf16 v[92:95], v[132:135], v[200:203], v[92:95]
	v_mfma_f32_16x16x32_bf16 v[88:91], v[160:163], v[200:203], v[88:91]
	v_mfma_f32_16x16x32_bf16 v[76:79], v[132:135], v[208:211], v[76:79]
	v_mfma_f32_16x16x32_bf16 v[72:75], v[160:163], v[208:211], v[72:75]
	v_mfma_f32_16x16x32_bf16 v[116:119], v[164:167], v[180:183], v[116:119]
	v_mfma_f32_16x16x32_bf16 v[112:115], v[172:175], v[180:183], v[112:115]
	v_mfma_f32_16x16x32_bf16 v[100:103], v[164:167], v[188:191], v[100:103]
	v_mfma_f32_16x16x32_bf16 v[96:99], v[172:175], v[188:191], v[96:99]
	v_mfma_f32_16x16x32_bf16 v[84:87], v[164:167], v[196:199], v[84:87]
	v_mfma_f32_16x16x32_bf16 v[80:83], v[172:175], v[196:199], v[80:83]
	v_mfma_f32_16x16x32_bf16 v[68:71], v[164:167], v[204:207], v[68:71]
	v_mfma_f32_16x16x32_bf16 v[64:67], v[172:175], v[204:207], v[64:67]
	v_mfma_f32_16x16x32_bf16 v[116:119], v[168:171], v[184:187], v[116:119]
	v_mfma_f32_16x16x32_bf16 v[112:115], v[176:179], v[184:187], v[112:115]
	v_mfma_f32_16x16x32_bf16 v[100:103], v[168:171], v[192:195], v[100:103]
	v_mfma_f32_16x16x32_bf16 v[96:99], v[176:179], v[192:195], v[96:99]
	v_mfma_f32_16x16x32_bf16 v[84:87], v[168:171], v[200:203], v[84:87]
	v_mfma_f32_16x16x32_bf16 v[80:83], v[176:179], v[200:203], v[80:83]
	v_mfma_f32_16x16x32_bf16 v[68:71], v[168:171], v[208:211], v[68:71]
	v_mfma_f32_16x16x32_bf16 v[64:67], v[176:179], v[208:211], v[64:67]
	s_barrier
	s_add_i32 s34, s52, s2
	v_lshl_add_u64 v[152:153], v[152:153], 0, s[4:5]
	s_mov_b32 m0, s34
	ds_read_b128 v[180:183], v158 offset:49152
	ds_read_b128 v[184:187], v158 offset:50176
	ds_read_b128 v[188:191], v158 offset:51200
	ds_read_b128 v[192:195], v158 offset:52224
	ds_read_b128 v[196:199], v158 offset:53248
	ds_read_b128 v[200:203], v158 offset:54272
	ds_read_b128 v[204:207], v158 offset:55296
	ds_read_b128 v[208:211], v158 offset:56320
	global_load_lds_dwordx4 v[152:153], off
	s_add_i32 m0, s34, 0x2000
	s_add_u32 s30, s30, 0x200080
	v_lshl_add_u64 v[152:153], v[212:213], 0, s[4:5]
	s_addc_u32 s31, s31, 0
	s_add_i32 s34, s53, s2
	global_load_lds_dwordx4 v[152:153], off
	v_lshl_add_u64 v[152:153], s[30:31], 0, v[138:139]
	s_mov_b32 m0, s34
	s_nop 0
	global_load_lds_dwordx4 v[152:153], off
	v_lshl_add_u64 v[152:153], s[30:31], 0, v[142:143]
	s_add_i32 m0, s34, 0x2000
	s_nop 0
	global_load_lds_dwordx4 v[152:153], off
	v_lshl_add_u64 v[152:153], v[214:215], 0, s[4:5]
	s_mov_b32 m0, s40
	s_nop 0
	global_load_lds_dwordx4 v[152:153], off
	v_lshl_add_u64 v[152:153], v[216:217], 0, s[4:5]
	s_mov_b32 m0, s41
	s_nop 0
	global_load_lds_dwordx4 v[152:153], off
	s_waitcnt vmcnt(8)
	s_waitcnt lgkmcnt(0)
	s_barrier
	v_mfma_f32_16x16x32_bf16 v[60:63], v[128:131], v[180:183], v[60:63]
	v_mfma_f32_16x16x32_bf16 v[56:59], v[148:151], v[180:183], v[56:59]
	v_mfma_f32_16x16x32_bf16 v[44:47], v[128:131], v[188:191], v[44:47]
	v_mfma_f32_16x16x32_bf16 v[40:43], v[148:151], v[188:191], v[40:43]
	v_mfma_f32_16x16x32_bf16 v[28:31], v[128:131], v[196:199], v[28:31]
	v_mfma_f32_16x16x32_bf16 v[24:27], v[148:151], v[196:199], v[24:27]
	v_mfma_f32_16x16x32_bf16 v[12:15], v[128:131], v[204:207], v[12:15]
	v_mfma_f32_16x16x32_bf16 v[8:11], v[148:151], v[204:207], v[8:11]
	v_mfma_f32_16x16x32_bf16 v[60:63], v[132:135], v[184:187], v[60:63]
	v_mfma_f32_16x16x32_bf16 v[56:59], v[160:163], v[184:187], v[56:59]
	v_mfma_f32_16x16x32_bf16 v[44:47], v[132:135], v[192:195], v[44:47]
	v_mfma_f32_16x16x32_bf16 v[40:43], v[160:163], v[192:195], v[40:43]
	v_mfma_f32_16x16x32_bf16 v[28:31], v[132:135], v[200:203], v[28:31]
	v_mfma_f32_16x16x32_bf16 v[24:27], v[160:163], v[200:203], v[24:27]
	v_mfma_f32_16x16x32_bf16 v[12:15], v[132:135], v[208:211], v[12:15]
	v_mfma_f32_16x16x32_bf16 v[8:11], v[160:163], v[208:211], v[8:11]
	v_mfma_f32_16x16x32_bf16 v[52:55], v[164:167], v[180:183], v[52:55]
	v_mfma_f32_16x16x32_bf16 v[48:51], v[172:175], v[180:183], v[48:51]
	v_mfma_f32_16x16x32_bf16 v[36:39], v[164:167], v[188:191], v[36:39]
	v_mfma_f32_16x16x32_bf16 v[32:35], v[172:175], v[188:191], v[32:35]
	v_mfma_f32_16x16x32_bf16 v[20:23], v[164:167], v[196:199], v[20:23]
	v_mfma_f32_16x16x32_bf16 v[16:19], v[172:175], v[196:199], v[16:19]
	v_mfma_f32_16x16x32_bf16 v[4:7], v[164:167], v[204:207], v[4:7]
	v_mfma_f32_16x16x32_bf16 v[0:3], v[172:175], v[204:207], v[0:3]
	v_mfma_f32_16x16x32_bf16 v[52:55], v[168:171], v[184:187], v[52:55]
	v_mfma_f32_16x16x32_bf16 v[48:51], v[176:179], v[184:187], v[48:51]
	v_mfma_f32_16x16x32_bf16 v[36:39], v[168:171], v[192:195], v[36:39]
	v_mfma_f32_16x16x32_bf16 v[32:35], v[176:179], v[192:195], v[32:35]
	v_mfma_f32_16x16x32_bf16 v[20:23], v[168:171], v[200:203], v[20:23]
	v_mfma_f32_16x16x32_bf16 v[16:19], v[176:179], v[200:203], v[16:19]
	v_mfma_f32_16x16x32_bf16 v[4:7], v[168:171], v[208:211], v[4:7]
	v_mfma_f32_16x16x32_bf16 v[0:3], v[176:179], v[208:211], v[0:3]
	s_barrier
	s_add_i32 s51, s51, 2
	s_add_u32 s28, s28, 0x100
	s_addc_u32 s29, s29, 0
	s_add_u32 s21, s21, 0x100
	s_addc_u32 s43, s43, 0
	s_cmpk_gt_u32 s51, 0x7d
	s_cbranch_scc0 .LBB0_1081
	s_and_b64 vcc, exec, s[6:7]
	s_cbranch_vccz .LBB0_1084
	s_barrier
